# v79 + rhs set-up of the forward substitution re-emitted with batched LDS reads (three batches in flight, packed multiplies), x[62..63] included
# speedup vs baseline: 1.0037x; 1.0037x over previous
; __device__ __forceinline__ void gdn_local_unit(LAS unsigned char* lds, const GdnP& P, int unit, const int tid, const int pf) {
;     ...
;     if (tid < 256 && !(pf & 2)) {
;         const int col = tid; f32x2 sol2[32];
;         if (col < 128) {
; #pragma unroll
;             for (int t = 0; t < 64; ++t) sol2[t >> 1][t & 1] = Vs[t * 128 + col] * beta[t];
;         } else {
; #pragma unroll
;             for (int t = 0; t < 64; ++t) sol2[t >> 1][t & 1] = Ks[t * 132 + col - 128] * rk[t] * beta[t] * eG[t];
;         }
.LBB0_1020:
	s_andn2_saveexec_b64 s[40:41], s[0:1]
	s_cbranch_execz .LBB0_1030
	v_lshl_add_u32 v111, v165, 2, v219
	v_readfirstlane_b32 s0, v165
	s_cmpk_lt_u32 s0, 0x80
	s_cbranch_scc1 .Lfi_v
	v_lshl_add_u32 v20, v165, 2, v131
	v_add_u32_e32 v20, 0xfffffe00, v20
	v_add_u32_e32 v21, 0x400, v130
	ds_read2_b32 v[0:1], v20 offset1:132
	v_add_u32_e32 v20, 0x420, v20
	ds_read2_b32 v[142:143], v130 offset0:64 offset1:65
	ds_read2_b32 v[144:145], v130 offset0:128 offset1:129
	ds_read2_b32 v[146:147], v21 offset0:0 offset1:1
	ds_read2_b32 v[8:9], v20 offset1:132
	v_add_u32_e32 v20, 0x420, v20
	ds_read2_b32 v[148:149], v130 offset0:66 offset1:67
	ds_read2_b32 v[150:151], v130 offset0:130 offset1:131
	ds_read2_b32 v[152:153], v21 offset0:2 offset1:3
	ds_read2_b32 v[14:15], v20 offset1:132
	v_add_u32_e32 v20, 0x420, v20
	ds_read2_b32 v[154:155], v130 offset0:68 offset1:69
	ds_read2_b32 v[156:157], v130 offset0:132 offset1:133
	ds_read2_b32 v[158:159], v21 offset0:4 offset1:5
	s_waitcnt lgkmcnt(8)
	v_pk_mul_f32 v[142:143], v[142:143], v[144:145]
	v_pk_mul_f32 v[0:1], v[0:1], v[146:147]
	ds_read2_b32 v[18:19], v20 offset1:132
	v_add_u32_e32 v20, 0x420, v20
	ds_read2_b32 v[160:161], v130 offset0:70 offset1:71
	ds_read2_b32 v[220:221], v130 offset0:134 offset1:135
	ds_read2_b32 v[222:223], v21 offset0:6 offset1:7
	v_pk_mul_f32 v[0:1], v[0:1], v[142:143]
	s_waitcnt lgkmcnt(8)
	v_pk_mul_f32 v[148:149], v[148:149], v[150:151]
	v_pk_mul_f32 v[8:9], v[8:9], v[152:153]
	ds_read2_b32 v[22:23], v20 offset1:132
	v_add_u32_e32 v20, 0x420, v20
	ds_read2_b32 v[142:143], v130 offset0:72 offset1:73
	ds_read2_b32 v[144:145], v130 offset0:136 offset1:137
	ds_read2_b32 v[146:147], v21 offset0:8 offset1:9
	v_pk_mul_f32 v[8:9], v[8:9], v[148:149]
	s_waitcnt lgkmcnt(8)
	v_pk_mul_f32 v[154:155], v[154:155], v[156:157]
	v_pk_mul_f32 v[14:15], v[14:15], v[158:159]
	ds_read2_b32 v[26:27], v20 offset1:132
	v_add_u32_e32 v20, 0x420, v20
	ds_read2_b32 v[148:149], v130 offset0:74 offset1:75
	ds_read2_b32 v[150:151], v130 offset0:138 offset1:139
	ds_read2_b32 v[152:153], v21 offset0:10 offset1:11
	v_pk_mul_f32 v[14:15], v[14:15], v[154:155]
	s_waitcnt lgkmcnt(8)
	v_pk_mul_f32 v[160:161], v[160:161], v[220:221]
	v_pk_mul_f32 v[18:19], v[18:19], v[222:223]
	ds_read2_b32 v[30:31], v20 offset1:132
	v_add_u32_e32 v20, 0x420, v20
	ds_read2_b32 v[154:155], v130 offset0:76 offset1:77
	ds_read2_b32 v[156:157], v130 offset0:140 offset1:141
	ds_read2_b32 v[158:159], v21 offset0:12 offset1:13
	v_pk_mul_f32 v[18:19], v[18:19], v[160:161]
	s_waitcnt lgkmcnt(8)
	v_pk_mul_f32 v[142:143], v[142:143], v[144:145]
	v_pk_mul_f32 v[22:23], v[22:23], v[146:147]
	ds_read2_b32 v[36:37], v20 offset1:132
	v_add_u32_e32 v20, 0x420, v20
	ds_read2_b32 v[160:161], v130 offset0:78 offset1:79
	ds_read2_b32 v[220:221], v130 offset0:142 offset1:143
	ds_read2_b32 v[222:223], v21 offset0:14 offset1:15
	v_pk_mul_f32 v[22:23], v[22:23], v[142:143]
	s_waitcnt lgkmcnt(8)
	v_pk_mul_f32 v[148:149], v[148:149], v[150:151]
	v_pk_mul_f32 v[26:27], v[26:27], v[152:153]
	ds_read2_b32 v[40:41], v20 offset1:132
	v_add_u32_e32 v20, 0x420, v20
	ds_read2_b32 v[142:143], v130 offset0:80 offset1:81
	ds_read2_b32 v[144:145], v130 offset0:144 offset1:145
	ds_read2_b32 v[146:147], v21 offset0:16 offset1:17
	v_pk_mul_f32 v[26:27], v[26:27], v[148:149]
	s_waitcnt lgkmcnt(8)
	v_pk_mul_f32 v[154:155], v[154:155], v[156:157]
	v_pk_mul_f32 v[30:31], v[30:31], v[158:159]
	ds_read2_b32 v[44:45], v20 offset1:132
	v_add_u32_e32 v20, 0x420, v20
	ds_read2_b32 v[148:149], v130 offset0:82 offset1:83
	ds_read2_b32 v[150:151], v130 offset0:146 offset1:147
	ds_read2_b32 v[152:153], v21 offset0:18 offset1:19
	v_pk_mul_f32 v[30:31], v[30:31], v[154:155]
	s_waitcnt lgkmcnt(8)
	v_pk_mul_f32 v[160:161], v[160:161], v[220:221]
	v_pk_mul_f32 v[36:37], v[36:37], v[222:223]
	ds_read2_b32 v[50:51], v20 offset1:132
	v_add_u32_e32 v20, 0x420, v20
	ds_read2_b32 v[154:155], v130 offset0:84 offset1:85
	ds_read2_b32 v[156:157], v130 offset0:148 offset1:149
	ds_read2_b32 v[158:159], v21 offset0:20 offset1:21
	v_pk_mul_f32 v[36:37], v[36:37], v[160:161]
	s_waitcnt lgkmcnt(8)
	v_pk_mul_f32 v[142:143], v[142:143], v[144:145]
	v_pk_mul_f32 v[40:41], v[40:41], v[146:147]
	ds_read2_b32 v[54:55], v20 offset1:132
	v_add_u32_e32 v20, 0x420, v20
	ds_read2_b32 v[160:161], v130 offset0:86 offset1:87
	ds_read2_b32 v[220:221], v130 offset0:150 offset1:151
	ds_read2_b32 v[222:223], v21 offset0:22 offset1:23
	v_pk_mul_f32 v[40:41], v[40:41], v[142:143]
	s_waitcnt lgkmcnt(8)
	v_pk_mul_f32 v[148:149], v[148:149], v[150:151]
	v_pk_mul_f32 v[44:45], v[44:45], v[152:153]
	ds_read2_b32 v[60:61], v20 offset1:132
	v_add_u32_e32 v20, 0x420, v20
	ds_read2_b32 v[142:143], v130 offset0:88 offset1:89
	ds_read2_b32 v[144:145], v130 offset0:152 offset1:153
	ds_read2_b32 v[146:147], v21 offset0:24 offset1:25
	v_pk_mul_f32 v[44:45], v[44:45], v[148:149]
	s_waitcnt lgkmcnt(8)
	v_pk_mul_f32 v[154:155], v[154:155], v[156:157]
	v_pk_mul_f32 v[50:51], v[50:51], v[158:159]
	ds_read2_b32 v[64:65], v20 offset1:132
	v_add_u32_e32 v20, 0x420, v20
	ds_read2_b32 v[148:149], v130 offset0:90 offset1:91
	ds_read2_b32 v[150:151], v130 offset0:154 offset1:155
	ds_read2_b32 v[152:153], v21 offset0:26 offset1:27
	v_pk_mul_f32 v[50:51], v[50:51], v[154:155]
	s_waitcnt lgkmcnt(8)
	v_pk_mul_f32 v[160:161], v[160:161], v[220:221]
	v_pk_mul_f32 v[54:55], v[54:55], v[222:223]
	ds_read2_b32 v[70:71], v20 offset1:132
	v_add_u32_e32 v20, 0x420, v20
	ds_read2_b32 v[154:155], v130 offset0:92 offset1:93
	ds_read2_b32 v[156:157], v130 offset0:156 offset1:157
	ds_read2_b32 v[158:159], v21 offset0:28 offset1:29
	v_pk_mul_f32 v[54:55], v[54:55], v[160:161]
	s_waitcnt lgkmcnt(8)
; __device__ __forceinline__ void gdn_local_unit(LAS unsigned char* lds, const GdnP& P, int unit, const int tid, const int pf) {
;     ...
;     if (tid < 256 && !(pf & 2)) {
;         const int col = tid; f32x2 sol2[32];
;         if (col < 128) {
; #pragma unroll
;             for (int t = 0; t < 64; ++t) sol2[t >> 1][t & 1] = Vs[t * 128 + col] * beta[t];
;         } else {
; #pragma unroll
;             for (int t = 0; t < 64; ++t) sol2[t >> 1][t & 1] = Ks[t * 132 + col - 128] * rk[t] * beta[t] * eG[t];
;         }
	v_pk_mul_f32 v[142:143], v[142:143], v[144:145]
	v_pk_mul_f32 v[60:61], v[60:61], v[146:147]
	ds_read2_b32 v[112:113], v20 offset1:132
	v_add_u32_e32 v20, 0x420, v20
	ds_read2_b32 v[160:161], v130 offset0:94 offset1:95
	ds_read2_b32 v[220:221], v130 offset0:158 offset1:159
	ds_read2_b32 v[222:223], v21 offset0:30 offset1:31
	v_pk_mul_f32 v[60:61], v[60:61], v[142:143]
	s_waitcnt lgkmcnt(8)
	v_pk_mul_f32 v[148:149], v[148:149], v[150:151]
	v_pk_mul_f32 v[64:65], v[64:65], v[152:153]
	ds_read2_b32 v[116:117], v20 offset1:132
	v_add_u32_e32 v20, 0x420, v20
	ds_read2_b32 v[142:143], v130 offset0:96 offset1:97
	ds_read2_b32 v[144:145], v130 offset0:160 offset1:161
	ds_read2_b32 v[146:147], v21 offset0:32 offset1:33
	v_pk_mul_f32 v[64:65], v[64:65], v[148:149]
	s_waitcnt lgkmcnt(8)
	v_pk_mul_f32 v[154:155], v[154:155], v[156:157]
	v_pk_mul_f32 v[70:71], v[70:71], v[158:159]
	ds_read2_b32 v[122:123], v20 offset1:132
	v_add_u32_e32 v20, 0x420, v20
	ds_read2_b32 v[148:149], v130 offset0:98 offset1:99
	ds_read2_b32 v[150:151], v130 offset0:162 offset1:163
	ds_read2_b32 v[152:153], v21 offset0:34 offset1:35
	v_pk_mul_f32 v[70:71], v[70:71], v[154:155]
	s_waitcnt lgkmcnt(8)
	v_pk_mul_f32 v[160:161], v[160:161], v[220:221]
	v_pk_mul_f32 v[112:113], v[112:113], v[222:223]
	ds_read2_b32 v[128:129], v20 offset1:132
	v_add_u32_e32 v20, 0x420, v20
	ds_read2_b32 v[154:155], v130 offset0:100 offset1:101
	ds_read2_b32 v[156:157], v130 offset0:164 offset1:165
	ds_read2_b32 v[158:159], v21 offset0:36 offset1:37
	v_pk_mul_f32 v[112:113], v[112:113], v[160:161]
	s_waitcnt lgkmcnt(8)
	v_pk_mul_f32 v[142:143], v[142:143], v[144:145]
	v_pk_mul_f32 v[116:117], v[116:117], v[146:147]
	ds_read2_b32 v[134:135], v20 offset1:132
	v_add_u32_e32 v20, 0x420, v20
	ds_read2_b32 v[160:161], v130 offset0:102 offset1:103
	ds_read2_b32 v[220:221], v130 offset0:166 offset1:167
	ds_read2_b32 v[222:223], v21 offset0:38 offset1:39
	v_pk_mul_f32 v[116:117], v[116:117], v[142:143]
	s_waitcnt lgkmcnt(8)
	v_pk_mul_f32 v[148:149], v[148:149], v[150:151]
	v_pk_mul_f32 v[122:123], v[122:123], v[152:153]
	ds_read2_b32 v[140:141], v20 offset1:132
	v_add_u32_e32 v20, 0x420, v20
	ds_read2_b32 v[142:143], v130 offset0:104 offset1:105
	ds_read2_b32 v[144:145], v130 offset0:168 offset1:169
	ds_read2_b32 v[146:147], v21 offset0:40 offset1:41
	v_pk_mul_f32 v[122:123], v[122:123], v[148:149]
	s_waitcnt lgkmcnt(8)
	v_pk_mul_f32 v[154:155], v[154:155], v[156:157]
	v_pk_mul_f32 v[128:129], v[128:129], v[158:159]
	ds_read2_b32 v[138:139], v20 offset1:132
	v_add_u32_e32 v20, 0x420, v20
	ds_read2_b32 v[148:149], v130 offset0:106 offset1:107
	ds_read2_b32 v[150:151], v130 offset0:170 offset1:171
	ds_read2_b32 v[152:153], v21 offset0:42 offset1:43
	v_pk_mul_f32 v[128:129], v[128:129], v[154:155]
	s_waitcnt lgkmcnt(8)
	v_pk_mul_f32 v[160:161], v[160:161], v[220:221]
	v_pk_mul_f32 v[134:135], v[134:135], v[222:223]
	ds_read2_b32 v[132:133], v20 offset1:132
	v_add_u32_e32 v20, 0x420, v20
	ds_read2_b32 v[154:155], v130 offset0:108 offset1:109
	ds_read2_b32 v[156:157], v130 offset0:172 offset1:173
	ds_read2_b32 v[158:159], v21 offset0:44 offset1:45
	v_pk_mul_f32 v[134:135], v[134:135], v[160:161]
	s_waitcnt lgkmcnt(8)
	v_pk_mul_f32 v[142:143], v[142:143], v[144:145]
	v_pk_mul_f32 v[140:141], v[140:141], v[146:147]
	ds_read2_b32 v[124:125], v20 offset1:132
	v_add_u32_e32 v20, 0x420, v20
	ds_read2_b32 v[160:161], v130 offset0:110 offset1:111
	ds_read2_b32 v[220:221], v130 offset0:174 offset1:175
	ds_read2_b32 v[222:223], v21 offset0:46 offset1:47
	v_pk_mul_f32 v[140:141], v[140:141], v[142:143]
	s_waitcnt lgkmcnt(8)
	v_pk_mul_f32 v[148:149], v[148:149], v[150:151]
	v_pk_mul_f32 v[138:139], v[138:139], v[152:153]
	ds_read2_b32 v[118:119], v20 offset1:132
	v_add_u32_e32 v20, 0x420, v20
	ds_read2_b32 v[142:143], v130 offset0:112 offset1:113
	ds_read2_b32 v[144:145], v130 offset0:176 offset1:177
	ds_read2_b32 v[146:147], v21 offset0:48 offset1:49
	v_pk_mul_f32 v[138:139], v[138:139], v[148:149]
	s_waitcnt lgkmcnt(8)
	v_pk_mul_f32 v[154:155], v[154:155], v[156:157]
	v_pk_mul_f32 v[132:133], v[132:133], v[158:159]
	ds_read2_b32 v[74:75], v20 offset1:132
	v_add_u32_e32 v20, 0x420, v20
	ds_read2_b32 v[148:149], v130 offset0:114 offset1:115
	ds_read2_b32 v[150:151], v130 offset0:178 offset1:179
	ds_read2_b32 v[152:153], v21 offset0:50 offset1:51
	v_pk_mul_f32 v[132:133], v[132:133], v[154:155]
	s_waitcnt lgkmcnt(8)
	v_pk_mul_f32 v[160:161], v[160:161], v[220:221]
	v_pk_mul_f32 v[124:125], v[124:125], v[222:223]
	ds_read2_b32 v[66:67], v20 offset1:132
	v_add_u32_e32 v20, 0x420, v20
	ds_read2_b32 v[154:155], v130 offset0:116 offset1:117
	ds_read2_b32 v[156:157], v130 offset0:180 offset1:181
	ds_read2_b32 v[158:159], v21 offset0:52 offset1:53
	v_pk_mul_f32 v[124:125], v[124:125], v[160:161]
	s_waitcnt lgkmcnt(8)
	v_pk_mul_f32 v[142:143], v[142:143], v[144:145]
	v_pk_mul_f32 v[118:119], v[118:119], v[146:147]
	ds_read2_b32 v[56:57], v20 offset1:132
	v_add_u32_e32 v20, 0x420, v20
	ds_read2_b32 v[160:161], v130 offset0:118 offset1:119
	ds_read2_b32 v[220:221], v130 offset0:182 offset1:183
	ds_read2_b32 v[222:223], v21 offset0:54 offset1:55
	v_pk_mul_f32 v[118:119], v[118:119], v[142:143]
	s_waitcnt lgkmcnt(8)
	v_pk_mul_f32 v[148:149], v[148:149], v[150:151]
	v_pk_mul_f32 v[74:75], v[74:75], v[152:153]
	ds_read2_b32 v[46:47], v20 offset1:132
	v_add_u32_e32 v20, 0x420, v20
	ds_read2_b32 v[142:143], v130 offset0:120 offset1:121
	ds_read2_b32 v[144:145], v130 offset0:184 offset1:185
	ds_read2_b32 v[146:147], v21 offset0:56 offset1:57
	v_pk_mul_f32 v[74:75], v[74:75], v[148:149]
	s_waitcnt lgkmcnt(8)
; __device__ __forceinline__ void gdn_local_unit(LAS unsigned char* lds, const GdnP& P, int unit, const int tid, const int pf) {
;     ...
;         if (col < 128) {
; #pragma unroll
;             for (int t = 0; t < 64; ++t) sol2[t >> 1][t & 1] = Vs[t * 128 + col] * beta[t];
;         } else {
; #pragma unroll
;             for (int t = 0; t < 64; ++t) sol2[t >> 1][t & 1] = Ks[t * 132 + col - 128] * rk[t] * beta[t] * eG[t];
;         }
	v_pk_mul_f32 v[154:155], v[154:155], v[156:157]
	v_pk_mul_f32 v[66:67], v[66:67], v[158:159]
	ds_read2_b32 v[32:33], v20 offset1:132
	v_add_u32_e32 v20, 0x420, v20
	ds_read2_b32 v[148:149], v130 offset0:122 offset1:123
	ds_read2_b32 v[150:151], v130 offset0:186 offset1:187
	ds_read2_b32 v[152:153], v21 offset0:58 offset1:59
	v_pk_mul_f32 v[66:67], v[66:67], v[154:155]
	s_waitcnt lgkmcnt(8)
	v_pk_mul_f32 v[160:161], v[160:161], v[220:221]
	v_pk_mul_f32 v[56:57], v[56:57], v[222:223]
	ds_read2_b32 v[12:13], v20 offset1:132
	v_add_u32_e32 v20, 0x420, v20
	ds_read2_b32 v[154:155], v130 offset0:124 offset1:125
	ds_read2_b32 v[156:157], v130 offset0:188 offset1:189
	ds_read2_b32 v[158:159], v21 offset0:60 offset1:61
	v_pk_mul_f32 v[56:57], v[56:57], v[160:161]
	s_waitcnt lgkmcnt(8)
	v_pk_mul_f32 v[142:143], v[142:143], v[144:145]
	v_pk_mul_f32 v[46:47], v[46:47], v[146:147]
	ds_read2_b32 v[2:3], v20 offset1:132
	v_add_u32_e32 v20, 0x420, v20
	ds_read2_b32 v[160:161], v130 offset0:126 offset1:127
	ds_read2_b32 v[220:221], v130 offset0:190 offset1:191
	ds_read2_b32 v[222:223], v21 offset0:62 offset1:63
	v_pk_mul_f32 v[46:47], v[46:47], v[142:143]
	s_waitcnt lgkmcnt(8)
	v_pk_mul_f32 v[148:149], v[148:149], v[150:151]
	v_pk_mul_f32 v[32:33], v[32:33], v[152:153]
	s_nop 0
	v_pk_mul_f32 v[32:33], v[32:33], v[148:149]
	s_waitcnt lgkmcnt(4)
	v_pk_mul_f32 v[154:155], v[154:155], v[156:157]
	v_pk_mul_f32 v[12:13], v[12:13], v[158:159]
	s_nop 0
	v_pk_mul_f32 v[12:13], v[12:13], v[154:155]
	s_waitcnt lgkmcnt(0)
	v_pk_mul_f32 v[160:161], v[160:161], v[220:221]
	v_pk_mul_f32 v[2:3], v[2:3], v[222:223]
	s_nop 0
	v_pk_mul_f32 v[2:3], v[2:3], v[160:161]
	s_branch .Lfi_done
.Lfi_v:
	ds_read2st64_b32 v[0:1], v111 offset1:2
	ds_read2_b32 v[142:143], v130 offset0:128 offset1:129
	ds_read2st64_b32 v[8:9], v111 offset0:4 offset1:6
	ds_read2_b32 v[144:145], v130 offset0:130 offset1:131
	ds_read2st64_b32 v[14:15], v111 offset0:8 offset1:10
	ds_read2_b32 v[148:149], v130 offset0:132 offset1:133
	ds_read2st64_b32 v[18:19], v111 offset0:12 offset1:14
	ds_read2_b32 v[150:151], v130 offset0:134 offset1:135
	ds_read2st64_b32 v[22:23], v111 offset0:16 offset1:18
	ds_read2_b32 v[154:155], v130 offset0:136 offset1:137
	ds_read2st64_b32 v[26:27], v111 offset0:20 offset1:22
	ds_read2_b32 v[156:157], v130 offset0:138 offset1:139
	s_waitcnt lgkmcnt(8)
	v_pk_mul_f32 v[0:1], v[0:1], v[142:143]
	v_pk_mul_f32 v[8:9], v[8:9], v[144:145]
	ds_read2st64_b32 v[30:31], v111 offset0:24 offset1:26
	ds_read2_b32 v[160:161], v130 offset0:140 offset1:141
	ds_read2st64_b32 v[36:37], v111 offset0:28 offset1:30
	ds_read2_b32 v[220:221], v130 offset0:142 offset1:143
	s_waitcnt lgkmcnt(8)
	v_pk_mul_f32 v[14:15], v[14:15], v[148:149]
	v_pk_mul_f32 v[18:19], v[18:19], v[150:151]
	ds_read2st64_b32 v[40:41], v111 offset0:32 offset1:34
	ds_read2_b32 v[142:143], v130 offset0:144 offset1:145
	ds_read2st64_b32 v[44:45], v111 offset0:36 offset1:38
	ds_read2_b32 v[144:145], v130 offset0:146 offset1:147
	s_waitcnt lgkmcnt(8)
	v_pk_mul_f32 v[22:23], v[22:23], v[154:155]
	v_pk_mul_f32 v[26:27], v[26:27], v[156:157]
	ds_read2st64_b32 v[50:51], v111 offset0:40 offset1:42
	ds_read2_b32 v[148:149], v130 offset0:148 offset1:149
	ds_read2st64_b32 v[54:55], v111 offset0:44 offset1:46
	ds_read2_b32 v[150:151], v130 offset0:150 offset1:151
	s_waitcnt lgkmcnt(8)
	v_pk_mul_f32 v[30:31], v[30:31], v[160:161]
	v_pk_mul_f32 v[36:37], v[36:37], v[220:221]
	ds_read2st64_b32 v[60:61], v111 offset0:48 offset1:50
	ds_read2_b32 v[154:155], v130 offset0:152 offset1:153
	ds_read2st64_b32 v[64:65], v111 offset0:52 offset1:54
	ds_read2_b32 v[156:157], v130 offset0:154 offset1:155
	s_waitcnt lgkmcnt(8)
	v_pk_mul_f32 v[40:41], v[40:41], v[142:143]
	v_pk_mul_f32 v[44:45], v[44:45], v[144:145]
	ds_read2st64_b32 v[70:71], v111 offset0:56 offset1:58
	ds_read2_b32 v[160:161], v130 offset0:156 offset1:157
	ds_read2st64_b32 v[112:113], v111 offset0:60 offset1:62
	ds_read2_b32 v[220:221], v130 offset0:158 offset1:159
	s_waitcnt lgkmcnt(8)
	v_pk_mul_f32 v[50:51], v[50:51], v[148:149]
	v_pk_mul_f32 v[54:55], v[54:55], v[150:151]
	ds_read2st64_b32 v[116:117], v111 offset0:64 offset1:66
	ds_read2_b32 v[142:143], v130 offset0:160 offset1:161
	ds_read2st64_b32 v[122:123], v111 offset0:68 offset1:70
	ds_read2_b32 v[144:145], v130 offset0:162 offset1:163
	s_waitcnt lgkmcnt(8)
	v_pk_mul_f32 v[60:61], v[60:61], v[154:155]
	v_pk_mul_f32 v[64:65], v[64:65], v[156:157]
	ds_read2st64_b32 v[128:129], v111 offset0:72 offset1:74
	ds_read2_b32 v[148:149], v130 offset0:164 offset1:165
	ds_read2st64_b32 v[134:135], v111 offset0:76 offset1:78
	ds_read2_b32 v[150:151], v130 offset0:166 offset1:167
	s_waitcnt lgkmcnt(8)
	v_pk_mul_f32 v[70:71], v[70:71], v[160:161]
	v_pk_mul_f32 v[112:113], v[112:113], v[220:221]
	ds_read2st64_b32 v[140:141], v111 offset0:80 offset1:82
	ds_read2_b32 v[154:155], v130 offset0:168 offset1:169
	ds_read2st64_b32 v[138:139], v111 offset0:84 offset1:86
	ds_read2_b32 v[156:157], v130 offset0:170 offset1:171
	s_waitcnt lgkmcnt(8)
	v_pk_mul_f32 v[116:117], v[116:117], v[142:143]
	v_pk_mul_f32 v[122:123], v[122:123], v[144:145]
	ds_read2st64_b32 v[132:133], v111 offset0:88 offset1:90
	ds_read2_b32 v[160:161], v130 offset0:172 offset1:173
	ds_read2st64_b32 v[124:125], v111 offset0:92 offset1:94
	ds_read2_b32 v[220:221], v130 offset0:174 offset1:175
	s_waitcnt lgkmcnt(8)
	v_pk_mul_f32 v[128:129], v[128:129], v[148:149]
	v_pk_mul_f32 v[134:135], v[134:135], v[150:151]
	ds_read2st64_b32 v[118:119], v111 offset0:96 offset1:98
	ds_read2_b32 v[142:143], v130 offset0:176 offset1:177
	ds_read2st64_b32 v[74:75], v111 offset0:100 offset1:102
	ds_read2_b32 v[144:145], v130 offset0:178 offset1:179
	s_waitcnt lgkmcnt(8)
	v_pk_mul_f32 v[140:141], v[140:141], v[154:155]
	v_pk_mul_f32 v[138:139], v[138:139], v[156:157]
	ds_read2st64_b32 v[66:67], v111 offset0:104 offset1:106
	ds_read2_b32 v[148:149], v130 offset0:180 offset1:181
	ds_read2st64_b32 v[56:57], v111 offset0:108 offset1:110
	ds_read2_b32 v[150:151], v130 offset0:182 offset1:183
	s_waitcnt lgkmcnt(8)
	v_pk_mul_f32 v[132:133], v[132:133], v[160:161]
	v_pk_mul_f32 v[124:125], v[124:125], v[220:221]
	ds_read2st64_b32 v[46:47], v111 offset0:112 offset1:114
	ds_read2_b32 v[154:155], v130 offset0:184 offset1:185
	ds_read2st64_b32 v[32:33], v111 offset0:116 offset1:118
	ds_read2_b32 v[156:157], v130 offset0:186 offset1:187
	s_waitcnt lgkmcnt(8)
	v_pk_mul_f32 v[118:119], v[118:119], v[142:143]
	v_pk_mul_f32 v[74:75], v[74:75], v[144:145]
	ds_read2st64_b32 v[12:13], v111 offset0:120 offset1:122
	ds_read2_b32 v[160:161], v130 offset0:188 offset1:189
	ds_read2st64_b32 v[2:3], v111 offset0:124 offset1:126
	ds_read2_b32 v[220:221], v130 offset0:190 offset1:191
	s_waitcnt lgkmcnt(8)
	v_pk_mul_f32 v[66:67], v[66:67], v[148:149]
	v_pk_mul_f32 v[56:57], v[56:57], v[150:151]
	s_waitcnt lgkmcnt(4)
	v_pk_mul_f32 v[46:47], v[46:47], v[154:155]
	v_pk_mul_f32 v[32:33], v[32:33], v[156:157]
	s_waitcnt lgkmcnt(0)
	v_pk_mul_f32 v[12:13], v[12:13], v[160:161]
	v_pk_mul_f32 v[2:3], v[2:3], v[220:221]
; #define LAS __attribute__((address_space(3)))
; __device__ __forceinline__ void gdn_local_unit(LAS unsigned char* lds, const GdnP& P, int unit, const int tid, const int pf) {
;     ...
;         const int col = tid; f32x2 sol2[32];
;         if (col < 128) {
; #pragma unroll
;             for (int t = 0; t < 64; ++t) sol2[t >> 1][t & 1] = Vs[t * 128 + col] * beta[t];
;         } else {
; #pragma unroll
;             for (int t = 0; t < 64; ++t) sol2[t >> 1][t & 1] = Ks[t * 132 + col - 128] * rk[t] * beta[t] * eG[t];
;         }
; #pragma unroll
;         for (int c = 1; c < 64; ++c) { f32x2 sp = (f32x2){sol2[c >> 1][c & 1], 0.f};
; #pragma unroll
;             for (int jb = 0; jb <= (c - 1) / 4; ++jb) { const f32x4 m4 = *(const LAS f32x4*)(Ms + c * 64 + 4 * jb);
;                 sp -= (f32x2){m4.x, m4.y} * sol2[2 * jb]; sp -= (f32x2){m4.z, m4.w} * sol2[2 * jb + 1]; }
;             sol2[c >> 1][c & 1] = sp.x + sp.y; }
.Lfi_done:
	ds_read_b128 v[142:145], v109 offset:256
	ds_read_b128 v[146:149], v109 offset:512
	ds_read_b128 v[150:153], v109 offset:768
	ds_read_b128 v[154:157], v109 offset:1024
	ds_read_b128 v[158:161], v109 offset:1280
	ds_read_b128 v[220:223], v109 offset:1536
	ds_read_b128 v[230:233], v109 offset:1792
	ds_read_b128 v[234:237], v109 offset:2048
	s_waitcnt lgkmcnt(5)
	v_fma_f32 v1, -v142, v0, v1
	ds_read_b128 v[142:145], v109 offset:2304
	v_fma_f32 v8, -v146, v0, v8
	v_fma_f32 v9, -v150, v0, v9
	v_fma_f32 v8, -v147, v1, v8
	ds_read_b128 v[146:149], v109 offset:2560
	v_fma_f32 v9, -v151, v1, v9
	v_fma_f32 v9, -v152, v8, v9
	ds_read_b128 v[150:153], v109 offset:2816
	s_waitcnt lgkmcnt(4)
	v_pk_mul_f32 v[28:29], v[154:155], v[0:1] neg_lo:[1,0] neg_hi:[1,0]
	v_pk_mul_f32 v[34:35], v[158:159], v[0:1] neg_lo:[1,0] neg_hi:[1,0]
	v_pk_mul_f32 v[38:39], v[220:221], v[0:1] neg_lo:[1,0] neg_hi:[1,0]
	v_pk_mul_f32 v[42:43], v[230:231], v[0:1] neg_lo:[1,0] neg_hi:[1,0]
	v_pk_fma_f32 v[28:29], v[156:157], v[8:9], v[28:29] neg_lo:[1,0,0] neg_hi:[1,0,0]
	ds_read_b128 v[154:157], v109 offset:1296
	v_pk_fma_f32 v[34:35], v[160:161], v[8:9], v[34:35] neg_lo:[1,0,0] neg_hi:[1,0,0]
	ds_read_b128 v[158:161], v109 offset:1552
	v_pk_fma_f32 v[38:39], v[222:223], v[8:9], v[38:39] neg_lo:[1,0,0] neg_hi:[1,0,0]
	ds_read_b128 v[220:223], v109 offset:1808
	v_pk_fma_f32 v[42:43], v[232:233], v[8:9], v[42:43] neg_lo:[1,0,0] neg_hi:[1,0,0]
	ds_read_b128 v[230:233], v109 offset:2064
	v_add_f32_e32 v28, v28, v29
	s_waitcnt lgkmcnt(5)
	v_pk_mul_f32 v[10:11], v[234:235], v[0:1] neg_lo:[1,0] neg_hi:[1,0]
	v_pk_mul_f32 v[16:17], v[142:143], v[0:1] neg_lo:[1,0] neg_hi:[1,0]
	v_add_f32_e32 v34, v34, v35
	v_pk_mul_f32 v[20:21], v[146:147], v[0:1] neg_lo:[1,0] neg_hi:[1,0]
	s_waitcnt lgkmcnt(4)
	v_pk_mul_f32 v[24:25], v[150:151], v[0:1] neg_lo:[1,0] neg_hi:[1,0]
	v_add_f32_e32 v38, v38, v39
	v_pk_fma_f32 v[10:11], v[236:237], v[8:9], v[10:11] neg_lo:[1,0,0] neg_hi:[1,0,0]
	ds_read_b128 v[234:237], v109 offset:2320
	v_pk_fma_f32 v[16:17], v[144:145], v[8:9], v[16:17] neg_lo:[1,0,0] neg_hi:[1,0,0]
	ds_read_b128 v[142:145], v109 offset:2576
	v_add_f32_e32 v42, v42, v43
	v_pk_fma_f32 v[20:21], v[148:149], v[8:9], v[20:21] neg_lo:[1,0,0] neg_hi:[1,0,0]
	ds_read_b128 v[146:149], v109 offset:2832
	v_pk_fma_f32 v[24:25], v[152:153], v[8:9], v[24:25] neg_lo:[1,0,0] neg_hi:[1,0,0]
	ds_read_b128 v[150:153], v109 offset:3072
	v_add_f32_e32 v14, v28, v14
	v_add_f32_e32 v34, v34, v15
	v_add_f32_e32 v38, v38, v18
	v_add_f32_e32 v42, v42, v19
	s_waitcnt lgkmcnt(5)
	v_fma_f32 v15, -v154, v14, v34
	ds_read_b128 v[154:157], v109 offset:3328
	v_fma_f32 v38, -v158, v14, v38
	v_fma_f32 v42, -v220, v14, v42
	v_fma_f32 v18, -v159, v15, v38
	ds_read_b128 v[158:161], v109 offset:3584
	v_fma_f32 v42, -v221, v15, v42
	v_fma_f32 v19, -v222, v18, v42
	ds_read_b128 v[220:223], v109 offset:3840
	s_waitcnt lgkmcnt(4)
	v_pk_fma_f32 v[10:11], v[230:231], v[14:15], v[10:11] neg_lo:[1,0,0] neg_hi:[1,0,0]
	v_pk_fma_f32 v[16:17], v[234:235], v[14:15], v[16:17] neg_lo:[1,0,0] neg_hi:[1,0,0]
	v_pk_fma_f32 v[20:21], v[142:143], v[14:15], v[20:21] neg_lo:[1,0,0] neg_hi:[1,0,0]
	v_pk_fma_f32 v[24:25], v[146:147], v[14:15], v[24:25] neg_lo:[1,0,0] neg_hi:[1,0,0]
	v_pk_fma_f32 v[10:11], v[232:233], v[18:19], v[10:11] neg_lo:[1,0,0] neg_hi:[1,0,0]
	ds_read_b128 v[230:233], v109 offset:3088
	v_pk_fma_f32 v[16:17], v[236:237], v[18:19], v[16:17] neg_lo:[1,0,0] neg_hi:[1,0,0]
	ds_read_b128 v[234:237], v109 offset:3344
	v_pk_fma_f32 v[20:21], v[144:145], v[18:19], v[20:21] neg_lo:[1,0,0] neg_hi:[1,0,0]
	ds_read_b128 v[142:145], v109 offset:3600
	v_pk_fma_f32 v[24:25], v[148:149], v[18:19], v[24:25] neg_lo:[1,0,0] neg_hi:[1,0,0]
	ds_read_b128 v[146:149], v109 offset:3856
	v_add_f32_e32 v10, v10, v11
	s_waitcnt lgkmcnt(5)
	v_pk_mul_f32 v[28:29], v[150:151], v[0:1] neg_lo:[1,0] neg_hi:[1,0]
	v_pk_mul_f32 v[34:35], v[154:155], v[0:1] neg_lo:[1,0] neg_hi:[1,0]
	v_add_f32_e32 v16, v16, v17
	v_pk_mul_f32 v[38:39], v[158:159], v[0:1] neg_lo:[1,0] neg_hi:[1,0]
	s_waitcnt lgkmcnt(4)
	v_pk_mul_f32 v[42:43], v[220:221], v[0:1] neg_lo:[1,0] neg_hi:[1,0]
	v_add_f32_e32 v20, v20, v21
	v_pk_fma_f32 v[28:29], v[152:153], v[8:9], v[28:29] neg_lo:[1,0,0] neg_hi:[1,0,0]
	ds_read_b128 v[150:153], v109 offset:2336
	v_pk_fma_f32 v[34:35], v[156:157], v[8:9], v[34:35] neg_lo:[1,0,0] neg_hi:[1,0,0]
	ds_read_b128 v[154:157], v109 offset:2592
	v_add_f32_e32 v24, v24, v25
	v_pk_fma_f32 v[38:39], v[160:161], v[8:9], v[38:39] neg_lo:[1,0,0] neg_hi:[1,0,0]
	ds_read_b128 v[158:161], v109 offset:2848
	v_pk_fma_f32 v[42:43], v[222:223], v[8:9], v[42:43] neg_lo:[1,0,0] neg_hi:[1,0,0]
	ds_read_b128 v[220:223], v109 offset:3104
	v_add_f32_e32 v22, v10, v22
	s_waitcnt lgkmcnt(5)
	v_pk_fma_f32 v[28:29], v[230:231], v[14:15], v[28:29] neg_lo:[1,0,0] neg_hi:[1,0,0]
	v_pk_fma_f32 v[34:35], v[234:235], v[14:15], v[34:35] neg_lo:[1,0,0] neg_hi:[1,0,0]
	v_add_f32_e32 v16, v16, v23
	v_pk_fma_f32 v[38:39], v[142:143], v[14:15], v[38:39] neg_lo:[1,0,0] neg_hi:[1,0,0]
	s_waitcnt lgkmcnt(4)
	v_pk_fma_f32 v[42:43], v[146:147], v[14:15], v[42:43] neg_lo:[1,0,0] neg_hi:[1,0,0]
	v_add_f32_e32 v20, v20, v26
	v_pk_fma_f32 v[28:29], v[232:233], v[18:19], v[28:29] neg_lo:[1,0,0] neg_hi:[1,0,0]
	ds_read_b128 v[230:233], v109 offset:3360
	v_pk_fma_f32 v[34:35], v[236:237], v[18:19], v[34:35] neg_lo:[1,0,0] neg_hi:[1,0,0]
	ds_read_b128 v[234:237], v109 offset:3616
	v_add_f32_e32 v24, v24, v27
	v_pk_fma_f32 v[38:39], v[144:145], v[18:19], v[38:39] neg_lo:[1,0,0] neg_hi:[1,0,0]
	ds_read_b128 v[142:145], v109 offset:3872
	v_pk_fma_f32 v[42:43], v[148:149], v[18:19], v[42:43] neg_lo:[1,0,0] neg_hi:[1,0,0]
	ds_read_b128 v[146:149], v109 offset:4096
	s_waitcnt lgkmcnt(5)
; #define LAS __attribute__((address_space(3)))
; __device__ __forceinline__ void gdn_local_unit(LAS unsigned char* lds, const GdnP& P, int unit, const int tid, const int pf) {
;     ...
;         for (int c = 1; c < 64; ++c) { f32x2 sp = (f32x2){sol2[c >> 1][c & 1], 0.f};
; #pragma unroll
;             for (int jb = 0; jb <= (c - 1) / 4; ++jb) { const f32x4 m4 = *(const LAS f32x4*)(Ms + c * 64 + 4 * jb);
;                 sp -= (f32x2){m4.x, m4.y} * sol2[2 * jb]; sp -= (f32x2){m4.z, m4.w} * sol2[2 * jb + 1]; }
;             sol2[c >> 1][c & 1] = sp.x + sp.y; }
	v_fma_f32 v23, -v150, v22, v16
	ds_read_b128 v[150:153], v109 offset:4352
	v_fma_f32 v20, -v154, v22, v20
	v_fma_f32 v24, -v158, v22, v24
	v_fma_f32 v26, -v155, v23, v20
	ds_read_b128 v[154:157], v109 offset:4608
	v_fma_f32 v24, -v159, v23, v24
	v_fma_f32 v27, -v160, v26, v24
	ds_read_b128 v[158:161], v109 offset:4864
	s_waitcnt lgkmcnt(4)
	v_pk_fma_f32 v[28:29], v[220:221], v[22:23], v[28:29] neg_lo:[1,0,0] neg_hi:[1,0,0]
	v_pk_fma_f32 v[34:35], v[230:231], v[22:23], v[34:35] neg_lo:[1,0,0] neg_hi:[1,0,0]
	v_pk_fma_f32 v[38:39], v[234:235], v[22:23], v[38:39] neg_lo:[1,0,0] neg_hi:[1,0,0]
	v_pk_fma_f32 v[42:43], v[142:143], v[22:23], v[42:43] neg_lo:[1,0,0] neg_hi:[1,0,0]
	v_pk_fma_f32 v[28:29], v[222:223], v[26:27], v[28:29] neg_lo:[1,0,0] neg_hi:[1,0,0]
	ds_read_b128 v[220:223], v109 offset:4112
	v_pk_fma_f32 v[34:35], v[232:233], v[26:27], v[34:35] neg_lo:[1,0,0] neg_hi:[1,0,0]
	ds_read_b128 v[230:233], v109 offset:4368
	v_pk_fma_f32 v[38:39], v[236:237], v[26:27], v[38:39] neg_lo:[1,0,0] neg_hi:[1,0,0]
	ds_read_b128 v[234:237], v109 offset:4624
	v_pk_fma_f32 v[42:43], v[144:145], v[26:27], v[42:43] neg_lo:[1,0,0] neg_hi:[1,0,0]
	ds_read_b128 v[142:145], v109 offset:4880
	v_add_f32_e32 v28, v28, v29
	s_waitcnt lgkmcnt(5)
	v_pk_mul_f32 v[10:11], v[146:147], v[0:1] neg_lo:[1,0] neg_hi:[1,0]
	v_pk_mul_f32 v[16:17], v[150:151], v[0:1] neg_lo:[1,0] neg_hi:[1,0]
	v_add_f32_e32 v34, v34, v35
	v_pk_mul_f32 v[20:21], v[154:155], v[0:1] neg_lo:[1,0] neg_hi:[1,0]
	s_waitcnt lgkmcnt(4)
	v_pk_mul_f32 v[24:25], v[158:159], v[0:1] neg_lo:[1,0] neg_hi:[1,0]
	v_add_f32_e32 v38, v38, v39
	v_pk_fma_f32 v[10:11], v[148:149], v[8:9], v[10:11] neg_lo:[1,0,0] neg_hi:[1,0,0]
	ds_read_b128 v[146:149], v109 offset:3376
	v_pk_fma_f32 v[16:17], v[152:153], v[8:9], v[16:17] neg_lo:[1,0,0] neg_hi:[1,0,0]
	ds_read_b128 v[150:153], v109 offset:4128
	v_add_f32_e32 v42, v42, v43
	v_pk_fma_f32 v[20:21], v[156:157], v[8:9], v[20:21] neg_lo:[1,0,0] neg_hi:[1,0,0]
	ds_read_b128 v[154:157], v109 offset:4384
	v_pk_fma_f32 v[24:25], v[160:161], v[8:9], v[24:25] neg_lo:[1,0,0] neg_hi:[1,0,0]
	ds_read_b128 v[158:161], v109 offset:3632
	v_add_f32_e32 v30, v28, v30
	s_waitcnt lgkmcnt(5)
	v_pk_fma_f32 v[10:11], v[220:221], v[14:15], v[10:11] neg_lo:[1,0,0] neg_hi:[1,0,0]
	v_pk_fma_f32 v[16:17], v[230:231], v[14:15], v[16:17] neg_lo:[1,0,0] neg_hi:[1,0,0]
	v_add_f32_e32 v34, v34, v31
	v_pk_fma_f32 v[20:21], v[234:235], v[14:15], v[20:21] neg_lo:[1,0,0] neg_hi:[1,0,0]
	s_waitcnt lgkmcnt(4)
	v_pk_fma_f32 v[24:25], v[142:143], v[14:15], v[24:25] neg_lo:[1,0,0] neg_hi:[1,0,0]
	v_add_f32_e32 v38, v38, v36
	v_pk_fma_f32 v[10:11], v[222:223], v[18:19], v[10:11] neg_lo:[1,0,0] neg_hi:[1,0,0]
	ds_read_b128 v[220:223], v109 offset:4640
	v_pk_fma_f32 v[16:17], v[232:233], v[18:19], v[16:17] neg_lo:[1,0,0] neg_hi:[1,0,0]
	ds_read_b128 v[230:233], v109 offset:4896
	v_add_f32_e32 v42, v42, v37
	v_pk_fma_f32 v[20:21], v[236:237], v[18:19], v[20:21] neg_lo:[1,0,0] neg_hi:[1,0,0]
	ds_read_b128 v[234:237], v109 offset:3888
	v_pk_fma_f32 v[24:25], v[144:145], v[18:19], v[24:25] neg_lo:[1,0,0] neg_hi:[1,0,0]
	ds_read_b128 v[142:145], v109 offset:4144
	s_waitcnt lgkmcnt(4)
	v_fma_f32 v31, -v146, v30, v34
	ds_read_b128 v[146:149], v109 offset:4400
	v_pk_fma_f32 v[10:11], v[150:151], v[22:23], v[10:11] neg_lo:[1,0,0] neg_hi:[1,0,0]
	v_pk_fma_f32 v[16:17], v[154:155], v[22:23], v[16:17] neg_lo:[1,0,0] neg_hi:[1,0,0]
	v_fma_f32 v38, -v158, v30, v38
	s_waitcnt lgkmcnt(2)
	v_pk_fma_f32 v[20:21], v[220:221], v[22:23], v[20:21] neg_lo:[1,0,0] neg_hi:[1,0,0]
	v_pk_fma_f32 v[24:25], v[230:231], v[22:23], v[24:25] neg_lo:[1,0,0] neg_hi:[1,0,0]
	v_fma_f32 v42, -v234, v30, v42
	v_pk_fma_f32 v[10:11], v[152:153], v[26:27], v[10:11] neg_lo:[1,0,0] neg_hi:[1,0,0]
	ds_read_b128 v[150:153], v109 offset:4656
	v_pk_fma_f32 v[16:17], v[156:157], v[26:27], v[16:17] neg_lo:[1,0,0] neg_hi:[1,0,0]
	ds_read_b128 v[154:157], v109 offset:4912
	v_fma_f32 v36, -v159, v31, v38
	ds_read_b128 v[158:161], v109 offset:5120
	v_pk_fma_f32 v[20:21], v[222:223], v[26:27], v[20:21] neg_lo:[1,0,0] neg_hi:[1,0,0]
	ds_read_b128 v[220:223], v109 offset:5376
	v_pk_fma_f32 v[24:25], v[232:233], v[26:27], v[24:25] neg_lo:[1,0,0] neg_hi:[1,0,0]
	ds_read_b128 v[230:233], v109 offset:5632
	v_fma_f32 v42, -v235, v31, v42
	v_fma_f32 v37, -v236, v36, v42
	ds_read_b128 v[234:237], v109 offset:5888
	s_waitcnt lgkmcnt(4)
	v_pk_fma_f32 v[10:11], v[142:143], v[30:31], v[10:11] neg_lo:[1,0,0] neg_hi:[1,0,0]
	v_pk_fma_f32 v[16:17], v[146:147], v[30:31], v[16:17] neg_lo:[1,0,0] neg_hi:[1,0,0]
	v_pk_fma_f32 v[20:21], v[150:151], v[30:31], v[20:21] neg_lo:[1,0,0] neg_hi:[1,0,0]
	v_pk_fma_f32 v[24:25], v[154:155], v[30:31], v[24:25] neg_lo:[1,0,0] neg_hi:[1,0,0]
	v_pk_fma_f32 v[10:11], v[144:145], v[36:37], v[10:11] neg_lo:[1,0,0] neg_hi:[1,0,0]
	ds_read_b128 v[142:145], v109 offset:5136
	v_pk_fma_f32 v[16:17], v[148:149], v[36:37], v[16:17] neg_lo:[1,0,0] neg_hi:[1,0,0]
	ds_read_b128 v[146:149], v109 offset:5392
	v_pk_fma_f32 v[20:21], v[152:153], v[36:37], v[20:21] neg_lo:[1,0,0] neg_hi:[1,0,0]
	ds_read_b128 v[150:153], v109 offset:5648
	v_pk_fma_f32 v[24:25], v[156:157], v[36:37], v[24:25] neg_lo:[1,0,0] neg_hi:[1,0,0]
	ds_read_b128 v[154:157], v109 offset:5904
	v_add_f32_e32 v10, v10, v11
	s_waitcnt lgkmcnt(5)
	v_pk_mul_f32 v[28:29], v[158:159], v[0:1] neg_lo:[1,0] neg_hi:[1,0]
	v_pk_mul_f32 v[34:35], v[220:221], v[0:1] neg_lo:[1,0] neg_hi:[1,0]
	v_add_f32_e32 v16, v16, v17
	v_pk_mul_f32 v[38:39], v[230:231], v[0:1] neg_lo:[1,0] neg_hi:[1,0]
	s_waitcnt lgkmcnt(4)
; #define LAS __attribute__((address_space(3)))
; __device__ __forceinline__ void gdn_local_unit(LAS unsigned char* lds, const GdnP& P, int unit, const int tid, const int pf) {
;     ...
;         for (int c = 1; c < 64; ++c) { f32x2 sp = (f32x2){sol2[c >> 1][c & 1], 0.f};
; #pragma unroll
;             for (int jb = 0; jb <= (c - 1) / 4; ++jb) { const f32x4 m4 = *(const LAS f32x4*)(Ms + c * 64 + 4 * jb);
;                 sp -= (f32x2){m4.x, m4.y} * sol2[2 * jb]; sp -= (f32x2){m4.z, m4.w} * sol2[2 * jb + 1]; }
;             sol2[c >> 1][c & 1] = sp.x + sp.y; }
	v_pk_mul_f32 v[42:43], v[234:235], v[0:1] neg_lo:[1,0] neg_hi:[1,0]
	v_add_f32_e32 v20, v20, v21
	v_pk_fma_f32 v[28:29], v[160:161], v[8:9], v[28:29] neg_lo:[1,0,0] neg_hi:[1,0,0]
	ds_read_b128 v[158:161], v109 offset:4416
	v_pk_fma_f32 v[34:35], v[222:223], v[8:9], v[34:35] neg_lo:[1,0,0] neg_hi:[1,0,0]
	ds_read_b128 v[220:223], v109 offset:5152
	v_add_f32_e32 v24, v24, v25
	v_pk_fma_f32 v[38:39], v[232:233], v[8:9], v[38:39] neg_lo:[1,0,0] neg_hi:[1,0,0]
	ds_read_b128 v[230:233], v109 offset:5408
	v_pk_fma_f32 v[42:43], v[236:237], v[8:9], v[42:43] neg_lo:[1,0,0] neg_hi:[1,0,0]
	ds_read_b128 v[234:237], v109 offset:4672
	v_add_f32_e32 v40, v10, v40
	s_waitcnt lgkmcnt(5)
	v_pk_fma_f32 v[28:29], v[142:143], v[14:15], v[28:29] neg_lo:[1,0,0] neg_hi:[1,0,0]
	v_pk_fma_f32 v[34:35], v[146:147], v[14:15], v[34:35] neg_lo:[1,0,0] neg_hi:[1,0,0]
	v_add_f32_e32 v16, v16, v41
	v_pk_fma_f32 v[38:39], v[150:151], v[14:15], v[38:39] neg_lo:[1,0,0] neg_hi:[1,0,0]
	s_waitcnt lgkmcnt(4)
	v_pk_fma_f32 v[42:43], v[154:155], v[14:15], v[42:43] neg_lo:[1,0,0] neg_hi:[1,0,0]
	v_add_f32_e32 v20, v20, v44
	v_pk_fma_f32 v[28:29], v[144:145], v[18:19], v[28:29] neg_lo:[1,0,0] neg_hi:[1,0,0]
	ds_read_b128 v[142:145], v109 offset:5664
	v_pk_fma_f32 v[34:35], v[148:149], v[18:19], v[34:35] neg_lo:[1,0,0] neg_hi:[1,0,0]
	ds_read_b128 v[146:149], v109 offset:5920
	v_add_f32_e32 v24, v24, v45
	v_pk_fma_f32 v[38:39], v[152:153], v[18:19], v[38:39] neg_lo:[1,0,0] neg_hi:[1,0,0]
	ds_read_b128 v[150:153], v109 offset:4928
	v_pk_fma_f32 v[42:43], v[156:157], v[18:19], v[42:43] neg_lo:[1,0,0] neg_hi:[1,0,0]
	ds_read_b128 v[154:157], v109 offset:5168
	s_waitcnt lgkmcnt(4)
	v_fma_f32 v41, -v158, v40, v16
	ds_read_b128 v[158:161], v109 offset:5424
	v_pk_fma_f32 v[28:29], v[220:221], v[22:23], v[28:29] neg_lo:[1,0,0] neg_hi:[1,0,0]
	v_pk_fma_f32 v[34:35], v[230:231], v[22:23], v[34:35] neg_lo:[1,0,0] neg_hi:[1,0,0]
	v_fma_f32 v20, -v234, v40, v20
	s_waitcnt lgkmcnt(2)
	v_pk_fma_f32 v[38:39], v[142:143], v[22:23], v[38:39] neg_lo:[1,0,0] neg_hi:[1,0,0]
	v_pk_fma_f32 v[42:43], v[146:147], v[22:23], v[42:43] neg_lo:[1,0,0] neg_hi:[1,0,0]
	v_fma_f32 v24, -v150, v40, v24
	v_pk_fma_f32 v[28:29], v[222:223], v[26:27], v[28:29] neg_lo:[1,0,0] neg_hi:[1,0,0]
	ds_read_b128 v[220:223], v109 offset:5680
	v_pk_fma_f32 v[34:35], v[232:233], v[26:27], v[34:35] neg_lo:[1,0,0] neg_hi:[1,0,0]
	ds_read_b128 v[230:233], v109 offset:5936
	v_fma_f32 v44, -v235, v41, v20
	ds_read_b128 v[234:237], v109 offset:5184
	v_pk_fma_f32 v[38:39], v[144:145], v[26:27], v[38:39] neg_lo:[1,0,0] neg_hi:[1,0,0]
	ds_read_b128 v[142:145], v109 offset:5440
	v_pk_fma_f32 v[42:43], v[148:149], v[26:27], v[42:43] neg_lo:[1,0,0] neg_hi:[1,0,0]
	ds_read_b128 v[146:149], v109 offset:5696
	v_fma_f32 v24, -v151, v41, v24
	s_waitcnt lgkmcnt(4)
	v_pk_fma_f32 v[28:29], v[154:155], v[30:31], v[28:29] neg_lo:[1,0,0] neg_hi:[1,0,0]
	v_pk_fma_f32 v[34:35], v[158:159], v[30:31], v[34:35] neg_lo:[1,0,0] neg_hi:[1,0,0]
	v_fma_f32 v45, -v152, v44, v24
	ds_read_b128 v[150:153], v109 offset:5952
	v_pk_fma_f32 v[38:39], v[220:221], v[30:31], v[38:39] neg_lo:[1,0,0] neg_hi:[1,0,0]
	s_waitcnt lgkmcnt(4)
	v_pk_fma_f32 v[42:43], v[230:231], v[30:31], v[42:43] neg_lo:[1,0,0] neg_hi:[1,0,0]
	v_pk_fma_f32 v[28:29], v[156:157], v[36:37], v[28:29] neg_lo:[1,0,0] neg_hi:[1,0,0]
	ds_read_b128 v[154:157], v109 offset:6144
	v_pk_fma_f32 v[34:35], v[160:161], v[36:37], v[34:35] neg_lo:[1,0,0] neg_hi:[1,0,0]
	ds_read_b128 v[158:161], v109 offset:6400
	v_pk_fma_f32 v[38:39], v[222:223], v[36:37], v[38:39] neg_lo:[1,0,0] neg_hi:[1,0,0]
	ds_read_b128 v[220:223], v109 offset:6656
	v_pk_fma_f32 v[42:43], v[232:233], v[36:37], v[42:43] neg_lo:[1,0,0] neg_hi:[1,0,0]
	ds_read_b128 v[230:233], v109 offset:6912
	s_waitcnt lgkmcnt(4)
	v_pk_fma_f32 v[28:29], v[234:235], v[40:41], v[28:29] neg_lo:[1,0,0] neg_hi:[1,0,0]
	v_pk_fma_f32 v[34:35], v[142:143], v[40:41], v[34:35] neg_lo:[1,0,0] neg_hi:[1,0,0]
	v_pk_fma_f32 v[38:39], v[146:147], v[40:41], v[38:39] neg_lo:[1,0,0] neg_hi:[1,0,0]
	v_pk_fma_f32 v[42:43], v[150:151], v[40:41], v[42:43] neg_lo:[1,0,0] neg_hi:[1,0,0]
	v_pk_fma_f32 v[28:29], v[236:237], v[44:45], v[28:29] neg_lo:[1,0,0] neg_hi:[1,0,0]
	ds_read_b128 v[234:237], v109 offset:6160
	v_pk_fma_f32 v[34:35], v[144:145], v[44:45], v[34:35] neg_lo:[1,0,0] neg_hi:[1,0,0]
	ds_read_b128 v[142:145], v109 offset:6416
	v_pk_fma_f32 v[38:39], v[148:149], v[44:45], v[38:39] neg_lo:[1,0,0] neg_hi:[1,0,0]
	ds_read_b128 v[146:149], v109 offset:6672
	v_pk_fma_f32 v[42:43], v[152:153], v[44:45], v[42:43] neg_lo:[1,0,0] neg_hi:[1,0,0]
	ds_read_b128 v[150:153], v109 offset:6928
	v_add_f32_e32 v28, v28, v29
	s_waitcnt lgkmcnt(5)
	v_pk_mul_f32 v[10:11], v[154:155], v[0:1] neg_lo:[1,0] neg_hi:[1,0]
	v_pk_mul_f32 v[16:17], v[158:159], v[0:1] neg_lo:[1,0] neg_hi:[1,0]
	v_add_f32_e32 v34, v34, v35
	v_pk_mul_f32 v[20:21], v[220:221], v[0:1] neg_lo:[1,0] neg_hi:[1,0]
	s_waitcnt lgkmcnt(4)
	v_pk_mul_f32 v[24:25], v[230:231], v[0:1] neg_lo:[1,0] neg_hi:[1,0]
	v_add_f32_e32 v38, v38, v39
	v_pk_fma_f32 v[10:11], v[156:157], v[8:9], v[10:11] neg_lo:[1,0,0] neg_hi:[1,0,0]
	ds_read_b128 v[154:157], v109 offset:5456
	v_pk_fma_f32 v[16:17], v[160:161], v[8:9], v[16:17] neg_lo:[1,0,0] neg_hi:[1,0,0]
	ds_read_b128 v[158:161], v109 offset:6176
	v_add_f32_e32 v42, v42, v43
	v_pk_fma_f32 v[20:21], v[222:223], v[8:9], v[20:21] neg_lo:[1,0,0] neg_hi:[1,0,0]
	ds_read_b128 v[220:223], v109 offset:6432
	v_pk_fma_f32 v[24:25], v[232:233], v[8:9], v[24:25] neg_lo:[1,0,0] neg_hi:[1,0,0]
	ds_read_b128 v[230:233], v109 offset:5712
	v_add_f32_e32 v50, v28, v50
	s_waitcnt lgkmcnt(5)
; #define LAS __attribute__((address_space(3)))
; __device__ __forceinline__ void gdn_local_unit(LAS unsigned char* lds, const GdnP& P, int unit, const int tid, const int pf) {
;     ...
;         for (int c = 1; c < 64; ++c) { f32x2 sp = (f32x2){sol2[c >> 1][c & 1], 0.f};
; #pragma unroll
;             for (int jb = 0; jb <= (c - 1) / 4; ++jb) { const f32x4 m4 = *(const LAS f32x4*)(Ms + c * 64 + 4 * jb);
;                 sp -= (f32x2){m4.x, m4.y} * sol2[2 * jb]; sp -= (f32x2){m4.z, m4.w} * sol2[2 * jb + 1]; }
;             sol2[c >> 1][c & 1] = sp.x + sp.y; }
	v_pk_fma_f32 v[10:11], v[234:235], v[14:15], v[10:11] neg_lo:[1,0,0] neg_hi:[1,0,0]
	v_pk_fma_f32 v[16:17], v[142:143], v[14:15], v[16:17] neg_lo:[1,0,0] neg_hi:[1,0,0]
	v_add_f32_e32 v34, v34, v51
	v_pk_fma_f32 v[20:21], v[146:147], v[14:15], v[20:21] neg_lo:[1,0,0] neg_hi:[1,0,0]
	s_waitcnt lgkmcnt(4)
	v_pk_fma_f32 v[24:25], v[150:151], v[14:15], v[24:25] neg_lo:[1,0,0] neg_hi:[1,0,0]
	v_add_f32_e32 v38, v38, v54
	v_pk_fma_f32 v[10:11], v[236:237], v[18:19], v[10:11] neg_lo:[1,0,0] neg_hi:[1,0,0]
	ds_read_b128 v[234:237], v109 offset:6688
	v_pk_fma_f32 v[16:17], v[144:145], v[18:19], v[16:17] neg_lo:[1,0,0] neg_hi:[1,0,0]
	ds_read_b128 v[142:145], v109 offset:6944
	v_add_f32_e32 v42, v42, v55
	v_pk_fma_f32 v[20:21], v[148:149], v[18:19], v[20:21] neg_lo:[1,0,0] neg_hi:[1,0,0]
	ds_read_b128 v[146:149], v109 offset:5968
	v_pk_fma_f32 v[24:25], v[152:153], v[18:19], v[24:25] neg_lo:[1,0,0] neg_hi:[1,0,0]
	ds_read_b128 v[150:153], v109 offset:6192
	s_waitcnt lgkmcnt(4)
	v_fma_f32 v51, -v154, v50, v34
	ds_read_b128 v[154:157], v109 offset:6448
	v_pk_fma_f32 v[10:11], v[158:159], v[22:23], v[10:11] neg_lo:[1,0,0] neg_hi:[1,0,0]
	v_pk_fma_f32 v[16:17], v[220:221], v[22:23], v[16:17] neg_lo:[1,0,0] neg_hi:[1,0,0]
	v_fma_f32 v38, -v230, v50, v38
	s_waitcnt lgkmcnt(2)
	v_pk_fma_f32 v[20:21], v[234:235], v[22:23], v[20:21] neg_lo:[1,0,0] neg_hi:[1,0,0]
	v_pk_fma_f32 v[24:25], v[142:143], v[22:23], v[24:25] neg_lo:[1,0,0] neg_hi:[1,0,0]
	v_fma_f32 v42, -v146, v50, v42
	v_pk_fma_f32 v[10:11], v[160:161], v[26:27], v[10:11] neg_lo:[1,0,0] neg_hi:[1,0,0]
	ds_read_b128 v[158:161], v109 offset:6704
	v_pk_fma_f32 v[16:17], v[222:223], v[26:27], v[16:17] neg_lo:[1,0,0] neg_hi:[1,0,0]
	ds_read_b128 v[220:223], v109 offset:6960
	v_fma_f32 v54, -v231, v51, v38
	ds_read_b128 v[230:233], v109 offset:6208
	v_pk_fma_f32 v[20:21], v[236:237], v[26:27], v[20:21] neg_lo:[1,0,0] neg_hi:[1,0,0]
	ds_read_b128 v[234:237], v109 offset:6464
	v_pk_fma_f32 v[24:25], v[144:145], v[26:27], v[24:25] neg_lo:[1,0,0] neg_hi:[1,0,0]
	ds_read_b128 v[142:145], v109 offset:6720
	v_fma_f32 v42, -v147, v51, v42
	s_waitcnt lgkmcnt(4)
	v_pk_fma_f32 v[10:11], v[150:151], v[30:31], v[10:11] neg_lo:[1,0,0] neg_hi:[1,0,0]
	v_pk_fma_f32 v[16:17], v[154:155], v[30:31], v[16:17] neg_lo:[1,0,0] neg_hi:[1,0,0]
	v_fma_f32 v55, -v148, v54, v42
	ds_read_b128 v[146:149], v109 offset:6976
	v_pk_fma_f32 v[20:21], v[158:159], v[30:31], v[20:21] neg_lo:[1,0,0] neg_hi:[1,0,0]
	s_waitcnt lgkmcnt(4)
	v_pk_fma_f32 v[24:25], v[220:221], v[30:31], v[24:25] neg_lo:[1,0,0] neg_hi:[1,0,0]
	v_pk_fma_f32 v[10:11], v[152:153], v[36:37], v[10:11] neg_lo:[1,0,0] neg_hi:[1,0,0]
	ds_read_b128 v[150:153], v109 offset:6224
	v_pk_fma_f32 v[16:17], v[156:157], v[36:37], v[16:17] neg_lo:[1,0,0] neg_hi:[1,0,0]
	ds_read_b128 v[154:157], v109 offset:6480
	v_pk_fma_f32 v[20:21], v[160:161], v[36:37], v[20:21] neg_lo:[1,0,0] neg_hi:[1,0,0]
	ds_read_b128 v[158:161], v109 offset:6736
	v_pk_fma_f32 v[24:25], v[222:223], v[36:37], v[24:25] neg_lo:[1,0,0] neg_hi:[1,0,0]
	ds_read_b128 v[220:223], v109 offset:6992
	s_waitcnt lgkmcnt(4)
	v_pk_fma_f32 v[10:11], v[230:231], v[40:41], v[10:11] neg_lo:[1,0,0] neg_hi:[1,0,0]
	v_pk_fma_f32 v[16:17], v[234:235], v[40:41], v[16:17] neg_lo:[1,0,0] neg_hi:[1,0,0]
	v_pk_fma_f32 v[20:21], v[142:143], v[40:41], v[20:21] neg_lo:[1,0,0] neg_hi:[1,0,0]
	v_pk_fma_f32 v[24:25], v[146:147], v[40:41], v[24:25] neg_lo:[1,0,0] neg_hi:[1,0,0]
	v_pk_fma_f32 v[10:11], v[232:233], v[44:45], v[10:11] neg_lo:[1,0,0] neg_hi:[1,0,0]
	ds_read_b128 v[230:233], v109 offset:7168
	v_pk_fma_f32 v[16:17], v[236:237], v[44:45], v[16:17] neg_lo:[1,0,0] neg_hi:[1,0,0]
	ds_read_b128 v[234:237], v109 offset:7424
	v_pk_fma_f32 v[20:21], v[144:145], v[44:45], v[20:21] neg_lo:[1,0,0] neg_hi:[1,0,0]
	ds_read_b128 v[142:145], v109 offset:7680
	v_pk_fma_f32 v[24:25], v[148:149], v[44:45], v[24:25] neg_lo:[1,0,0] neg_hi:[1,0,0]
	ds_read_b128 v[146:149], v109 offset:7936
	s_waitcnt lgkmcnt(4)
	v_pk_fma_f32 v[10:11], v[150:151], v[50:51], v[10:11] neg_lo:[1,0,0] neg_hi:[1,0,0]
	v_pk_fma_f32 v[16:17], v[154:155], v[50:51], v[16:17] neg_lo:[1,0,0] neg_hi:[1,0,0]
	v_pk_fma_f32 v[20:21], v[158:159], v[50:51], v[20:21] neg_lo:[1,0,0] neg_hi:[1,0,0]
	v_pk_fma_f32 v[24:25], v[220:221], v[50:51], v[24:25] neg_lo:[1,0,0] neg_hi:[1,0,0]
	v_pk_fma_f32 v[10:11], v[152:153], v[54:55], v[10:11] neg_lo:[1,0,0] neg_hi:[1,0,0]
	ds_read_b128 v[150:153], v109 offset:7184
	v_pk_fma_f32 v[16:17], v[156:157], v[54:55], v[16:17] neg_lo:[1,0,0] neg_hi:[1,0,0]
	ds_read_b128 v[154:157], v109 offset:7440
	v_pk_fma_f32 v[20:21], v[160:161], v[54:55], v[20:21] neg_lo:[1,0,0] neg_hi:[1,0,0]
	ds_read_b128 v[158:161], v109 offset:7696
	v_pk_fma_f32 v[24:25], v[222:223], v[54:55], v[24:25] neg_lo:[1,0,0] neg_hi:[1,0,0]
	ds_read_b128 v[220:223], v109 offset:7952
	v_add_f32_e32 v10, v10, v11
	s_waitcnt lgkmcnt(5)
	v_pk_mul_f32 v[28:29], v[230:231], v[0:1] neg_lo:[1,0] neg_hi:[1,0]
	v_pk_mul_f32 v[34:35], v[234:235], v[0:1] neg_lo:[1,0] neg_hi:[1,0]
	v_add_f32_e32 v16, v16, v17
	v_pk_mul_f32 v[38:39], v[142:143], v[0:1] neg_lo:[1,0] neg_hi:[1,0]
	s_waitcnt lgkmcnt(4)
	v_pk_mul_f32 v[42:43], v[146:147], v[0:1] neg_lo:[1,0] neg_hi:[1,0]
	v_add_f32_e32 v20, v20, v21
	v_pk_fma_f32 v[28:29], v[232:233], v[8:9], v[28:29] neg_lo:[1,0,0] neg_hi:[1,0,0]
	ds_read_b128 v[230:233], v109 offset:6496
	v_pk_fma_f32 v[34:35], v[236:237], v[8:9], v[34:35] neg_lo:[1,0,0] neg_hi:[1,0,0]
	ds_read_b128 v[234:237], v109 offset:7200
	v_add_f32_e32 v24, v24, v25
	v_pk_fma_f32 v[38:39], v[144:145], v[8:9], v[38:39] neg_lo:[1,0,0] neg_hi:[1,0,0]
	ds_read_b128 v[142:145], v109 offset:7456
	v_pk_fma_f32 v[42:43], v[148:149], v[8:9], v[42:43] neg_lo:[1,0,0] neg_hi:[1,0,0]
	ds_read_b128 v[146:149], v109 offset:6752
	v_add_f32_e32 v60, v10, v60
	s_waitcnt lgkmcnt(5)
; #define LAS __attribute__((address_space(3)))
; __device__ __forceinline__ void gdn_local_unit(LAS unsigned char* lds, const GdnP& P, int unit, const int tid, const int pf) {
;     ...
;         for (int c = 1; c < 64; ++c) { f32x2 sp = (f32x2){sol2[c >> 1][c & 1], 0.f};
; #pragma unroll
;             for (int jb = 0; jb <= (c - 1) / 4; ++jb) { const f32x4 m4 = *(const LAS f32x4*)(Ms + c * 64 + 4 * jb);
;                 sp -= (f32x2){m4.x, m4.y} * sol2[2 * jb]; sp -= (f32x2){m4.z, m4.w} * sol2[2 * jb + 1]; }
;             sol2[c >> 1][c & 1] = sp.x + sp.y; }
	v_pk_fma_f32 v[28:29], v[150:151], v[14:15], v[28:29] neg_lo:[1,0,0] neg_hi:[1,0,0]
	v_pk_fma_f32 v[34:35], v[154:155], v[14:15], v[34:35] neg_lo:[1,0,0] neg_hi:[1,0,0]
	v_add_f32_e32 v16, v16, v61
	v_pk_fma_f32 v[38:39], v[158:159], v[14:15], v[38:39] neg_lo:[1,0,0] neg_hi:[1,0,0]
	s_waitcnt lgkmcnt(4)
	v_pk_fma_f32 v[42:43], v[220:221], v[14:15], v[42:43] neg_lo:[1,0,0] neg_hi:[1,0,0]
	v_add_f32_e32 v20, v20, v64
	v_pk_fma_f32 v[28:29], v[152:153], v[18:19], v[28:29] neg_lo:[1,0,0] neg_hi:[1,0,0]
	ds_read_b128 v[150:153], v109 offset:7712
	v_pk_fma_f32 v[34:35], v[156:157], v[18:19], v[34:35] neg_lo:[1,0,0] neg_hi:[1,0,0]
	ds_read_b128 v[154:157], v109 offset:7968
	v_add_f32_e32 v24, v24, v65
	v_pk_fma_f32 v[38:39], v[160:161], v[18:19], v[38:39] neg_lo:[1,0,0] neg_hi:[1,0,0]
	ds_read_b128 v[158:161], v109 offset:7008
	v_pk_fma_f32 v[42:43], v[222:223], v[18:19], v[42:43] neg_lo:[1,0,0] neg_hi:[1,0,0]
	ds_read_b128 v[220:223], v109 offset:7216
	s_waitcnt lgkmcnt(4)
	v_fma_f32 v61, -v230, v60, v16
	ds_read_b128 v[230:233], v109 offset:7472
	v_pk_fma_f32 v[28:29], v[234:235], v[22:23], v[28:29] neg_lo:[1,0,0] neg_hi:[1,0,0]
	v_pk_fma_f32 v[34:35], v[142:143], v[22:23], v[34:35] neg_lo:[1,0,0] neg_hi:[1,0,0]
	v_fma_f32 v20, -v146, v60, v20
	s_waitcnt lgkmcnt(2)
	v_pk_fma_f32 v[38:39], v[150:151], v[22:23], v[38:39] neg_lo:[1,0,0] neg_hi:[1,0,0]
	v_pk_fma_f32 v[42:43], v[154:155], v[22:23], v[42:43] neg_lo:[1,0,0] neg_hi:[1,0,0]
	v_fma_f32 v24, -v158, v60, v24
	v_pk_fma_f32 v[28:29], v[236:237], v[26:27], v[28:29] neg_lo:[1,0,0] neg_hi:[1,0,0]
	ds_read_b128 v[234:237], v109 offset:7728
	v_pk_fma_f32 v[34:35], v[144:145], v[26:27], v[34:35] neg_lo:[1,0,0] neg_hi:[1,0,0]
	ds_read_b128 v[142:145], v109 offset:7984
	v_fma_f32 v64, -v147, v61, v20
	ds_read_b128 v[146:149], v109 offset:7232
	v_pk_fma_f32 v[38:39], v[152:153], v[26:27], v[38:39] neg_lo:[1,0,0] neg_hi:[1,0,0]
	ds_read_b128 v[150:153], v109 offset:7488
	v_pk_fma_f32 v[42:43], v[156:157], v[26:27], v[42:43] neg_lo:[1,0,0] neg_hi:[1,0,0]
	ds_read_b128 v[154:157], v109 offset:7744
	v_fma_f32 v24, -v159, v61, v24
	s_waitcnt lgkmcnt(4)
	v_pk_fma_f32 v[28:29], v[220:221], v[30:31], v[28:29] neg_lo:[1,0,0] neg_hi:[1,0,0]
	v_pk_fma_f32 v[34:35], v[230:231], v[30:31], v[34:35] neg_lo:[1,0,0] neg_hi:[1,0,0]
	v_fma_f32 v65, -v160, v64, v24
	ds_read_b128 v[158:161], v109 offset:8000
	v_pk_fma_f32 v[38:39], v[234:235], v[30:31], v[38:39] neg_lo:[1,0,0] neg_hi:[1,0,0]
	s_waitcnt lgkmcnt(4)
	v_pk_fma_f32 v[42:43], v[142:143], v[30:31], v[42:43] neg_lo:[1,0,0] neg_hi:[1,0,0]
	v_pk_fma_f32 v[28:29], v[222:223], v[36:37], v[28:29] neg_lo:[1,0,0] neg_hi:[1,0,0]
	ds_read_b128 v[220:223], v109 offset:7248
	v_pk_fma_f32 v[34:35], v[232:233], v[36:37], v[34:35] neg_lo:[1,0,0] neg_hi:[1,0,0]
	ds_read_b128 v[230:233], v109 offset:7504
	v_pk_fma_f32 v[38:39], v[236:237], v[36:37], v[38:39] neg_lo:[1,0,0] neg_hi:[1,0,0]
	ds_read_b128 v[234:237], v109 offset:7760
	v_pk_fma_f32 v[42:43], v[144:145], v[36:37], v[42:43] neg_lo:[1,0,0] neg_hi:[1,0,0]
	ds_read_b128 v[142:145], v109 offset:8016
	s_waitcnt lgkmcnt(4)
	v_pk_fma_f32 v[28:29], v[146:147], v[40:41], v[28:29] neg_lo:[1,0,0] neg_hi:[1,0,0]
	v_pk_fma_f32 v[34:35], v[150:151], v[40:41], v[34:35] neg_lo:[1,0,0] neg_hi:[1,0,0]
	v_pk_fma_f32 v[38:39], v[154:155], v[40:41], v[38:39] neg_lo:[1,0,0] neg_hi:[1,0,0]
	v_pk_fma_f32 v[42:43], v[158:159], v[40:41], v[42:43] neg_lo:[1,0,0] neg_hi:[1,0,0]
	v_pk_fma_f32 v[28:29], v[148:149], v[44:45], v[28:29] neg_lo:[1,0,0] neg_hi:[1,0,0]
	ds_read_b128 v[146:149], v109 offset:7264
	v_pk_fma_f32 v[34:35], v[152:153], v[44:45], v[34:35] neg_lo:[1,0,0] neg_hi:[1,0,0]
	ds_read_b128 v[150:153], v109 offset:7520
	v_pk_fma_f32 v[38:39], v[156:157], v[44:45], v[38:39] neg_lo:[1,0,0] neg_hi:[1,0,0]
	ds_read_b128 v[154:157], v109 offset:7776
	v_pk_fma_f32 v[42:43], v[160:161], v[44:45], v[42:43] neg_lo:[1,0,0] neg_hi:[1,0,0]
	ds_read_b128 v[158:161], v109 offset:8032
	s_waitcnt lgkmcnt(4)
	v_pk_fma_f32 v[28:29], v[220:221], v[50:51], v[28:29] neg_lo:[1,0,0] neg_hi:[1,0,0]
	v_pk_fma_f32 v[34:35], v[230:231], v[50:51], v[34:35] neg_lo:[1,0,0] neg_hi:[1,0,0]
	v_pk_fma_f32 v[38:39], v[234:235], v[50:51], v[38:39] neg_lo:[1,0,0] neg_hi:[1,0,0]
	v_pk_fma_f32 v[42:43], v[142:143], v[50:51], v[42:43] neg_lo:[1,0,0] neg_hi:[1,0,0]
	v_pk_fma_f32 v[28:29], v[222:223], v[54:55], v[28:29] neg_lo:[1,0,0] neg_hi:[1,0,0]
	ds_read_b128 v[220:223], v109 offset:8192
	v_pk_fma_f32 v[34:35], v[232:233], v[54:55], v[34:35] neg_lo:[1,0,0] neg_hi:[1,0,0]
	ds_read_b128 v[230:233], v109 offset:8448
	v_pk_fma_f32 v[38:39], v[236:237], v[54:55], v[38:39] neg_lo:[1,0,0] neg_hi:[1,0,0]
	ds_read_b128 v[234:237], v109 offset:8704
	v_pk_fma_f32 v[42:43], v[144:145], v[54:55], v[42:43] neg_lo:[1,0,0] neg_hi:[1,0,0]
	ds_read_b128 v[142:145], v109 offset:8960
	s_waitcnt lgkmcnt(4)
	v_pk_fma_f32 v[28:29], v[146:147], v[60:61], v[28:29] neg_lo:[1,0,0] neg_hi:[1,0,0]
	v_pk_fma_f32 v[34:35], v[150:151], v[60:61], v[34:35] neg_lo:[1,0,0] neg_hi:[1,0,0]
	v_pk_fma_f32 v[38:39], v[154:155], v[60:61], v[38:39] neg_lo:[1,0,0] neg_hi:[1,0,0]
	v_pk_fma_f32 v[42:43], v[158:159], v[60:61], v[42:43] neg_lo:[1,0,0] neg_hi:[1,0,0]
	v_pk_fma_f32 v[28:29], v[148:149], v[64:65], v[28:29] neg_lo:[1,0,0] neg_hi:[1,0,0]
	ds_read_b128 v[146:149], v109 offset:8208
	v_pk_fma_f32 v[34:35], v[152:153], v[64:65], v[34:35] neg_lo:[1,0,0] neg_hi:[1,0,0]
	ds_read_b128 v[150:153], v109 offset:8464
	v_pk_fma_f32 v[38:39], v[156:157], v[64:65], v[38:39] neg_lo:[1,0,0] neg_hi:[1,0,0]
	ds_read_b128 v[154:157], v109 offset:8720
	v_pk_fma_f32 v[42:43], v[160:161], v[64:65], v[42:43] neg_lo:[1,0,0] neg_hi:[1,0,0]
	ds_read_b128 v[158:161], v109 offset:8976
	v_add_f32_e32 v28, v28, v29
	s_waitcnt lgkmcnt(5)
; #define LAS __attribute__((address_space(3)))
; __device__ __forceinline__ void gdn_local_unit(LAS unsigned char* lds, const GdnP& P, int unit, const int tid, const int pf) {
;     ...
;         for (int c = 1; c < 64; ++c) { f32x2 sp = (f32x2){sol2[c >> 1][c & 1], 0.f};
; #pragma unroll
;             for (int jb = 0; jb <= (c - 1) / 4; ++jb) { const f32x4 m4 = *(const LAS f32x4*)(Ms + c * 64 + 4 * jb);
;                 sp -= (f32x2){m4.x, m4.y} * sol2[2 * jb]; sp -= (f32x2){m4.z, m4.w} * sol2[2 * jb + 1]; }
;             sol2[c >> 1][c & 1] = sp.x + sp.y; }
	v_pk_mul_f32 v[10:11], v[220:221], v[0:1] neg_lo:[1,0] neg_hi:[1,0]
	v_pk_mul_f32 v[16:17], v[230:231], v[0:1] neg_lo:[1,0] neg_hi:[1,0]
	v_add_f32_e32 v34, v34, v35
	v_pk_mul_f32 v[20:21], v[234:235], v[0:1] neg_lo:[1,0] neg_hi:[1,0]
	s_waitcnt lgkmcnt(4)
	v_pk_mul_f32 v[24:25], v[142:143], v[0:1] neg_lo:[1,0] neg_hi:[1,0]
	v_add_f32_e32 v38, v38, v39
	v_pk_fma_f32 v[10:11], v[222:223], v[8:9], v[10:11] neg_lo:[1,0,0] neg_hi:[1,0,0]
	ds_read_b128 v[220:223], v109 offset:7536
	v_pk_fma_f32 v[16:17], v[232:233], v[8:9], v[16:17] neg_lo:[1,0,0] neg_hi:[1,0,0]
	ds_read_b128 v[230:233], v109 offset:8224
	v_add_f32_e32 v42, v42, v43
	v_pk_fma_f32 v[20:21], v[236:237], v[8:9], v[20:21] neg_lo:[1,0,0] neg_hi:[1,0,0]
	ds_read_b128 v[234:237], v109 offset:8480
	v_pk_fma_f32 v[24:25], v[144:145], v[8:9], v[24:25] neg_lo:[1,0,0] neg_hi:[1,0,0]
	ds_read_b128 v[142:145], v109 offset:7792
	v_add_f32_e32 v70, v28, v70
	s_waitcnt lgkmcnt(5)
	v_pk_fma_f32 v[10:11], v[146:147], v[14:15], v[10:11] neg_lo:[1,0,0] neg_hi:[1,0,0]
	v_pk_fma_f32 v[16:17], v[150:151], v[14:15], v[16:17] neg_lo:[1,0,0] neg_hi:[1,0,0]
	v_add_f32_e32 v34, v34, v71
	v_pk_fma_f32 v[20:21], v[154:155], v[14:15], v[20:21] neg_lo:[1,0,0] neg_hi:[1,0,0]
	s_waitcnt lgkmcnt(4)
	v_pk_fma_f32 v[24:25], v[158:159], v[14:15], v[24:25] neg_lo:[1,0,0] neg_hi:[1,0,0]
	v_add_f32_e32 v38, v38, v112
	v_pk_fma_f32 v[10:11], v[148:149], v[18:19], v[10:11] neg_lo:[1,0,0] neg_hi:[1,0,0]
	ds_read_b128 v[146:149], v109 offset:8736
	v_pk_fma_f32 v[16:17], v[152:153], v[18:19], v[16:17] neg_lo:[1,0,0] neg_hi:[1,0,0]
	ds_read_b128 v[150:153], v109 offset:8992
	v_add_f32_e32 v42, v42, v113
	v_pk_fma_f32 v[20:21], v[156:157], v[18:19], v[20:21] neg_lo:[1,0,0] neg_hi:[1,0,0]
	ds_read_b128 v[154:157], v109 offset:8048
	v_pk_fma_f32 v[24:25], v[160:161], v[18:19], v[24:25] neg_lo:[1,0,0] neg_hi:[1,0,0]
	ds_read_b128 v[158:161], v109 offset:8240
	s_waitcnt lgkmcnt(4)
	v_fma_f32 v71, -v220, v70, v34
	ds_read_b128 v[220:223], v109 offset:8496
	v_pk_fma_f32 v[10:11], v[230:231], v[22:23], v[10:11] neg_lo:[1,0,0] neg_hi:[1,0,0]
	v_pk_fma_f32 v[16:17], v[234:235], v[22:23], v[16:17] neg_lo:[1,0,0] neg_hi:[1,0,0]
	v_fma_f32 v38, -v142, v70, v38
	s_waitcnt lgkmcnt(2)
	v_pk_fma_f32 v[20:21], v[146:147], v[22:23], v[20:21] neg_lo:[1,0,0] neg_hi:[1,0,0]
	v_pk_fma_f32 v[24:25], v[150:151], v[22:23], v[24:25] neg_lo:[1,0,0] neg_hi:[1,0,0]
	v_fma_f32 v42, -v154, v70, v42
	v_pk_fma_f32 v[10:11], v[232:233], v[26:27], v[10:11] neg_lo:[1,0,0] neg_hi:[1,0,0]
	ds_read_b128 v[230:233], v109 offset:8752
	v_pk_fma_f32 v[16:17], v[236:237], v[26:27], v[16:17] neg_lo:[1,0,0] neg_hi:[1,0,0]
	ds_read_b128 v[234:237], v109 offset:9008
	v_fma_f32 v112, -v143, v71, v38
	ds_read_b128 v[142:145], v109 offset:8256
	v_pk_fma_f32 v[20:21], v[148:149], v[26:27], v[20:21] neg_lo:[1,0,0] neg_hi:[1,0,0]
	ds_read_b128 v[146:149], v109 offset:8512
	v_pk_fma_f32 v[24:25], v[152:153], v[26:27], v[24:25] neg_lo:[1,0,0] neg_hi:[1,0,0]
	ds_read_b128 v[150:153], v109 offset:8768
	v_fma_f32 v42, -v155, v71, v42
	s_waitcnt lgkmcnt(4)
	v_pk_fma_f32 v[10:11], v[158:159], v[30:31], v[10:11] neg_lo:[1,0,0] neg_hi:[1,0,0]
	v_pk_fma_f32 v[16:17], v[220:221], v[30:31], v[16:17] neg_lo:[1,0,0] neg_hi:[1,0,0]
	v_fma_f32 v113, -v156, v112, v42
	ds_read_b128 v[154:157], v109 offset:9024
	v_pk_fma_f32 v[20:21], v[230:231], v[30:31], v[20:21] neg_lo:[1,0,0] neg_hi:[1,0,0]
	s_waitcnt lgkmcnt(4)
	v_pk_fma_f32 v[24:25], v[234:235], v[30:31], v[24:25] neg_lo:[1,0,0] neg_hi:[1,0,0]
	v_pk_fma_f32 v[10:11], v[160:161], v[36:37], v[10:11] neg_lo:[1,0,0] neg_hi:[1,0,0]
	ds_read_b128 v[158:161], v109 offset:8272
	v_pk_fma_f32 v[16:17], v[222:223], v[36:37], v[16:17] neg_lo:[1,0,0] neg_hi:[1,0,0]
	ds_read_b128 v[220:223], v109 offset:8528
	v_pk_fma_f32 v[20:21], v[232:233], v[36:37], v[20:21] neg_lo:[1,0,0] neg_hi:[1,0,0]
	ds_read_b128 v[230:233], v109 offset:8784
	v_pk_fma_f32 v[24:25], v[236:237], v[36:37], v[24:25] neg_lo:[1,0,0] neg_hi:[1,0,0]
	ds_read_b128 v[234:237], v109 offset:9040
	s_waitcnt lgkmcnt(4)
	v_pk_fma_f32 v[10:11], v[142:143], v[40:41], v[10:11] neg_lo:[1,0,0] neg_hi:[1,0,0]
	v_pk_fma_f32 v[16:17], v[146:147], v[40:41], v[16:17] neg_lo:[1,0,0] neg_hi:[1,0,0]
	v_pk_fma_f32 v[20:21], v[150:151], v[40:41], v[20:21] neg_lo:[1,0,0] neg_hi:[1,0,0]
	v_pk_fma_f32 v[24:25], v[154:155], v[40:41], v[24:25] neg_lo:[1,0,0] neg_hi:[1,0,0]
	v_pk_fma_f32 v[10:11], v[144:145], v[44:45], v[10:11] neg_lo:[1,0,0] neg_hi:[1,0,0]
	ds_read_b128 v[142:145], v109 offset:8288
	v_pk_fma_f32 v[16:17], v[148:149], v[44:45], v[16:17] neg_lo:[1,0,0] neg_hi:[1,0,0]
	ds_read_b128 v[146:149], v109 offset:8544
	v_pk_fma_f32 v[20:21], v[152:153], v[44:45], v[20:21] neg_lo:[1,0,0] neg_hi:[1,0,0]
	ds_read_b128 v[150:153], v109 offset:8800
	v_pk_fma_f32 v[24:25], v[156:157], v[44:45], v[24:25] neg_lo:[1,0,0] neg_hi:[1,0,0]
	ds_read_b128 v[154:157], v109 offset:9056
	s_waitcnt lgkmcnt(4)
	v_pk_fma_f32 v[10:11], v[158:159], v[50:51], v[10:11] neg_lo:[1,0,0] neg_hi:[1,0,0]
	v_pk_fma_f32 v[16:17], v[220:221], v[50:51], v[16:17] neg_lo:[1,0,0] neg_hi:[1,0,0]
	v_pk_fma_f32 v[20:21], v[230:231], v[50:51], v[20:21] neg_lo:[1,0,0] neg_hi:[1,0,0]
	v_pk_fma_f32 v[24:25], v[234:235], v[50:51], v[24:25] neg_lo:[1,0,0] neg_hi:[1,0,0]
	v_pk_fma_f32 v[10:11], v[160:161], v[54:55], v[10:11] neg_lo:[1,0,0] neg_hi:[1,0,0]
	ds_read_b128 v[158:161], v109 offset:8304
	v_pk_fma_f32 v[16:17], v[222:223], v[54:55], v[16:17] neg_lo:[1,0,0] neg_hi:[1,0,0]
	ds_read_b128 v[220:223], v109 offset:8560
	v_pk_fma_f32 v[20:21], v[232:233], v[54:55], v[20:21] neg_lo:[1,0,0] neg_hi:[1,0,0]
	ds_read_b128 v[230:233], v109 offset:8816
	v_pk_fma_f32 v[24:25], v[236:237], v[54:55], v[24:25] neg_lo:[1,0,0] neg_hi:[1,0,0]
	ds_read_b128 v[234:237], v109 offset:9072
	s_waitcnt lgkmcnt(4)
; #define LAS __attribute__((address_space(3)))
; __device__ __forceinline__ void gdn_local_unit(LAS unsigned char* lds, const GdnP& P, int unit, const int tid, const int pf) {
;     ...
;         for (int c = 1; c < 64; ++c) { f32x2 sp = (f32x2){sol2[c >> 1][c & 1], 0.f};
; #pragma unroll
;             for (int jb = 0; jb <= (c - 1) / 4; ++jb) { const f32x4 m4 = *(const LAS f32x4*)(Ms + c * 64 + 4 * jb);
;                 sp -= (f32x2){m4.x, m4.y} * sol2[2 * jb]; sp -= (f32x2){m4.z, m4.w} * sol2[2 * jb + 1]; }
;             sol2[c >> 1][c & 1] = sp.x + sp.y; }
	v_pk_fma_f32 v[10:11], v[142:143], v[60:61], v[10:11] neg_lo:[1,0,0] neg_hi:[1,0,0]
	v_pk_fma_f32 v[16:17], v[146:147], v[60:61], v[16:17] neg_lo:[1,0,0] neg_hi:[1,0,0]
	v_pk_fma_f32 v[20:21], v[150:151], v[60:61], v[20:21] neg_lo:[1,0,0] neg_hi:[1,0,0]
	v_pk_fma_f32 v[24:25], v[154:155], v[60:61], v[24:25] neg_lo:[1,0,0] neg_hi:[1,0,0]
	v_pk_fma_f32 v[10:11], v[144:145], v[64:65], v[10:11] neg_lo:[1,0,0] neg_hi:[1,0,0]
	ds_read_b128 v[142:145], v109 offset:9216
	v_pk_fma_f32 v[16:17], v[148:149], v[64:65], v[16:17] neg_lo:[1,0,0] neg_hi:[1,0,0]
	ds_read_b128 v[146:149], v109 offset:9472
	v_pk_fma_f32 v[20:21], v[152:153], v[64:65], v[20:21] neg_lo:[1,0,0] neg_hi:[1,0,0]
	ds_read_b128 v[150:153], v109 offset:9728
	v_pk_fma_f32 v[24:25], v[156:157], v[64:65], v[24:25] neg_lo:[1,0,0] neg_hi:[1,0,0]
	ds_read_b128 v[154:157], v109 offset:9984
	s_waitcnt lgkmcnt(4)
	v_pk_fma_f32 v[10:11], v[158:159], v[70:71], v[10:11] neg_lo:[1,0,0] neg_hi:[1,0,0]
	v_pk_fma_f32 v[16:17], v[220:221], v[70:71], v[16:17] neg_lo:[1,0,0] neg_hi:[1,0,0]
	v_pk_fma_f32 v[20:21], v[230:231], v[70:71], v[20:21] neg_lo:[1,0,0] neg_hi:[1,0,0]
	v_pk_fma_f32 v[24:25], v[234:235], v[70:71], v[24:25] neg_lo:[1,0,0] neg_hi:[1,0,0]
	v_pk_fma_f32 v[10:11], v[160:161], v[112:113], v[10:11] neg_lo:[1,0,0] neg_hi:[1,0,0]
	ds_read_b128 v[158:161], v109 offset:9232
	v_pk_fma_f32 v[16:17], v[222:223], v[112:113], v[16:17] neg_lo:[1,0,0] neg_hi:[1,0,0]
	ds_read_b128 v[220:223], v109 offset:9488
	v_pk_fma_f32 v[20:21], v[232:233], v[112:113], v[20:21] neg_lo:[1,0,0] neg_hi:[1,0,0]
	ds_read_b128 v[230:233], v109 offset:9744
	v_pk_fma_f32 v[24:25], v[236:237], v[112:113], v[24:25] neg_lo:[1,0,0] neg_hi:[1,0,0]
	ds_read_b128 v[234:237], v109 offset:10000
	v_add_f32_e32 v10, v10, v11
	s_waitcnt lgkmcnt(5)
	v_pk_mul_f32 v[28:29], v[142:143], v[0:1] neg_lo:[1,0] neg_hi:[1,0]
	v_pk_mul_f32 v[34:35], v[146:147], v[0:1] neg_lo:[1,0] neg_hi:[1,0]
	v_add_f32_e32 v16, v16, v17
	v_pk_mul_f32 v[38:39], v[150:151], v[0:1] neg_lo:[1,0] neg_hi:[1,0]
	s_waitcnt lgkmcnt(4)
	v_pk_mul_f32 v[42:43], v[154:155], v[0:1] neg_lo:[1,0] neg_hi:[1,0]
	v_add_f32_e32 v20, v20, v21
	v_pk_fma_f32 v[28:29], v[144:145], v[8:9], v[28:29] neg_lo:[1,0,0] neg_hi:[1,0,0]
	ds_read_b128 v[142:145], v109 offset:8576
	v_pk_fma_f32 v[34:35], v[148:149], v[8:9], v[34:35] neg_lo:[1,0,0] neg_hi:[1,0,0]
	ds_read_b128 v[146:149], v109 offset:9248
	v_add_f32_e32 v24, v24, v25
	v_pk_fma_f32 v[38:39], v[152:153], v[8:9], v[38:39] neg_lo:[1,0,0] neg_hi:[1,0,0]
	ds_read_b128 v[150:153], v109 offset:9504
	v_pk_fma_f32 v[42:43], v[156:157], v[8:9], v[42:43] neg_lo:[1,0,0] neg_hi:[1,0,0]
	ds_read_b128 v[154:157], v109 offset:8832
	v_add_f32_e32 v116, v10, v116
	s_waitcnt lgkmcnt(5)
	v_pk_fma_f32 v[28:29], v[158:159], v[14:15], v[28:29] neg_lo:[1,0,0] neg_hi:[1,0,0]
	v_pk_fma_f32 v[34:35], v[220:221], v[14:15], v[34:35] neg_lo:[1,0,0] neg_hi:[1,0,0]
	v_add_f32_e32 v16, v16, v117
	v_pk_fma_f32 v[38:39], v[230:231], v[14:15], v[38:39] neg_lo:[1,0,0] neg_hi:[1,0,0]
	s_waitcnt lgkmcnt(4)
	v_pk_fma_f32 v[42:43], v[234:235], v[14:15], v[42:43] neg_lo:[1,0,0] neg_hi:[1,0,0]
	v_add_f32_e32 v20, v20, v122
	v_pk_fma_f32 v[28:29], v[160:161], v[18:19], v[28:29] neg_lo:[1,0,0] neg_hi:[1,0,0]
	ds_read_b128 v[158:161], v109 offset:9760
	v_pk_fma_f32 v[34:35], v[222:223], v[18:19], v[34:35] neg_lo:[1,0,0] neg_hi:[1,0,0]
	ds_read_b128 v[220:223], v109 offset:10016
	v_add_f32_e32 v24, v24, v123
	v_pk_fma_f32 v[38:39], v[232:233], v[18:19], v[38:39] neg_lo:[1,0,0] neg_hi:[1,0,0]
	ds_read_b128 v[230:233], v109 offset:9088
	v_pk_fma_f32 v[42:43], v[236:237], v[18:19], v[42:43] neg_lo:[1,0,0] neg_hi:[1,0,0]
	ds_read_b128 v[234:237], v109 offset:9264
	s_waitcnt lgkmcnt(4)
	v_fma_f32 v117, -v142, v116, v16
	ds_read_b128 v[142:145], v109 offset:9520
	v_pk_fma_f32 v[28:29], v[146:147], v[22:23], v[28:29] neg_lo:[1,0,0] neg_hi:[1,0,0]
	v_pk_fma_f32 v[34:35], v[150:151], v[22:23], v[34:35] neg_lo:[1,0,0] neg_hi:[1,0,0]
	v_fma_f32 v20, -v154, v116, v20
	s_waitcnt lgkmcnt(2)
	v_pk_fma_f32 v[38:39], v[158:159], v[22:23], v[38:39] neg_lo:[1,0,0] neg_hi:[1,0,0]
	v_pk_fma_f32 v[42:43], v[220:221], v[22:23], v[42:43] neg_lo:[1,0,0] neg_hi:[1,0,0]
	v_fma_f32 v24, -v230, v116, v24
	v_pk_fma_f32 v[28:29], v[148:149], v[26:27], v[28:29] neg_lo:[1,0,0] neg_hi:[1,0,0]
	ds_read_b128 v[146:149], v109 offset:9776
	v_pk_fma_f32 v[34:35], v[152:153], v[26:27], v[34:35] neg_lo:[1,0,0] neg_hi:[1,0,0]
	ds_read_b128 v[150:153], v109 offset:10032
	v_fma_f32 v122, -v155, v117, v20
	ds_read_b128 v[154:157], v109 offset:9280
	v_pk_fma_f32 v[38:39], v[160:161], v[26:27], v[38:39] neg_lo:[1,0,0] neg_hi:[1,0,0]
	ds_read_b128 v[158:161], v109 offset:9536
	v_pk_fma_f32 v[42:43], v[222:223], v[26:27], v[42:43] neg_lo:[1,0,0] neg_hi:[1,0,0]
	ds_read_b128 v[220:223], v109 offset:9792
	v_fma_f32 v24, -v231, v117, v24
	s_waitcnt lgkmcnt(4)
	v_pk_fma_f32 v[28:29], v[234:235], v[30:31], v[28:29] neg_lo:[1,0,0] neg_hi:[1,0,0]
	v_pk_fma_f32 v[34:35], v[142:143], v[30:31], v[34:35] neg_lo:[1,0,0] neg_hi:[1,0,0]
	v_fma_f32 v123, -v232, v122, v24
	ds_read_b128 v[230:233], v109 offset:10048
	v_pk_fma_f32 v[38:39], v[146:147], v[30:31], v[38:39] neg_lo:[1,0,0] neg_hi:[1,0,0]
	s_waitcnt lgkmcnt(4)
	v_pk_fma_f32 v[42:43], v[150:151], v[30:31], v[42:43] neg_lo:[1,0,0] neg_hi:[1,0,0]
	v_pk_fma_f32 v[28:29], v[236:237], v[36:37], v[28:29] neg_lo:[1,0,0] neg_hi:[1,0,0]
	ds_read_b128 v[234:237], v109 offset:9296
	v_pk_fma_f32 v[34:35], v[144:145], v[36:37], v[34:35] neg_lo:[1,0,0] neg_hi:[1,0,0]
	ds_read_b128 v[142:145], v109 offset:9552
	v_pk_fma_f32 v[38:39], v[148:149], v[36:37], v[38:39] neg_lo:[1,0,0] neg_hi:[1,0,0]
	ds_read_b128 v[146:149], v109 offset:9808
	v_pk_fma_f32 v[42:43], v[152:153], v[36:37], v[42:43] neg_lo:[1,0,0] neg_hi:[1,0,0]
	ds_read_b128 v[150:153], v109 offset:10064
	s_waitcnt lgkmcnt(4)
; #define LAS __attribute__((address_space(3)))
; __device__ __forceinline__ void gdn_local_unit(LAS unsigned char* lds, const GdnP& P, int unit, const int tid, const int pf) {
;     ...
;         for (int c = 1; c < 64; ++c) { f32x2 sp = (f32x2){sol2[c >> 1][c & 1], 0.f};
; #pragma unroll
;             for (int jb = 0; jb <= (c - 1) / 4; ++jb) { const f32x4 m4 = *(const LAS f32x4*)(Ms + c * 64 + 4 * jb);
;                 sp -= (f32x2){m4.x, m4.y} * sol2[2 * jb]; sp -= (f32x2){m4.z, m4.w} * sol2[2 * jb + 1]; }
;             sol2[c >> 1][c & 1] = sp.x + sp.y; }
	v_pk_fma_f32 v[28:29], v[154:155], v[40:41], v[28:29] neg_lo:[1,0,0] neg_hi:[1,0,0]
	v_pk_fma_f32 v[34:35], v[158:159], v[40:41], v[34:35] neg_lo:[1,0,0] neg_hi:[1,0,0]
	v_pk_fma_f32 v[38:39], v[220:221], v[40:41], v[38:39] neg_lo:[1,0,0] neg_hi:[1,0,0]
	v_pk_fma_f32 v[42:43], v[230:231], v[40:41], v[42:43] neg_lo:[1,0,0] neg_hi:[1,0,0]
	v_pk_fma_f32 v[28:29], v[156:157], v[44:45], v[28:29] neg_lo:[1,0,0] neg_hi:[1,0,0]
	ds_read_b128 v[154:157], v109 offset:9312
	v_pk_fma_f32 v[34:35], v[160:161], v[44:45], v[34:35] neg_lo:[1,0,0] neg_hi:[1,0,0]
	ds_read_b128 v[158:161], v109 offset:9568
	v_pk_fma_f32 v[38:39], v[222:223], v[44:45], v[38:39] neg_lo:[1,0,0] neg_hi:[1,0,0]
	ds_read_b128 v[220:223], v109 offset:9824
	v_pk_fma_f32 v[42:43], v[232:233], v[44:45], v[42:43] neg_lo:[1,0,0] neg_hi:[1,0,0]
	ds_read_b128 v[230:233], v109 offset:10080
	s_waitcnt lgkmcnt(4)
	v_pk_fma_f32 v[28:29], v[234:235], v[50:51], v[28:29] neg_lo:[1,0,0] neg_hi:[1,0,0]
	v_pk_fma_f32 v[34:35], v[142:143], v[50:51], v[34:35] neg_lo:[1,0,0] neg_hi:[1,0,0]
	v_pk_fma_f32 v[38:39], v[146:147], v[50:51], v[38:39] neg_lo:[1,0,0] neg_hi:[1,0,0]
	v_pk_fma_f32 v[42:43], v[150:151], v[50:51], v[42:43] neg_lo:[1,0,0] neg_hi:[1,0,0]
	v_pk_fma_f32 v[28:29], v[236:237], v[54:55], v[28:29] neg_lo:[1,0,0] neg_hi:[1,0,0]
	ds_read_b128 v[234:237], v109 offset:9328
	v_pk_fma_f32 v[34:35], v[144:145], v[54:55], v[34:35] neg_lo:[1,0,0] neg_hi:[1,0,0]
	ds_read_b128 v[142:145], v109 offset:9584
	v_pk_fma_f32 v[38:39], v[148:149], v[54:55], v[38:39] neg_lo:[1,0,0] neg_hi:[1,0,0]
	ds_read_b128 v[146:149], v109 offset:9840
	v_pk_fma_f32 v[42:43], v[152:153], v[54:55], v[42:43] neg_lo:[1,0,0] neg_hi:[1,0,0]
	ds_read_b128 v[150:153], v109 offset:10096
	s_waitcnt lgkmcnt(4)
	v_pk_fma_f32 v[28:29], v[154:155], v[60:61], v[28:29] neg_lo:[1,0,0] neg_hi:[1,0,0]
	v_pk_fma_f32 v[34:35], v[158:159], v[60:61], v[34:35] neg_lo:[1,0,0] neg_hi:[1,0,0]
	v_pk_fma_f32 v[38:39], v[220:221], v[60:61], v[38:39] neg_lo:[1,0,0] neg_hi:[1,0,0]
	v_pk_fma_f32 v[42:43], v[230:231], v[60:61], v[42:43] neg_lo:[1,0,0] neg_hi:[1,0,0]
	v_pk_fma_f32 v[28:29], v[156:157], v[64:65], v[28:29] neg_lo:[1,0,0] neg_hi:[1,0,0]
	ds_read_b128 v[154:157], v109 offset:9344
	v_pk_fma_f32 v[34:35], v[160:161], v[64:65], v[34:35] neg_lo:[1,0,0] neg_hi:[1,0,0]
	ds_read_b128 v[158:161], v109 offset:9600
	v_pk_fma_f32 v[38:39], v[222:223], v[64:65], v[38:39] neg_lo:[1,0,0] neg_hi:[1,0,0]
	ds_read_b128 v[220:223], v109 offset:9856
	v_pk_fma_f32 v[42:43], v[232:233], v[64:65], v[42:43] neg_lo:[1,0,0] neg_hi:[1,0,0]
	ds_read_b128 v[230:233], v109 offset:10112
	s_waitcnt lgkmcnt(4)
	v_pk_fma_f32 v[28:29], v[234:235], v[70:71], v[28:29] neg_lo:[1,0,0] neg_hi:[1,0,0]
	v_pk_fma_f32 v[34:35], v[142:143], v[70:71], v[34:35] neg_lo:[1,0,0] neg_hi:[1,0,0]
	v_pk_fma_f32 v[38:39], v[146:147], v[70:71], v[38:39] neg_lo:[1,0,0] neg_hi:[1,0,0]
	v_pk_fma_f32 v[42:43], v[150:151], v[70:71], v[42:43] neg_lo:[1,0,0] neg_hi:[1,0,0]
	v_pk_fma_f32 v[28:29], v[236:237], v[112:113], v[28:29] neg_lo:[1,0,0] neg_hi:[1,0,0]
	ds_read_b128 v[234:237], v109 offset:10240
	v_pk_fma_f32 v[34:35], v[144:145], v[112:113], v[34:35] neg_lo:[1,0,0] neg_hi:[1,0,0]
	ds_read_b128 v[142:145], v109 offset:10496
	v_pk_fma_f32 v[38:39], v[148:149], v[112:113], v[38:39] neg_lo:[1,0,0] neg_hi:[1,0,0]
	ds_read_b128 v[146:149], v109 offset:10752
	v_pk_fma_f32 v[42:43], v[152:153], v[112:113], v[42:43] neg_lo:[1,0,0] neg_hi:[1,0,0]
	ds_read_b128 v[150:153], v109 offset:11008
	s_waitcnt lgkmcnt(4)
	v_pk_fma_f32 v[28:29], v[154:155], v[116:117], v[28:29] neg_lo:[1,0,0] neg_hi:[1,0,0]
	v_pk_fma_f32 v[34:35], v[158:159], v[116:117], v[34:35] neg_lo:[1,0,0] neg_hi:[1,0,0]
	v_pk_fma_f32 v[38:39], v[220:221], v[116:117], v[38:39] neg_lo:[1,0,0] neg_hi:[1,0,0]
	v_pk_fma_f32 v[42:43], v[230:231], v[116:117], v[42:43] neg_lo:[1,0,0] neg_hi:[1,0,0]
	v_pk_fma_f32 v[28:29], v[156:157], v[122:123], v[28:29] neg_lo:[1,0,0] neg_hi:[1,0,0]
	ds_read_b128 v[154:157], v109 offset:10256
	v_pk_fma_f32 v[34:35], v[160:161], v[122:123], v[34:35] neg_lo:[1,0,0] neg_hi:[1,0,0]
	ds_read_b128 v[158:161], v109 offset:10512
	v_pk_fma_f32 v[38:39], v[222:223], v[122:123], v[38:39] neg_lo:[1,0,0] neg_hi:[1,0,0]
	ds_read_b128 v[220:223], v109 offset:10768
	v_pk_fma_f32 v[42:43], v[232:233], v[122:123], v[42:43] neg_lo:[1,0,0] neg_hi:[1,0,0]
	ds_read_b128 v[230:233], v109 offset:11024
	v_add_f32_e32 v28, v28, v29
	s_waitcnt lgkmcnt(5)
	v_pk_mul_f32 v[10:11], v[234:235], v[0:1] neg_lo:[1,0] neg_hi:[1,0]
	v_pk_mul_f32 v[16:17], v[142:143], v[0:1] neg_lo:[1,0] neg_hi:[1,0]
	v_add_f32_e32 v34, v34, v35
	v_pk_mul_f32 v[20:21], v[146:147], v[0:1] neg_lo:[1,0] neg_hi:[1,0]
	s_waitcnt lgkmcnt(4)
	v_pk_mul_f32 v[24:25], v[150:151], v[0:1] neg_lo:[1,0] neg_hi:[1,0]
	v_add_f32_e32 v38, v38, v39
	v_pk_fma_f32 v[10:11], v[236:237], v[8:9], v[10:11] neg_lo:[1,0,0] neg_hi:[1,0,0]
	ds_read_b128 v[234:237], v109 offset:9616
	v_pk_fma_f32 v[16:17], v[144:145], v[8:9], v[16:17] neg_lo:[1,0,0] neg_hi:[1,0,0]
	ds_read_b128 v[142:145], v109 offset:10272
	v_add_f32_e32 v42, v42, v43
	v_pk_fma_f32 v[20:21], v[148:149], v[8:9], v[20:21] neg_lo:[1,0,0] neg_hi:[1,0,0]
	ds_read_b128 v[146:149], v109 offset:10528
	v_pk_fma_f32 v[24:25], v[152:153], v[8:9], v[24:25] neg_lo:[1,0,0] neg_hi:[1,0,0]
	ds_read_b128 v[150:153], v109 offset:9872
	v_add_f32_e32 v128, v28, v128
	s_waitcnt lgkmcnt(5)
	v_pk_fma_f32 v[10:11], v[154:155], v[14:15], v[10:11] neg_lo:[1,0,0] neg_hi:[1,0,0]
	v_pk_fma_f32 v[16:17], v[158:159], v[14:15], v[16:17] neg_lo:[1,0,0] neg_hi:[1,0,0]
	v_add_f32_e32 v34, v34, v129
	v_pk_fma_f32 v[20:21], v[220:221], v[14:15], v[20:21] neg_lo:[1,0,0] neg_hi:[1,0,0]
	s_waitcnt lgkmcnt(4)
; #define LAS __attribute__((address_space(3)))
; __device__ __forceinline__ void gdn_local_unit(LAS unsigned char* lds, const GdnP& P, int unit, const int tid, const int pf) {
;     ...
;         for (int c = 1; c < 64; ++c) { f32x2 sp = (f32x2){sol2[c >> 1][c & 1], 0.f};
; #pragma unroll
;             for (int jb = 0; jb <= (c - 1) / 4; ++jb) { const f32x4 m4 = *(const LAS f32x4*)(Ms + c * 64 + 4 * jb);
;                 sp -= (f32x2){m4.x, m4.y} * sol2[2 * jb]; sp -= (f32x2){m4.z, m4.w} * sol2[2 * jb + 1]; }
;             sol2[c >> 1][c & 1] = sp.x + sp.y; }
	v_pk_fma_f32 v[24:25], v[230:231], v[14:15], v[24:25] neg_lo:[1,0,0] neg_hi:[1,0,0]
	v_add_f32_e32 v38, v38, v134
	v_pk_fma_f32 v[10:11], v[156:157], v[18:19], v[10:11] neg_lo:[1,0,0] neg_hi:[1,0,0]
	ds_read_b128 v[154:157], v109 offset:10784
	v_pk_fma_f32 v[16:17], v[160:161], v[18:19], v[16:17] neg_lo:[1,0,0] neg_hi:[1,0,0]
	ds_read_b128 v[158:161], v109 offset:11040
	v_add_f32_e32 v42, v42, v135
	v_pk_fma_f32 v[20:21], v[222:223], v[18:19], v[20:21] neg_lo:[1,0,0] neg_hi:[1,0,0]
	ds_read_b128 v[220:223], v109 offset:10128
	v_pk_fma_f32 v[24:25], v[232:233], v[18:19], v[24:25] neg_lo:[1,0,0] neg_hi:[1,0,0]
	ds_read_b128 v[230:233], v109 offset:10288
	s_waitcnt lgkmcnt(4)
	v_fma_f32 v129, -v234, v128, v34
	ds_read_b128 v[234:237], v109 offset:10544
	v_pk_fma_f32 v[10:11], v[142:143], v[22:23], v[10:11] neg_lo:[1,0,0] neg_hi:[1,0,0]
	v_pk_fma_f32 v[16:17], v[146:147], v[22:23], v[16:17] neg_lo:[1,0,0] neg_hi:[1,0,0]
	v_fma_f32 v38, -v150, v128, v38
	s_waitcnt lgkmcnt(2)
	v_pk_fma_f32 v[20:21], v[154:155], v[22:23], v[20:21] neg_lo:[1,0,0] neg_hi:[1,0,0]
	v_pk_fma_f32 v[24:25], v[158:159], v[22:23], v[24:25] neg_lo:[1,0,0] neg_hi:[1,0,0]
	v_fma_f32 v42, -v220, v128, v42
	v_pk_fma_f32 v[10:11], v[144:145], v[26:27], v[10:11] neg_lo:[1,0,0] neg_hi:[1,0,0]
	ds_read_b128 v[142:145], v109 offset:10800
	v_pk_fma_f32 v[16:17], v[148:149], v[26:27], v[16:17] neg_lo:[1,0,0] neg_hi:[1,0,0]
	ds_read_b128 v[146:149], v109 offset:11056
	v_fma_f32 v134, -v151, v129, v38
	ds_read_b128 v[150:153], v109 offset:10304
	v_pk_fma_f32 v[20:21], v[156:157], v[26:27], v[20:21] neg_lo:[1,0,0] neg_hi:[1,0,0]
	ds_read_b128 v[154:157], v109 offset:10560
	v_pk_fma_f32 v[24:25], v[160:161], v[26:27], v[24:25] neg_lo:[1,0,0] neg_hi:[1,0,0]
	ds_read_b128 v[158:161], v109 offset:10816
	v_fma_f32 v42, -v221, v129, v42
	s_waitcnt lgkmcnt(4)
	v_pk_fma_f32 v[10:11], v[230:231], v[30:31], v[10:11] neg_lo:[1,0,0] neg_hi:[1,0,0]
	v_pk_fma_f32 v[16:17], v[234:235], v[30:31], v[16:17] neg_lo:[1,0,0] neg_hi:[1,0,0]
	v_fma_f32 v135, -v222, v134, v42
	ds_read_b128 v[220:223], v109 offset:11072
	v_pk_fma_f32 v[20:21], v[142:143], v[30:31], v[20:21] neg_lo:[1,0,0] neg_hi:[1,0,0]
	s_waitcnt lgkmcnt(4)
	v_pk_fma_f32 v[24:25], v[146:147], v[30:31], v[24:25] neg_lo:[1,0,0] neg_hi:[1,0,0]
	v_pk_fma_f32 v[10:11], v[232:233], v[36:37], v[10:11] neg_lo:[1,0,0] neg_hi:[1,0,0]
	ds_read_b128 v[230:233], v109 offset:10320
	v_pk_fma_f32 v[16:17], v[236:237], v[36:37], v[16:17] neg_lo:[1,0,0] neg_hi:[1,0,0]
	ds_read_b128 v[234:237], v109 offset:10576
	v_pk_fma_f32 v[20:21], v[144:145], v[36:37], v[20:21] neg_lo:[1,0,0] neg_hi:[1,0,0]
	ds_read_b128 v[142:145], v109 offset:10832
	v_pk_fma_f32 v[24:25], v[148:149], v[36:37], v[24:25] neg_lo:[1,0,0] neg_hi:[1,0,0]
	ds_read_b128 v[146:149], v109 offset:11088
	s_waitcnt lgkmcnt(4)
	v_pk_fma_f32 v[10:11], v[150:151], v[40:41], v[10:11] neg_lo:[1,0,0] neg_hi:[1,0,0]
	v_pk_fma_f32 v[16:17], v[154:155], v[40:41], v[16:17] neg_lo:[1,0,0] neg_hi:[1,0,0]
	v_pk_fma_f32 v[20:21], v[158:159], v[40:41], v[20:21] neg_lo:[1,0,0] neg_hi:[1,0,0]
	v_pk_fma_f32 v[24:25], v[220:221], v[40:41], v[24:25] neg_lo:[1,0,0] neg_hi:[1,0,0]
	v_pk_fma_f32 v[10:11], v[152:153], v[44:45], v[10:11] neg_lo:[1,0,0] neg_hi:[1,0,0]
	ds_read_b128 v[150:153], v109 offset:10336
	v_pk_fma_f32 v[16:17], v[156:157], v[44:45], v[16:17] neg_lo:[1,0,0] neg_hi:[1,0,0]
	ds_read_b128 v[154:157], v109 offset:10592
	v_pk_fma_f32 v[20:21], v[160:161], v[44:45], v[20:21] neg_lo:[1,0,0] neg_hi:[1,0,0]
	ds_read_b128 v[158:161], v109 offset:10848
	v_pk_fma_f32 v[24:25], v[222:223], v[44:45], v[24:25] neg_lo:[1,0,0] neg_hi:[1,0,0]
	ds_read_b128 v[220:223], v109 offset:11104
	s_waitcnt lgkmcnt(4)
	v_pk_fma_f32 v[10:11], v[230:231], v[50:51], v[10:11] neg_lo:[1,0,0] neg_hi:[1,0,0]
	v_pk_fma_f32 v[16:17], v[234:235], v[50:51], v[16:17] neg_lo:[1,0,0] neg_hi:[1,0,0]
	v_pk_fma_f32 v[20:21], v[142:143], v[50:51], v[20:21] neg_lo:[1,0,0] neg_hi:[1,0,0]
	v_pk_fma_f32 v[24:25], v[146:147], v[50:51], v[24:25] neg_lo:[1,0,0] neg_hi:[1,0,0]
	v_pk_fma_f32 v[10:11], v[232:233], v[54:55], v[10:11] neg_lo:[1,0,0] neg_hi:[1,0,0]
	ds_read_b128 v[230:233], v109 offset:10352
	v_pk_fma_f32 v[16:17], v[236:237], v[54:55], v[16:17] neg_lo:[1,0,0] neg_hi:[1,0,0]
	ds_read_b128 v[234:237], v109 offset:10608
	v_pk_fma_f32 v[20:21], v[144:145], v[54:55], v[20:21] neg_lo:[1,0,0] neg_hi:[1,0,0]
	ds_read_b128 v[142:145], v109 offset:10864
	v_pk_fma_f32 v[24:25], v[148:149], v[54:55], v[24:25] neg_lo:[1,0,0] neg_hi:[1,0,0]
	ds_read_b128 v[146:149], v109 offset:11120
	s_waitcnt lgkmcnt(4)
	v_pk_fma_f32 v[10:11], v[150:151], v[60:61], v[10:11] neg_lo:[1,0,0] neg_hi:[1,0,0]
	v_pk_fma_f32 v[16:17], v[154:155], v[60:61], v[16:17] neg_lo:[1,0,0] neg_hi:[1,0,0]
	v_pk_fma_f32 v[20:21], v[158:159], v[60:61], v[20:21] neg_lo:[1,0,0] neg_hi:[1,0,0]
	v_pk_fma_f32 v[24:25], v[220:221], v[60:61], v[24:25] neg_lo:[1,0,0] neg_hi:[1,0,0]
	v_pk_fma_f32 v[10:11], v[152:153], v[64:65], v[10:11] neg_lo:[1,0,0] neg_hi:[1,0,0]
	ds_read_b128 v[150:153], v109 offset:10368
	v_pk_fma_f32 v[16:17], v[156:157], v[64:65], v[16:17] neg_lo:[1,0,0] neg_hi:[1,0,0]
	ds_read_b128 v[154:157], v109 offset:10624
	v_pk_fma_f32 v[20:21], v[160:161], v[64:65], v[20:21] neg_lo:[1,0,0] neg_hi:[1,0,0]
	ds_read_b128 v[158:161], v109 offset:10880
	v_pk_fma_f32 v[24:25], v[222:223], v[64:65], v[24:25] neg_lo:[1,0,0] neg_hi:[1,0,0]
	ds_read_b128 v[220:223], v109 offset:11136
	s_waitcnt lgkmcnt(4)
; #define LAS __attribute__((address_space(3)))
; __device__ __forceinline__ void gdn_local_unit(LAS unsigned char* lds, const GdnP& P, int unit, const int tid, const int pf) {
;     ...
;         for (int c = 1; c < 64; ++c) { f32x2 sp = (f32x2){sol2[c >> 1][c & 1], 0.f};
; #pragma unroll
;             for (int jb = 0; jb <= (c - 1) / 4; ++jb) { const f32x4 m4 = *(const LAS f32x4*)(Ms + c * 64 + 4 * jb);
;                 sp -= (f32x2){m4.x, m4.y} * sol2[2 * jb]; sp -= (f32x2){m4.z, m4.w} * sol2[2 * jb + 1]; }
;             sol2[c >> 1][c & 1] = sp.x + sp.y; }
	v_pk_fma_f32 v[10:11], v[230:231], v[70:71], v[10:11] neg_lo:[1,0,0] neg_hi:[1,0,0]
	v_pk_fma_f32 v[16:17], v[234:235], v[70:71], v[16:17] neg_lo:[1,0,0] neg_hi:[1,0,0]
	v_pk_fma_f32 v[20:21], v[142:143], v[70:71], v[20:21] neg_lo:[1,0,0] neg_hi:[1,0,0]
	v_pk_fma_f32 v[24:25], v[146:147], v[70:71], v[24:25] neg_lo:[1,0,0] neg_hi:[1,0,0]
	v_pk_fma_f32 v[10:11], v[232:233], v[112:113], v[10:11] neg_lo:[1,0,0] neg_hi:[1,0,0]
	ds_read_b128 v[230:233], v109 offset:10384
	v_pk_fma_f32 v[16:17], v[236:237], v[112:113], v[16:17] neg_lo:[1,0,0] neg_hi:[1,0,0]
	ds_read_b128 v[234:237], v109 offset:10640
	v_pk_fma_f32 v[20:21], v[144:145], v[112:113], v[20:21] neg_lo:[1,0,0] neg_hi:[1,0,0]
	ds_read_b128 v[142:145], v109 offset:10896
	v_pk_fma_f32 v[24:25], v[148:149], v[112:113], v[24:25] neg_lo:[1,0,0] neg_hi:[1,0,0]
	ds_read_b128 v[146:149], v109 offset:11152
	s_waitcnt lgkmcnt(4)
	v_pk_fma_f32 v[10:11], v[150:151], v[116:117], v[10:11] neg_lo:[1,0,0] neg_hi:[1,0,0]
	v_pk_fma_f32 v[16:17], v[154:155], v[116:117], v[16:17] neg_lo:[1,0,0] neg_hi:[1,0,0]
	v_pk_fma_f32 v[20:21], v[158:159], v[116:117], v[20:21] neg_lo:[1,0,0] neg_hi:[1,0,0]
	v_pk_fma_f32 v[24:25], v[220:221], v[116:117], v[24:25] neg_lo:[1,0,0] neg_hi:[1,0,0]
	v_pk_fma_f32 v[10:11], v[152:153], v[122:123], v[10:11] neg_lo:[1,0,0] neg_hi:[1,0,0]
	ds_read_b128 v[150:153], v109 offset:11264
	v_pk_fma_f32 v[16:17], v[156:157], v[122:123], v[16:17] neg_lo:[1,0,0] neg_hi:[1,0,0]
	ds_read_b128 v[154:157], v109 offset:11520
	v_pk_fma_f32 v[20:21], v[160:161], v[122:123], v[20:21] neg_lo:[1,0,0] neg_hi:[1,0,0]
	ds_read_b128 v[158:161], v109 offset:11776
	v_pk_fma_f32 v[24:25], v[222:223], v[122:123], v[24:25] neg_lo:[1,0,0] neg_hi:[1,0,0]
	ds_read_b128 v[220:223], v109 offset:12032
	s_waitcnt lgkmcnt(4)
	v_pk_fma_f32 v[10:11], v[230:231], v[128:129], v[10:11] neg_lo:[1,0,0] neg_hi:[1,0,0]
	v_pk_fma_f32 v[16:17], v[234:235], v[128:129], v[16:17] neg_lo:[1,0,0] neg_hi:[1,0,0]
	v_pk_fma_f32 v[20:21], v[142:143], v[128:129], v[20:21] neg_lo:[1,0,0] neg_hi:[1,0,0]
	v_pk_fma_f32 v[24:25], v[146:147], v[128:129], v[24:25] neg_lo:[1,0,0] neg_hi:[1,0,0]
	v_pk_fma_f32 v[10:11], v[232:233], v[134:135], v[10:11] neg_lo:[1,0,0] neg_hi:[1,0,0]
	ds_read_b128 v[230:233], v109 offset:11280
	v_pk_fma_f32 v[16:17], v[236:237], v[134:135], v[16:17] neg_lo:[1,0,0] neg_hi:[1,0,0]
	ds_read_b128 v[234:237], v109 offset:11536
	v_pk_fma_f32 v[20:21], v[144:145], v[134:135], v[20:21] neg_lo:[1,0,0] neg_hi:[1,0,0]
	ds_read_b128 v[142:145], v109 offset:11792
	v_pk_fma_f32 v[24:25], v[148:149], v[134:135], v[24:25] neg_lo:[1,0,0] neg_hi:[1,0,0]
	ds_read_b128 v[146:149], v109 offset:12048
	v_add_f32_e32 v10, v10, v11
	s_waitcnt lgkmcnt(5)
	v_pk_mul_f32 v[28:29], v[150:151], v[0:1] neg_lo:[1,0] neg_hi:[1,0]
	v_pk_mul_f32 v[34:35], v[154:155], v[0:1] neg_lo:[1,0] neg_hi:[1,0]
	v_add_f32_e32 v16, v16, v17
	v_pk_mul_f32 v[38:39], v[158:159], v[0:1] neg_lo:[1,0] neg_hi:[1,0]
	s_waitcnt lgkmcnt(4)
	v_pk_mul_f32 v[42:43], v[220:221], v[0:1] neg_lo:[1,0] neg_hi:[1,0]
	v_add_f32_e32 v20, v20, v21
	v_pk_fma_f32 v[28:29], v[152:153], v[8:9], v[28:29] neg_lo:[1,0,0] neg_hi:[1,0,0]
	ds_read_b128 v[150:153], v109 offset:10656
	v_pk_fma_f32 v[34:35], v[156:157], v[8:9], v[34:35] neg_lo:[1,0,0] neg_hi:[1,0,0]
	ds_read_b128 v[154:157], v109 offset:11296
	v_add_f32_e32 v24, v24, v25
	v_pk_fma_f32 v[38:39], v[160:161], v[8:9], v[38:39] neg_lo:[1,0,0] neg_hi:[1,0,0]
	ds_read_b128 v[158:161], v109 offset:11552
	v_pk_fma_f32 v[42:43], v[222:223], v[8:9], v[42:43] neg_lo:[1,0,0] neg_hi:[1,0,0]
	ds_read_b128 v[220:223], v109 offset:10912
	v_add_f32_e32 v140, v10, v140
	s_waitcnt lgkmcnt(5)
	v_pk_fma_f32 v[28:29], v[230:231], v[14:15], v[28:29] neg_lo:[1,0,0] neg_hi:[1,0,0]
	v_pk_fma_f32 v[34:35], v[234:235], v[14:15], v[34:35] neg_lo:[1,0,0] neg_hi:[1,0,0]
	v_add_f32_e32 v16, v16, v141
	v_pk_fma_f32 v[38:39], v[142:143], v[14:15], v[38:39] neg_lo:[1,0,0] neg_hi:[1,0,0]
	s_waitcnt lgkmcnt(4)
	v_pk_fma_f32 v[42:43], v[146:147], v[14:15], v[42:43] neg_lo:[1,0,0] neg_hi:[1,0,0]
	v_add_f32_e32 v20, v20, v138
	v_pk_fma_f32 v[28:29], v[232:233], v[18:19], v[28:29] neg_lo:[1,0,0] neg_hi:[1,0,0]
	ds_read_b128 v[230:233], v109 offset:11808
	v_pk_fma_f32 v[34:35], v[236:237], v[18:19], v[34:35] neg_lo:[1,0,0] neg_hi:[1,0,0]
	ds_read_b128 v[234:237], v109 offset:12064
	v_add_f32_e32 v24, v24, v139
	v_pk_fma_f32 v[38:39], v[144:145], v[18:19], v[38:39] neg_lo:[1,0,0] neg_hi:[1,0,0]
	ds_read_b128 v[142:145], v109 offset:11168
	v_pk_fma_f32 v[42:43], v[148:149], v[18:19], v[42:43] neg_lo:[1,0,0] neg_hi:[1,0,0]
	ds_read_b128 v[146:149], v109 offset:11312
	s_waitcnt lgkmcnt(4)
	v_fma_f32 v141, -v150, v140, v16
	ds_read_b128 v[150:153], v109 offset:11568
	v_pk_fma_f32 v[28:29], v[154:155], v[22:23], v[28:29] neg_lo:[1,0,0] neg_hi:[1,0,0]
	v_pk_fma_f32 v[34:35], v[158:159], v[22:23], v[34:35] neg_lo:[1,0,0] neg_hi:[1,0,0]
	v_fma_f32 v20, -v220, v140, v20
	s_waitcnt lgkmcnt(2)
	v_pk_fma_f32 v[38:39], v[230:231], v[22:23], v[38:39] neg_lo:[1,0,0] neg_hi:[1,0,0]
	v_pk_fma_f32 v[42:43], v[234:235], v[22:23], v[42:43] neg_lo:[1,0,0] neg_hi:[1,0,0]
	v_fma_f32 v24, -v142, v140, v24
	v_pk_fma_f32 v[28:29], v[156:157], v[26:27], v[28:29] neg_lo:[1,0,0] neg_hi:[1,0,0]
	ds_read_b128 v[154:157], v109 offset:11824
	v_pk_fma_f32 v[34:35], v[160:161], v[26:27], v[34:35] neg_lo:[1,0,0] neg_hi:[1,0,0]
	ds_read_b128 v[158:161], v109 offset:12080
	v_fma_f32 v138, -v221, v141, v20
	ds_read_b128 v[220:223], v109 offset:11328
	v_pk_fma_f32 v[38:39], v[232:233], v[26:27], v[38:39] neg_lo:[1,0,0] neg_hi:[1,0,0]
	ds_read_b128 v[230:233], v109 offset:11584
	v_pk_fma_f32 v[42:43], v[236:237], v[26:27], v[42:43] neg_lo:[1,0,0] neg_hi:[1,0,0]
	ds_read_b128 v[234:237], v109 offset:11840
	v_fma_f32 v24, -v143, v141, v24
	s_waitcnt lgkmcnt(4)
; #define LAS __attribute__((address_space(3)))
; __device__ __forceinline__ void gdn_local_unit(LAS unsigned char* lds, const GdnP& P, int unit, const int tid, const int pf) {
;     ...
;         for (int c = 1; c < 64; ++c) { f32x2 sp = (f32x2){sol2[c >> 1][c & 1], 0.f};
; #pragma unroll
;             for (int jb = 0; jb <= (c - 1) / 4; ++jb) { const f32x4 m4 = *(const LAS f32x4*)(Ms + c * 64 + 4 * jb);
;                 sp -= (f32x2){m4.x, m4.y} * sol2[2 * jb]; sp -= (f32x2){m4.z, m4.w} * sol2[2 * jb + 1]; }
;             sol2[c >> 1][c & 1] = sp.x + sp.y; }
	v_pk_fma_f32 v[28:29], v[146:147], v[30:31], v[28:29] neg_lo:[1,0,0] neg_hi:[1,0,0]
	v_pk_fma_f32 v[34:35], v[150:151], v[30:31], v[34:35] neg_lo:[1,0,0] neg_hi:[1,0,0]
	v_fma_f32 v139, -v144, v138, v24
	ds_read_b128 v[142:145], v109 offset:12096
	v_pk_fma_f32 v[38:39], v[154:155], v[30:31], v[38:39] neg_lo:[1,0,0] neg_hi:[1,0,0]
	s_waitcnt lgkmcnt(4)
	v_pk_fma_f32 v[42:43], v[158:159], v[30:31], v[42:43] neg_lo:[1,0,0] neg_hi:[1,0,0]
	v_pk_fma_f32 v[28:29], v[148:149], v[36:37], v[28:29] neg_lo:[1,0,0] neg_hi:[1,0,0]
	ds_read_b128 v[146:149], v109 offset:11344
	v_pk_fma_f32 v[34:35], v[152:153], v[36:37], v[34:35] neg_lo:[1,0,0] neg_hi:[1,0,0]
	ds_read_b128 v[150:153], v109 offset:11600
	v_pk_fma_f32 v[38:39], v[156:157], v[36:37], v[38:39] neg_lo:[1,0,0] neg_hi:[1,0,0]
	ds_read_b128 v[154:157], v109 offset:11856
	v_pk_fma_f32 v[42:43], v[160:161], v[36:37], v[42:43] neg_lo:[1,0,0] neg_hi:[1,0,0]
	ds_read_b128 v[158:161], v109 offset:12112
	s_waitcnt lgkmcnt(4)
	v_pk_fma_f32 v[28:29], v[220:221], v[40:41], v[28:29] neg_lo:[1,0,0] neg_hi:[1,0,0]
	v_pk_fma_f32 v[34:35], v[230:231], v[40:41], v[34:35] neg_lo:[1,0,0] neg_hi:[1,0,0]
	v_pk_fma_f32 v[38:39], v[234:235], v[40:41], v[38:39] neg_lo:[1,0,0] neg_hi:[1,0,0]
	v_pk_fma_f32 v[42:43], v[142:143], v[40:41], v[42:43] neg_lo:[1,0,0] neg_hi:[1,0,0]
	v_pk_fma_f32 v[28:29], v[222:223], v[44:45], v[28:29] neg_lo:[1,0,0] neg_hi:[1,0,0]
	ds_read_b128 v[220:223], v109 offset:11360
	v_pk_fma_f32 v[34:35], v[232:233], v[44:45], v[34:35] neg_lo:[1,0,0] neg_hi:[1,0,0]
	ds_read_b128 v[230:233], v109 offset:11616
	v_pk_fma_f32 v[38:39], v[236:237], v[44:45], v[38:39] neg_lo:[1,0,0] neg_hi:[1,0,0]
	ds_read_b128 v[234:237], v109 offset:11872
	v_pk_fma_f32 v[42:43], v[144:145], v[44:45], v[42:43] neg_lo:[1,0,0] neg_hi:[1,0,0]
	ds_read_b128 v[142:145], v109 offset:12128
	s_waitcnt lgkmcnt(4)
	v_pk_fma_f32 v[28:29], v[146:147], v[50:51], v[28:29] neg_lo:[1,0,0] neg_hi:[1,0,0]
	v_pk_fma_f32 v[34:35], v[150:151], v[50:51], v[34:35] neg_lo:[1,0,0] neg_hi:[1,0,0]
	v_pk_fma_f32 v[38:39], v[154:155], v[50:51], v[38:39] neg_lo:[1,0,0] neg_hi:[1,0,0]
	v_pk_fma_f32 v[42:43], v[158:159], v[50:51], v[42:43] neg_lo:[1,0,0] neg_hi:[1,0,0]
	v_pk_fma_f32 v[28:29], v[148:149], v[54:55], v[28:29] neg_lo:[1,0,0] neg_hi:[1,0,0]
	ds_read_b128 v[146:149], v109 offset:11376
	v_pk_fma_f32 v[34:35], v[152:153], v[54:55], v[34:35] neg_lo:[1,0,0] neg_hi:[1,0,0]
	ds_read_b128 v[150:153], v109 offset:11632
	v_pk_fma_f32 v[38:39], v[156:157], v[54:55], v[38:39] neg_lo:[1,0,0] neg_hi:[1,0,0]
	ds_read_b128 v[154:157], v109 offset:11888
	v_pk_fma_f32 v[42:43], v[160:161], v[54:55], v[42:43] neg_lo:[1,0,0] neg_hi:[1,0,0]
	ds_read_b128 v[158:161], v109 offset:12144
	s_waitcnt lgkmcnt(4)
	v_pk_fma_f32 v[28:29], v[220:221], v[60:61], v[28:29] neg_lo:[1,0,0] neg_hi:[1,0,0]
	v_pk_fma_f32 v[34:35], v[230:231], v[60:61], v[34:35] neg_lo:[1,0,0] neg_hi:[1,0,0]
	v_pk_fma_f32 v[38:39], v[234:235], v[60:61], v[38:39] neg_lo:[1,0,0] neg_hi:[1,0,0]
	v_pk_fma_f32 v[42:43], v[142:143], v[60:61], v[42:43] neg_lo:[1,0,0] neg_hi:[1,0,0]
	v_pk_fma_f32 v[28:29], v[222:223], v[64:65], v[28:29] neg_lo:[1,0,0] neg_hi:[1,0,0]
	ds_read_b128 v[220:223], v109 offset:11392
	v_pk_fma_f32 v[34:35], v[232:233], v[64:65], v[34:35] neg_lo:[1,0,0] neg_hi:[1,0,0]
	ds_read_b128 v[230:233], v109 offset:11648
	v_pk_fma_f32 v[38:39], v[236:237], v[64:65], v[38:39] neg_lo:[1,0,0] neg_hi:[1,0,0]
	ds_read_b128 v[234:237], v109 offset:11904
	v_pk_fma_f32 v[42:43], v[144:145], v[64:65], v[42:43] neg_lo:[1,0,0] neg_hi:[1,0,0]
	ds_read_b128 v[142:145], v109 offset:12160
	s_waitcnt lgkmcnt(4)
	v_pk_fma_f32 v[28:29], v[146:147], v[70:71], v[28:29] neg_lo:[1,0,0] neg_hi:[1,0,0]
	v_pk_fma_f32 v[34:35], v[150:151], v[70:71], v[34:35] neg_lo:[1,0,0] neg_hi:[1,0,0]
	v_pk_fma_f32 v[38:39], v[154:155], v[70:71], v[38:39] neg_lo:[1,0,0] neg_hi:[1,0,0]
	v_pk_fma_f32 v[42:43], v[158:159], v[70:71], v[42:43] neg_lo:[1,0,0] neg_hi:[1,0,0]
	v_pk_fma_f32 v[28:29], v[148:149], v[112:113], v[28:29] neg_lo:[1,0,0] neg_hi:[1,0,0]
	ds_read_b128 v[146:149], v109 offset:11408
	v_pk_fma_f32 v[34:35], v[152:153], v[112:113], v[34:35] neg_lo:[1,0,0] neg_hi:[1,0,0]
	ds_read_b128 v[150:153], v109 offset:11664
	v_pk_fma_f32 v[38:39], v[156:157], v[112:113], v[38:39] neg_lo:[1,0,0] neg_hi:[1,0,0]
	ds_read_b128 v[154:157], v109 offset:11920
	v_pk_fma_f32 v[42:43], v[160:161], v[112:113], v[42:43] neg_lo:[1,0,0] neg_hi:[1,0,0]
	ds_read_b128 v[158:161], v109 offset:12176
	s_waitcnt lgkmcnt(4)
	v_pk_fma_f32 v[28:29], v[220:221], v[116:117], v[28:29] neg_lo:[1,0,0] neg_hi:[1,0,0]
	v_pk_fma_f32 v[34:35], v[230:231], v[116:117], v[34:35] neg_lo:[1,0,0] neg_hi:[1,0,0]
	v_pk_fma_f32 v[38:39], v[234:235], v[116:117], v[38:39] neg_lo:[1,0,0] neg_hi:[1,0,0]
	v_pk_fma_f32 v[42:43], v[142:143], v[116:117], v[42:43] neg_lo:[1,0,0] neg_hi:[1,0,0]
	v_pk_fma_f32 v[28:29], v[222:223], v[122:123], v[28:29] neg_lo:[1,0,0] neg_hi:[1,0,0]
	ds_read_b128 v[220:223], v109 offset:11424
	v_pk_fma_f32 v[34:35], v[232:233], v[122:123], v[34:35] neg_lo:[1,0,0] neg_hi:[1,0,0]
	ds_read_b128 v[230:233], v109 offset:11680
	v_pk_fma_f32 v[38:39], v[236:237], v[122:123], v[38:39] neg_lo:[1,0,0] neg_hi:[1,0,0]
	ds_read_b128 v[234:237], v109 offset:11936
	v_pk_fma_f32 v[42:43], v[144:145], v[122:123], v[42:43] neg_lo:[1,0,0] neg_hi:[1,0,0]
	ds_read_b128 v[142:145], v109 offset:12192
	s_waitcnt lgkmcnt(4)
; #define LAS __attribute__((address_space(3)))
; __device__ __forceinline__ void gdn_local_unit(LAS unsigned char* lds, const GdnP& P, int unit, const int tid, const int pf) {
;     ...
;         for (int c = 1; c < 64; ++c) { f32x2 sp = (f32x2){sol2[c >> 1][c & 1], 0.f};
; #pragma unroll
;             for (int jb = 0; jb <= (c - 1) / 4; ++jb) { const f32x4 m4 = *(const LAS f32x4*)(Ms + c * 64 + 4 * jb);
;                 sp -= (f32x2){m4.x, m4.y} * sol2[2 * jb]; sp -= (f32x2){m4.z, m4.w} * sol2[2 * jb + 1]; }
;             sol2[c >> 1][c & 1] = sp.x + sp.y; }
	v_pk_fma_f32 v[28:29], v[146:147], v[128:129], v[28:29] neg_lo:[1,0,0] neg_hi:[1,0,0]
	v_pk_fma_f32 v[34:35], v[150:151], v[128:129], v[34:35] neg_lo:[1,0,0] neg_hi:[1,0,0]
	v_pk_fma_f32 v[38:39], v[154:155], v[128:129], v[38:39] neg_lo:[1,0,0] neg_hi:[1,0,0]
	v_pk_fma_f32 v[42:43], v[158:159], v[128:129], v[42:43] neg_lo:[1,0,0] neg_hi:[1,0,0]
	v_pk_fma_f32 v[28:29], v[148:149], v[134:135], v[28:29] neg_lo:[1,0,0] neg_hi:[1,0,0]
	ds_read_b128 v[146:149], v109 offset:12288
	v_pk_fma_f32 v[34:35], v[152:153], v[134:135], v[34:35] neg_lo:[1,0,0] neg_hi:[1,0,0]
	ds_read_b128 v[150:153], v109 offset:12544
	v_pk_fma_f32 v[38:39], v[156:157], v[134:135], v[38:39] neg_lo:[1,0,0] neg_hi:[1,0,0]
	ds_read_b128 v[154:157], v109 offset:12800
	v_pk_fma_f32 v[42:43], v[160:161], v[134:135], v[42:43] neg_lo:[1,0,0] neg_hi:[1,0,0]
	ds_read_b128 v[158:161], v109 offset:13056
	s_waitcnt lgkmcnt(4)
	v_pk_fma_f32 v[28:29], v[220:221], v[140:141], v[28:29] neg_lo:[1,0,0] neg_hi:[1,0,0]
	v_pk_fma_f32 v[34:35], v[230:231], v[140:141], v[34:35] neg_lo:[1,0,0] neg_hi:[1,0,0]
	v_pk_fma_f32 v[38:39], v[234:235], v[140:141], v[38:39] neg_lo:[1,0,0] neg_hi:[1,0,0]
	v_pk_fma_f32 v[42:43], v[142:143], v[140:141], v[42:43] neg_lo:[1,0,0] neg_hi:[1,0,0]
	v_pk_fma_f32 v[28:29], v[222:223], v[138:139], v[28:29] neg_lo:[1,0,0] neg_hi:[1,0,0]
	ds_read_b128 v[220:223], v109 offset:12304
	v_pk_fma_f32 v[34:35], v[232:233], v[138:139], v[34:35] neg_lo:[1,0,0] neg_hi:[1,0,0]
	ds_read_b128 v[230:233], v109 offset:12560
	v_pk_fma_f32 v[38:39], v[236:237], v[138:139], v[38:39] neg_lo:[1,0,0] neg_hi:[1,0,0]
	ds_read_b128 v[234:237], v109 offset:12816
	v_pk_fma_f32 v[42:43], v[144:145], v[138:139], v[42:43] neg_lo:[1,0,0] neg_hi:[1,0,0]
	ds_read_b128 v[142:145], v109 offset:13072
	v_add_f32_e32 v28, v28, v29
	s_waitcnt lgkmcnt(5)
	v_pk_mul_f32 v[10:11], v[146:147], v[0:1] neg_lo:[1,0] neg_hi:[1,0]
	v_pk_mul_f32 v[16:17], v[150:151], v[0:1] neg_lo:[1,0] neg_hi:[1,0]
	v_add_f32_e32 v34, v34, v35
	v_pk_mul_f32 v[20:21], v[154:155], v[0:1] neg_lo:[1,0] neg_hi:[1,0]
	s_waitcnt lgkmcnt(4)
	v_pk_mul_f32 v[24:25], v[158:159], v[0:1] neg_lo:[1,0] neg_hi:[1,0]
	v_add_f32_e32 v38, v38, v39
	v_pk_fma_f32 v[10:11], v[148:149], v[8:9], v[10:11] neg_lo:[1,0,0] neg_hi:[1,0,0]
	ds_read_b128 v[146:149], v109 offset:11696
	v_pk_fma_f32 v[16:17], v[152:153], v[8:9], v[16:17] neg_lo:[1,0,0] neg_hi:[1,0,0]
	ds_read_b128 v[150:153], v109 offset:12320
	v_add_f32_e32 v42, v42, v43
	v_pk_fma_f32 v[20:21], v[156:157], v[8:9], v[20:21] neg_lo:[1,0,0] neg_hi:[1,0,0]
	ds_read_b128 v[154:157], v109 offset:12576
	v_pk_fma_f32 v[24:25], v[160:161], v[8:9], v[24:25] neg_lo:[1,0,0] neg_hi:[1,0,0]
	ds_read_b128 v[158:161], v109 offset:11952
	v_add_f32_e32 v132, v28, v132
	s_waitcnt lgkmcnt(5)
	v_pk_fma_f32 v[10:11], v[220:221], v[14:15], v[10:11] neg_lo:[1,0,0] neg_hi:[1,0,0]
	v_pk_fma_f32 v[16:17], v[230:231], v[14:15], v[16:17] neg_lo:[1,0,0] neg_hi:[1,0,0]
	v_add_f32_e32 v34, v34, v133
	v_pk_fma_f32 v[20:21], v[234:235], v[14:15], v[20:21] neg_lo:[1,0,0] neg_hi:[1,0,0]
	s_waitcnt lgkmcnt(4)
	v_pk_fma_f32 v[24:25], v[142:143], v[14:15], v[24:25] neg_lo:[1,0,0] neg_hi:[1,0,0]
	v_add_f32_e32 v38, v38, v124
	v_pk_fma_f32 v[10:11], v[222:223], v[18:19], v[10:11] neg_lo:[1,0,0] neg_hi:[1,0,0]
	ds_read_b128 v[220:223], v109 offset:12832
	v_pk_fma_f32 v[16:17], v[232:233], v[18:19], v[16:17] neg_lo:[1,0,0] neg_hi:[1,0,0]
	ds_read_b128 v[230:233], v109 offset:13088
	v_add_f32_e32 v42, v42, v125
	v_pk_fma_f32 v[20:21], v[236:237], v[18:19], v[20:21] neg_lo:[1,0,0] neg_hi:[1,0,0]
	ds_read_b128 v[234:237], v109 offset:12208
	v_pk_fma_f32 v[24:25], v[144:145], v[18:19], v[24:25] neg_lo:[1,0,0] neg_hi:[1,0,0]
	ds_read_b128 v[142:145], v109 offset:12336
	s_waitcnt lgkmcnt(4)
	v_fma_f32 v133, -v146, v132, v34
	ds_read_b128 v[146:149], v109 offset:12592
	v_pk_fma_f32 v[10:11], v[150:151], v[22:23], v[10:11] neg_lo:[1,0,0] neg_hi:[1,0,0]
	v_pk_fma_f32 v[16:17], v[154:155], v[22:23], v[16:17] neg_lo:[1,0,0] neg_hi:[1,0,0]
	v_fma_f32 v38, -v158, v132, v38
	s_waitcnt lgkmcnt(2)
	v_pk_fma_f32 v[20:21], v[220:221], v[22:23], v[20:21] neg_lo:[1,0,0] neg_hi:[1,0,0]
	v_pk_fma_f32 v[24:25], v[230:231], v[22:23], v[24:25] neg_lo:[1,0,0] neg_hi:[1,0,0]
	v_fma_f32 v42, -v234, v132, v42
	v_pk_fma_f32 v[10:11], v[152:153], v[26:27], v[10:11] neg_lo:[1,0,0] neg_hi:[1,0,0]
	ds_read_b128 v[150:153], v109 offset:12848
	v_pk_fma_f32 v[16:17], v[156:157], v[26:27], v[16:17] neg_lo:[1,0,0] neg_hi:[1,0,0]
	ds_read_b128 v[154:157], v109 offset:13104
	v_fma_f32 v124, -v159, v133, v38
	ds_read_b128 v[158:161], v109 offset:12352
	v_pk_fma_f32 v[20:21], v[222:223], v[26:27], v[20:21] neg_lo:[1,0,0] neg_hi:[1,0,0]
	ds_read_b128 v[220:223], v109 offset:12608
	v_pk_fma_f32 v[24:25], v[232:233], v[26:27], v[24:25] neg_lo:[1,0,0] neg_hi:[1,0,0]
	ds_read_b128 v[230:233], v109 offset:12864
	v_fma_f32 v42, -v235, v133, v42
	s_waitcnt lgkmcnt(4)
	v_pk_fma_f32 v[10:11], v[142:143], v[30:31], v[10:11] neg_lo:[1,0,0] neg_hi:[1,0,0]
	v_pk_fma_f32 v[16:17], v[146:147], v[30:31], v[16:17] neg_lo:[1,0,0] neg_hi:[1,0,0]
	v_fma_f32 v125, -v236, v124, v42
	ds_read_b128 v[234:237], v109 offset:13120
	v_pk_fma_f32 v[20:21], v[150:151], v[30:31], v[20:21] neg_lo:[1,0,0] neg_hi:[1,0,0]
	s_waitcnt lgkmcnt(4)
	v_pk_fma_f32 v[24:25], v[154:155], v[30:31], v[24:25] neg_lo:[1,0,0] neg_hi:[1,0,0]
	v_pk_fma_f32 v[10:11], v[144:145], v[36:37], v[10:11] neg_lo:[1,0,0] neg_hi:[1,0,0]
	ds_read_b128 v[142:145], v109 offset:12368
	v_pk_fma_f32 v[16:17], v[148:149], v[36:37], v[16:17] neg_lo:[1,0,0] neg_hi:[1,0,0]
	ds_read_b128 v[146:149], v109 offset:12624
	v_pk_fma_f32 v[20:21], v[152:153], v[36:37], v[20:21] neg_lo:[1,0,0] neg_hi:[1,0,0]
	ds_read_b128 v[150:153], v109 offset:12880
	v_pk_fma_f32 v[24:25], v[156:157], v[36:37], v[24:25] neg_lo:[1,0,0] neg_hi:[1,0,0]
	ds_read_b128 v[154:157], v109 offset:13136
	s_waitcnt lgkmcnt(4)
; #define LAS __attribute__((address_space(3)))
; __device__ __forceinline__ void gdn_local_unit(LAS unsigned char* lds, const GdnP& P, int unit, const int tid, const int pf) {
;     ...
;         for (int c = 1; c < 64; ++c) { f32x2 sp = (f32x2){sol2[c >> 1][c & 1], 0.f};
; #pragma unroll
;             for (int jb = 0; jb <= (c - 1) / 4; ++jb) { const f32x4 m4 = *(const LAS f32x4*)(Ms + c * 64 + 4 * jb);
;                 sp -= (f32x2){m4.x, m4.y} * sol2[2 * jb]; sp -= (f32x2){m4.z, m4.w} * sol2[2 * jb + 1]; }
;             sol2[c >> 1][c & 1] = sp.x + sp.y; }
	v_pk_fma_f32 v[10:11], v[158:159], v[40:41], v[10:11] neg_lo:[1,0,0] neg_hi:[1,0,0]
	v_pk_fma_f32 v[16:17], v[220:221], v[40:41], v[16:17] neg_lo:[1,0,0] neg_hi:[1,0,0]
	v_pk_fma_f32 v[20:21], v[230:231], v[40:41], v[20:21] neg_lo:[1,0,0] neg_hi:[1,0,0]
	v_pk_fma_f32 v[24:25], v[234:235], v[40:41], v[24:25] neg_lo:[1,0,0] neg_hi:[1,0,0]
	v_pk_fma_f32 v[10:11], v[160:161], v[44:45], v[10:11] neg_lo:[1,0,0] neg_hi:[1,0,0]
	ds_read_b128 v[158:161], v109 offset:12384
	v_pk_fma_f32 v[16:17], v[222:223], v[44:45], v[16:17] neg_lo:[1,0,0] neg_hi:[1,0,0]
	ds_read_b128 v[220:223], v109 offset:12640
	v_pk_fma_f32 v[20:21], v[232:233], v[44:45], v[20:21] neg_lo:[1,0,0] neg_hi:[1,0,0]
	ds_read_b128 v[230:233], v109 offset:12896
	v_pk_fma_f32 v[24:25], v[236:237], v[44:45], v[24:25] neg_lo:[1,0,0] neg_hi:[1,0,0]
	ds_read_b128 v[234:237], v109 offset:13152
	s_waitcnt lgkmcnt(4)
	v_pk_fma_f32 v[10:11], v[142:143], v[50:51], v[10:11] neg_lo:[1,0,0] neg_hi:[1,0,0]
	v_pk_fma_f32 v[16:17], v[146:147], v[50:51], v[16:17] neg_lo:[1,0,0] neg_hi:[1,0,0]
	v_pk_fma_f32 v[20:21], v[150:151], v[50:51], v[20:21] neg_lo:[1,0,0] neg_hi:[1,0,0]
	v_pk_fma_f32 v[24:25], v[154:155], v[50:51], v[24:25] neg_lo:[1,0,0] neg_hi:[1,0,0]
	v_pk_fma_f32 v[10:11], v[144:145], v[54:55], v[10:11] neg_lo:[1,0,0] neg_hi:[1,0,0]
	ds_read_b128 v[142:145], v109 offset:12400
	v_pk_fma_f32 v[16:17], v[148:149], v[54:55], v[16:17] neg_lo:[1,0,0] neg_hi:[1,0,0]
	ds_read_b128 v[146:149], v109 offset:12656
	v_pk_fma_f32 v[20:21], v[152:153], v[54:55], v[20:21] neg_lo:[1,0,0] neg_hi:[1,0,0]
	ds_read_b128 v[150:153], v109 offset:12912
	v_pk_fma_f32 v[24:25], v[156:157], v[54:55], v[24:25] neg_lo:[1,0,0] neg_hi:[1,0,0]
	ds_read_b128 v[154:157], v109 offset:13168
	s_waitcnt lgkmcnt(4)
	v_pk_fma_f32 v[10:11], v[158:159], v[60:61], v[10:11] neg_lo:[1,0,0] neg_hi:[1,0,0]
	v_pk_fma_f32 v[16:17], v[220:221], v[60:61], v[16:17] neg_lo:[1,0,0] neg_hi:[1,0,0]
	v_pk_fma_f32 v[20:21], v[230:231], v[60:61], v[20:21] neg_lo:[1,0,0] neg_hi:[1,0,0]
	v_pk_fma_f32 v[24:25], v[234:235], v[60:61], v[24:25] neg_lo:[1,0,0] neg_hi:[1,0,0]
	v_pk_fma_f32 v[10:11], v[160:161], v[64:65], v[10:11] neg_lo:[1,0,0] neg_hi:[1,0,0]
	ds_read_b128 v[158:161], v109 offset:12416
	v_pk_fma_f32 v[16:17], v[222:223], v[64:65], v[16:17] neg_lo:[1,0,0] neg_hi:[1,0,0]
	ds_read_b128 v[220:223], v109 offset:12672
	v_pk_fma_f32 v[20:21], v[232:233], v[64:65], v[20:21] neg_lo:[1,0,0] neg_hi:[1,0,0]
	ds_read_b128 v[230:233], v109 offset:12928
	v_pk_fma_f32 v[24:25], v[236:237], v[64:65], v[24:25] neg_lo:[1,0,0] neg_hi:[1,0,0]
	ds_read_b128 v[234:237], v109 offset:13184
	s_waitcnt lgkmcnt(4)
	v_pk_fma_f32 v[10:11], v[142:143], v[70:71], v[10:11] neg_lo:[1,0,0] neg_hi:[1,0,0]
	v_pk_fma_f32 v[16:17], v[146:147], v[70:71], v[16:17] neg_lo:[1,0,0] neg_hi:[1,0,0]
	v_pk_fma_f32 v[20:21], v[150:151], v[70:71], v[20:21] neg_lo:[1,0,0] neg_hi:[1,0,0]
	v_pk_fma_f32 v[24:25], v[154:155], v[70:71], v[24:25] neg_lo:[1,0,0] neg_hi:[1,0,0]
	v_pk_fma_f32 v[10:11], v[144:145], v[112:113], v[10:11] neg_lo:[1,0,0] neg_hi:[1,0,0]
	ds_read_b128 v[142:145], v109 offset:12432
	v_pk_fma_f32 v[16:17], v[148:149], v[112:113], v[16:17] neg_lo:[1,0,0] neg_hi:[1,0,0]
	ds_read_b128 v[146:149], v109 offset:12688
	v_pk_fma_f32 v[20:21], v[152:153], v[112:113], v[20:21] neg_lo:[1,0,0] neg_hi:[1,0,0]
	ds_read_b128 v[150:153], v109 offset:12944
	v_pk_fma_f32 v[24:25], v[156:157], v[112:113], v[24:25] neg_lo:[1,0,0] neg_hi:[1,0,0]
	ds_read_b128 v[154:157], v109 offset:13200
	s_waitcnt lgkmcnt(4)
	v_pk_fma_f32 v[10:11], v[158:159], v[116:117], v[10:11] neg_lo:[1,0,0] neg_hi:[1,0,0]
	v_pk_fma_f32 v[16:17], v[220:221], v[116:117], v[16:17] neg_lo:[1,0,0] neg_hi:[1,0,0]
	v_pk_fma_f32 v[20:21], v[230:231], v[116:117], v[20:21] neg_lo:[1,0,0] neg_hi:[1,0,0]
	v_pk_fma_f32 v[24:25], v[234:235], v[116:117], v[24:25] neg_lo:[1,0,0] neg_hi:[1,0,0]
	v_pk_fma_f32 v[10:11], v[160:161], v[122:123], v[10:11] neg_lo:[1,0,0] neg_hi:[1,0,0]
	ds_read_b128 v[158:161], v109 offset:12448
	v_pk_fma_f32 v[16:17], v[222:223], v[122:123], v[16:17] neg_lo:[1,0,0] neg_hi:[1,0,0]
	ds_read_b128 v[220:223], v109 offset:12704
	v_pk_fma_f32 v[20:21], v[232:233], v[122:123], v[20:21] neg_lo:[1,0,0] neg_hi:[1,0,0]
	ds_read_b128 v[230:233], v109 offset:12960
	v_pk_fma_f32 v[24:25], v[236:237], v[122:123], v[24:25] neg_lo:[1,0,0] neg_hi:[1,0,0]
	ds_read_b128 v[234:237], v109 offset:13216
	s_waitcnt lgkmcnt(4)
	v_pk_fma_f32 v[10:11], v[142:143], v[128:129], v[10:11] neg_lo:[1,0,0] neg_hi:[1,0,0]
	v_pk_fma_f32 v[16:17], v[146:147], v[128:129], v[16:17] neg_lo:[1,0,0] neg_hi:[1,0,0]
	v_pk_fma_f32 v[20:21], v[150:151], v[128:129], v[20:21] neg_lo:[1,0,0] neg_hi:[1,0,0]
	v_pk_fma_f32 v[24:25], v[154:155], v[128:129], v[24:25] neg_lo:[1,0,0] neg_hi:[1,0,0]
	v_pk_fma_f32 v[10:11], v[144:145], v[134:135], v[10:11] neg_lo:[1,0,0] neg_hi:[1,0,0]
	ds_read_b128 v[142:145], v109 offset:12464
	v_pk_fma_f32 v[16:17], v[148:149], v[134:135], v[16:17] neg_lo:[1,0,0] neg_hi:[1,0,0]
	ds_read_b128 v[146:149], v109 offset:12720
	v_pk_fma_f32 v[20:21], v[152:153], v[134:135], v[20:21] neg_lo:[1,0,0] neg_hi:[1,0,0]
	ds_read_b128 v[150:153], v109 offset:12976
	v_pk_fma_f32 v[24:25], v[156:157], v[134:135], v[24:25] neg_lo:[1,0,0] neg_hi:[1,0,0]
	ds_read_b128 v[154:157], v109 offset:13232
	s_waitcnt lgkmcnt(4)
; #define LAS __attribute__((address_space(3)))
; __device__ __forceinline__ void gdn_local_unit(LAS unsigned char* lds, const GdnP& P, int unit, const int tid, const int pf) {
;     ...
;         for (int c = 1; c < 64; ++c) { f32x2 sp = (f32x2){sol2[c >> 1][c & 1], 0.f};
; #pragma unroll
;             for (int jb = 0; jb <= (c - 1) / 4; ++jb) { const f32x4 m4 = *(const LAS f32x4*)(Ms + c * 64 + 4 * jb);
;                 sp -= (f32x2){m4.x, m4.y} * sol2[2 * jb]; sp -= (f32x2){m4.z, m4.w} * sol2[2 * jb + 1]; }
;             sol2[c >> 1][c & 1] = sp.x + sp.y; }
	v_pk_fma_f32 v[10:11], v[158:159], v[140:141], v[10:11] neg_lo:[1,0,0] neg_hi:[1,0,0]
	v_pk_fma_f32 v[16:17], v[220:221], v[140:141], v[16:17] neg_lo:[1,0,0] neg_hi:[1,0,0]
	v_pk_fma_f32 v[20:21], v[230:231], v[140:141], v[20:21] neg_lo:[1,0,0] neg_hi:[1,0,0]
	v_pk_fma_f32 v[24:25], v[234:235], v[140:141], v[24:25] neg_lo:[1,0,0] neg_hi:[1,0,0]
	v_pk_fma_f32 v[10:11], v[160:161], v[138:139], v[10:11] neg_lo:[1,0,0] neg_hi:[1,0,0]
	ds_read_b128 v[158:161], v109 offset:13312
	v_pk_fma_f32 v[16:17], v[222:223], v[138:139], v[16:17] neg_lo:[1,0,0] neg_hi:[1,0,0]
	ds_read_b128 v[220:223], v109 offset:13568
	v_pk_fma_f32 v[20:21], v[232:233], v[138:139], v[20:21] neg_lo:[1,0,0] neg_hi:[1,0,0]
	ds_read_b128 v[230:233], v109 offset:13824
	v_pk_fma_f32 v[24:25], v[236:237], v[138:139], v[24:25] neg_lo:[1,0,0] neg_hi:[1,0,0]
	ds_read_b128 v[234:237], v109 offset:14080
	s_waitcnt lgkmcnt(4)
	v_pk_fma_f32 v[10:11], v[142:143], v[132:133], v[10:11] neg_lo:[1,0,0] neg_hi:[1,0,0]
	v_pk_fma_f32 v[16:17], v[146:147], v[132:133], v[16:17] neg_lo:[1,0,0] neg_hi:[1,0,0]
	v_pk_fma_f32 v[20:21], v[150:151], v[132:133], v[20:21] neg_lo:[1,0,0] neg_hi:[1,0,0]
	v_pk_fma_f32 v[24:25], v[154:155], v[132:133], v[24:25] neg_lo:[1,0,0] neg_hi:[1,0,0]
	v_pk_fma_f32 v[10:11], v[144:145], v[124:125], v[10:11] neg_lo:[1,0,0] neg_hi:[1,0,0]
	ds_read_b128 v[142:145], v109 offset:13328
	v_pk_fma_f32 v[16:17], v[148:149], v[124:125], v[16:17] neg_lo:[1,0,0] neg_hi:[1,0,0]
	ds_read_b128 v[146:149], v109 offset:13584
	v_pk_fma_f32 v[20:21], v[152:153], v[124:125], v[20:21] neg_lo:[1,0,0] neg_hi:[1,0,0]
	ds_read_b128 v[150:153], v109 offset:13840
	v_pk_fma_f32 v[24:25], v[156:157], v[124:125], v[24:25] neg_lo:[1,0,0] neg_hi:[1,0,0]
	ds_read_b128 v[154:157], v109 offset:14096
	v_add_f32_e32 v10, v10, v11
	s_waitcnt lgkmcnt(5)
	v_pk_mul_f32 v[28:29], v[158:159], v[0:1] neg_lo:[1,0] neg_hi:[1,0]
	v_pk_mul_f32 v[34:35], v[220:221], v[0:1] neg_lo:[1,0] neg_hi:[1,0]
	v_add_f32_e32 v16, v16, v17
	v_pk_mul_f32 v[38:39], v[230:231], v[0:1] neg_lo:[1,0] neg_hi:[1,0]
	s_waitcnt lgkmcnt(4)
	v_pk_mul_f32 v[42:43], v[234:235], v[0:1] neg_lo:[1,0] neg_hi:[1,0]
	v_add_f32_e32 v20, v20, v21
	v_pk_fma_f32 v[28:29], v[160:161], v[8:9], v[28:29] neg_lo:[1,0,0] neg_hi:[1,0,0]
	ds_read_b128 v[158:161], v109 offset:12736
	v_pk_fma_f32 v[34:35], v[222:223], v[8:9], v[34:35] neg_lo:[1,0,0] neg_hi:[1,0,0]
	ds_read_b128 v[220:223], v109 offset:13344
	v_add_f32_e32 v24, v24, v25
	v_pk_fma_f32 v[38:39], v[232:233], v[8:9], v[38:39] neg_lo:[1,0,0] neg_hi:[1,0,0]
	ds_read_b128 v[230:233], v109 offset:13600
	v_pk_fma_f32 v[42:43], v[236:237], v[8:9], v[42:43] neg_lo:[1,0,0] neg_hi:[1,0,0]
	ds_read_b128 v[234:237], v109 offset:12992
	v_add_f32_e32 v118, v10, v118
	s_waitcnt lgkmcnt(5)
	v_pk_fma_f32 v[28:29], v[142:143], v[14:15], v[28:29] neg_lo:[1,0,0] neg_hi:[1,0,0]
	v_pk_fma_f32 v[34:35], v[146:147], v[14:15], v[34:35] neg_lo:[1,0,0] neg_hi:[1,0,0]
	v_add_f32_e32 v16, v16, v119
	v_pk_fma_f32 v[38:39], v[150:151], v[14:15], v[38:39] neg_lo:[1,0,0] neg_hi:[1,0,0]
	s_waitcnt lgkmcnt(4)
	v_pk_fma_f32 v[42:43], v[154:155], v[14:15], v[42:43] neg_lo:[1,0,0] neg_hi:[1,0,0]
	v_add_f32_e32 v20, v20, v74
	v_pk_fma_f32 v[28:29], v[144:145], v[18:19], v[28:29] neg_lo:[1,0,0] neg_hi:[1,0,0]
	ds_read_b128 v[142:145], v109 offset:13856
	v_pk_fma_f32 v[34:35], v[148:149], v[18:19], v[34:35] neg_lo:[1,0,0] neg_hi:[1,0,0]
	ds_read_b128 v[146:149], v109 offset:14112
	v_add_f32_e32 v24, v24, v75
	v_pk_fma_f32 v[38:39], v[152:153], v[18:19], v[38:39] neg_lo:[1,0,0] neg_hi:[1,0,0]
	ds_read_b128 v[150:153], v109 offset:13248
	v_pk_fma_f32 v[42:43], v[156:157], v[18:19], v[42:43] neg_lo:[1,0,0] neg_hi:[1,0,0]
	ds_read_b128 v[154:157], v109 offset:13360
	s_waitcnt lgkmcnt(4)
	v_fma_f32 v119, -v158, v118, v16
	ds_read_b128 v[158:161], v109 offset:13616
	v_pk_fma_f32 v[28:29], v[220:221], v[22:23], v[28:29] neg_lo:[1,0,0] neg_hi:[1,0,0]
	v_pk_fma_f32 v[34:35], v[230:231], v[22:23], v[34:35] neg_lo:[1,0,0] neg_hi:[1,0,0]
	v_fma_f32 v20, -v234, v118, v20
	s_waitcnt lgkmcnt(2)
	v_pk_fma_f32 v[38:39], v[142:143], v[22:23], v[38:39] neg_lo:[1,0,0] neg_hi:[1,0,0]
	v_pk_fma_f32 v[42:43], v[146:147], v[22:23], v[42:43] neg_lo:[1,0,0] neg_hi:[1,0,0]
	v_fma_f32 v24, -v150, v118, v24
	v_pk_fma_f32 v[28:29], v[222:223], v[26:27], v[28:29] neg_lo:[1,0,0] neg_hi:[1,0,0]
	ds_read_b128 v[220:223], v109 offset:13872
	v_pk_fma_f32 v[34:35], v[232:233], v[26:27], v[34:35] neg_lo:[1,0,0] neg_hi:[1,0,0]
	ds_read_b128 v[230:233], v109 offset:14128
	v_fma_f32 v74, -v235, v119, v20
	ds_read_b128 v[234:237], v109 offset:13376
	v_pk_fma_f32 v[38:39], v[144:145], v[26:27], v[38:39] neg_lo:[1,0,0] neg_hi:[1,0,0]
	ds_read_b128 v[142:145], v109 offset:13632
	v_pk_fma_f32 v[42:43], v[148:149], v[26:27], v[42:43] neg_lo:[1,0,0] neg_hi:[1,0,0]
	ds_read_b128 v[146:149], v109 offset:13888
	v_fma_f32 v24, -v151, v119, v24
	s_waitcnt lgkmcnt(4)
	v_pk_fma_f32 v[28:29], v[154:155], v[30:31], v[28:29] neg_lo:[1,0,0] neg_hi:[1,0,0]
	v_pk_fma_f32 v[34:35], v[158:159], v[30:31], v[34:35] neg_lo:[1,0,0] neg_hi:[1,0,0]
	v_fma_f32 v75, -v152, v74, v24
	ds_read_b128 v[150:153], v109 offset:14144
	v_pk_fma_f32 v[38:39], v[220:221], v[30:31], v[38:39] neg_lo:[1,0,0] neg_hi:[1,0,0]
	s_waitcnt lgkmcnt(4)
	v_pk_fma_f32 v[42:43], v[230:231], v[30:31], v[42:43] neg_lo:[1,0,0] neg_hi:[1,0,0]
	v_pk_fma_f32 v[28:29], v[156:157], v[36:37], v[28:29] neg_lo:[1,0,0] neg_hi:[1,0,0]
	ds_read_b128 v[154:157], v109 offset:13392
	v_pk_fma_f32 v[34:35], v[160:161], v[36:37], v[34:35] neg_lo:[1,0,0] neg_hi:[1,0,0]
	ds_read_b128 v[158:161], v109 offset:13648
	v_pk_fma_f32 v[38:39], v[222:223], v[36:37], v[38:39] neg_lo:[1,0,0] neg_hi:[1,0,0]
	ds_read_b128 v[220:223], v109 offset:13904
	v_pk_fma_f32 v[42:43], v[232:233], v[36:37], v[42:43] neg_lo:[1,0,0] neg_hi:[1,0,0]
	ds_read_b128 v[230:233], v109 offset:14160
	s_waitcnt lgkmcnt(4)
; #define LAS __attribute__((address_space(3)))
; __device__ __forceinline__ void gdn_local_unit(LAS unsigned char* lds, const GdnP& P, int unit, const int tid, const int pf) {
;     ...
;         for (int c = 1; c < 64; ++c) { f32x2 sp = (f32x2){sol2[c >> 1][c & 1], 0.f};
; #pragma unroll
;             for (int jb = 0; jb <= (c - 1) / 4; ++jb) { const f32x4 m4 = *(const LAS f32x4*)(Ms + c * 64 + 4 * jb);
;                 sp -= (f32x2){m4.x, m4.y} * sol2[2 * jb]; sp -= (f32x2){m4.z, m4.w} * sol2[2 * jb + 1]; }
;             sol2[c >> 1][c & 1] = sp.x + sp.y; }
	v_pk_fma_f32 v[28:29], v[234:235], v[40:41], v[28:29] neg_lo:[1,0,0] neg_hi:[1,0,0]
	v_pk_fma_f32 v[34:35], v[142:143], v[40:41], v[34:35] neg_lo:[1,0,0] neg_hi:[1,0,0]
	v_pk_fma_f32 v[38:39], v[146:147], v[40:41], v[38:39] neg_lo:[1,0,0] neg_hi:[1,0,0]
	v_pk_fma_f32 v[42:43], v[150:151], v[40:41], v[42:43] neg_lo:[1,0,0] neg_hi:[1,0,0]
	v_pk_fma_f32 v[28:29], v[236:237], v[44:45], v[28:29] neg_lo:[1,0,0] neg_hi:[1,0,0]
	ds_read_b128 v[234:237], v109 offset:13408
	v_pk_fma_f32 v[34:35], v[144:145], v[44:45], v[34:35] neg_lo:[1,0,0] neg_hi:[1,0,0]
	ds_read_b128 v[142:145], v109 offset:13664
	v_pk_fma_f32 v[38:39], v[148:149], v[44:45], v[38:39] neg_lo:[1,0,0] neg_hi:[1,0,0]
	ds_read_b128 v[146:149], v109 offset:13920
	v_pk_fma_f32 v[42:43], v[152:153], v[44:45], v[42:43] neg_lo:[1,0,0] neg_hi:[1,0,0]
	ds_read_b128 v[150:153], v109 offset:14176
	s_waitcnt lgkmcnt(4)
	v_pk_fma_f32 v[28:29], v[154:155], v[50:51], v[28:29] neg_lo:[1,0,0] neg_hi:[1,0,0]
	v_pk_fma_f32 v[34:35], v[158:159], v[50:51], v[34:35] neg_lo:[1,0,0] neg_hi:[1,0,0]
	v_pk_fma_f32 v[38:39], v[220:221], v[50:51], v[38:39] neg_lo:[1,0,0] neg_hi:[1,0,0]
	v_pk_fma_f32 v[42:43], v[230:231], v[50:51], v[42:43] neg_lo:[1,0,0] neg_hi:[1,0,0]
	v_pk_fma_f32 v[28:29], v[156:157], v[54:55], v[28:29] neg_lo:[1,0,0] neg_hi:[1,0,0]
	ds_read_b128 v[154:157], v109 offset:13424
	v_pk_fma_f32 v[34:35], v[160:161], v[54:55], v[34:35] neg_lo:[1,0,0] neg_hi:[1,0,0]
	ds_read_b128 v[158:161], v109 offset:13680
	v_pk_fma_f32 v[38:39], v[222:223], v[54:55], v[38:39] neg_lo:[1,0,0] neg_hi:[1,0,0]
	ds_read_b128 v[220:223], v109 offset:13936
	v_pk_fma_f32 v[42:43], v[232:233], v[54:55], v[42:43] neg_lo:[1,0,0] neg_hi:[1,0,0]
	ds_read_b128 v[230:233], v109 offset:14192
	s_waitcnt lgkmcnt(4)
	v_pk_fma_f32 v[28:29], v[234:235], v[60:61], v[28:29] neg_lo:[1,0,0] neg_hi:[1,0,0]
	v_pk_fma_f32 v[34:35], v[142:143], v[60:61], v[34:35] neg_lo:[1,0,0] neg_hi:[1,0,0]
	v_pk_fma_f32 v[38:39], v[146:147], v[60:61], v[38:39] neg_lo:[1,0,0] neg_hi:[1,0,0]
	v_pk_fma_f32 v[42:43], v[150:151], v[60:61], v[42:43] neg_lo:[1,0,0] neg_hi:[1,0,0]
	v_pk_fma_f32 v[28:29], v[236:237], v[64:65], v[28:29] neg_lo:[1,0,0] neg_hi:[1,0,0]
	ds_read_b128 v[234:237], v109 offset:13440
	v_pk_fma_f32 v[34:35], v[144:145], v[64:65], v[34:35] neg_lo:[1,0,0] neg_hi:[1,0,0]
	ds_read_b128 v[142:145], v109 offset:13696
	v_pk_fma_f32 v[38:39], v[148:149], v[64:65], v[38:39] neg_lo:[1,0,0] neg_hi:[1,0,0]
	ds_read_b128 v[146:149], v109 offset:13952
	v_pk_fma_f32 v[42:43], v[152:153], v[64:65], v[42:43] neg_lo:[1,0,0] neg_hi:[1,0,0]
	ds_read_b128 v[150:153], v109 offset:14208
	s_waitcnt lgkmcnt(4)
	v_pk_fma_f32 v[28:29], v[154:155], v[70:71], v[28:29] neg_lo:[1,0,0] neg_hi:[1,0,0]
	v_pk_fma_f32 v[34:35], v[158:159], v[70:71], v[34:35] neg_lo:[1,0,0] neg_hi:[1,0,0]
	v_pk_fma_f32 v[38:39], v[220:221], v[70:71], v[38:39] neg_lo:[1,0,0] neg_hi:[1,0,0]
	v_pk_fma_f32 v[42:43], v[230:231], v[70:71], v[42:43] neg_lo:[1,0,0] neg_hi:[1,0,0]
	v_pk_fma_f32 v[28:29], v[156:157], v[112:113], v[28:29] neg_lo:[1,0,0] neg_hi:[1,0,0]
	ds_read_b128 v[154:157], v109 offset:13456
	v_pk_fma_f32 v[34:35], v[160:161], v[112:113], v[34:35] neg_lo:[1,0,0] neg_hi:[1,0,0]
	ds_read_b128 v[158:161], v109 offset:13712
	v_pk_fma_f32 v[38:39], v[222:223], v[112:113], v[38:39] neg_lo:[1,0,0] neg_hi:[1,0,0]
	ds_read_b128 v[220:223], v109 offset:13968
	v_pk_fma_f32 v[42:43], v[232:233], v[112:113], v[42:43] neg_lo:[1,0,0] neg_hi:[1,0,0]
	ds_read_b128 v[230:233], v109 offset:14224
	s_waitcnt lgkmcnt(4)
	v_pk_fma_f32 v[28:29], v[234:235], v[116:117], v[28:29] neg_lo:[1,0,0] neg_hi:[1,0,0]
	v_pk_fma_f32 v[34:35], v[142:143], v[116:117], v[34:35] neg_lo:[1,0,0] neg_hi:[1,0,0]
	v_pk_fma_f32 v[38:39], v[146:147], v[116:117], v[38:39] neg_lo:[1,0,0] neg_hi:[1,0,0]
	v_pk_fma_f32 v[42:43], v[150:151], v[116:117], v[42:43] neg_lo:[1,0,0] neg_hi:[1,0,0]
	v_pk_fma_f32 v[28:29], v[236:237], v[122:123], v[28:29] neg_lo:[1,0,0] neg_hi:[1,0,0]
	ds_read_b128 v[234:237], v109 offset:13472
	v_pk_fma_f32 v[34:35], v[144:145], v[122:123], v[34:35] neg_lo:[1,0,0] neg_hi:[1,0,0]
	ds_read_b128 v[142:145], v109 offset:13728
	v_pk_fma_f32 v[38:39], v[148:149], v[122:123], v[38:39] neg_lo:[1,0,0] neg_hi:[1,0,0]
	ds_read_b128 v[146:149], v109 offset:13984
	v_pk_fma_f32 v[42:43], v[152:153], v[122:123], v[42:43] neg_lo:[1,0,0] neg_hi:[1,0,0]
	ds_read_b128 v[150:153], v109 offset:14240
	s_waitcnt lgkmcnt(4)
	v_pk_fma_f32 v[28:29], v[154:155], v[128:129], v[28:29] neg_lo:[1,0,0] neg_hi:[1,0,0]
	v_pk_fma_f32 v[34:35], v[158:159], v[128:129], v[34:35] neg_lo:[1,0,0] neg_hi:[1,0,0]
	v_pk_fma_f32 v[38:39], v[220:221], v[128:129], v[38:39] neg_lo:[1,0,0] neg_hi:[1,0,0]
	v_pk_fma_f32 v[42:43], v[230:231], v[128:129], v[42:43] neg_lo:[1,0,0] neg_hi:[1,0,0]
	v_pk_fma_f32 v[28:29], v[156:157], v[134:135], v[28:29] neg_lo:[1,0,0] neg_hi:[1,0,0]
	ds_read_b128 v[154:157], v109 offset:13488
	v_pk_fma_f32 v[34:35], v[160:161], v[134:135], v[34:35] neg_lo:[1,0,0] neg_hi:[1,0,0]
	ds_read_b128 v[158:161], v109 offset:13744
	v_pk_fma_f32 v[38:39], v[222:223], v[134:135], v[38:39] neg_lo:[1,0,0] neg_hi:[1,0,0]
	ds_read_b128 v[220:223], v109 offset:14000
	v_pk_fma_f32 v[42:43], v[232:233], v[134:135], v[42:43] neg_lo:[1,0,0] neg_hi:[1,0,0]
	ds_read_b128 v[230:233], v109 offset:14256
	s_waitcnt lgkmcnt(4)
; #define LAS __attribute__((address_space(3)))
; __device__ __forceinline__ void gdn_local_unit(LAS unsigned char* lds, const GdnP& P, int unit, const int tid, const int pf) {
;     ...
;         for (int c = 1; c < 64; ++c) { f32x2 sp = (f32x2){sol2[c >> 1][c & 1], 0.f};
; #pragma unroll
;             for (int jb = 0; jb <= (c - 1) / 4; ++jb) { const f32x4 m4 = *(const LAS f32x4*)(Ms + c * 64 + 4 * jb);
;                 sp -= (f32x2){m4.x, m4.y} * sol2[2 * jb]; sp -= (f32x2){m4.z, m4.w} * sol2[2 * jb + 1]; }
;             sol2[c >> 1][c & 1] = sp.x + sp.y; }
	v_pk_fma_f32 v[28:29], v[234:235], v[140:141], v[28:29] neg_lo:[1,0,0] neg_hi:[1,0,0]
	v_pk_fma_f32 v[34:35], v[142:143], v[140:141], v[34:35] neg_lo:[1,0,0] neg_hi:[1,0,0]
	v_pk_fma_f32 v[38:39], v[146:147], v[140:141], v[38:39] neg_lo:[1,0,0] neg_hi:[1,0,0]
	v_pk_fma_f32 v[42:43], v[150:151], v[140:141], v[42:43] neg_lo:[1,0,0] neg_hi:[1,0,0]
	v_pk_fma_f32 v[28:29], v[236:237], v[138:139], v[28:29] neg_lo:[1,0,0] neg_hi:[1,0,0]
	ds_read_b128 v[234:237], v109 offset:13504
	v_pk_fma_f32 v[34:35], v[144:145], v[138:139], v[34:35] neg_lo:[1,0,0] neg_hi:[1,0,0]
	ds_read_b128 v[142:145], v109 offset:13760
	v_pk_fma_f32 v[38:39], v[148:149], v[138:139], v[38:39] neg_lo:[1,0,0] neg_hi:[1,0,0]
	ds_read_b128 v[146:149], v109 offset:14016
	v_pk_fma_f32 v[42:43], v[152:153], v[138:139], v[42:43] neg_lo:[1,0,0] neg_hi:[1,0,0]
	ds_read_b128 v[150:153], v109 offset:14272
	s_waitcnt lgkmcnt(4)
	v_pk_fma_f32 v[28:29], v[154:155], v[132:133], v[28:29] neg_lo:[1,0,0] neg_hi:[1,0,0]
	v_pk_fma_f32 v[34:35], v[158:159], v[132:133], v[34:35] neg_lo:[1,0,0] neg_hi:[1,0,0]
	v_pk_fma_f32 v[38:39], v[220:221], v[132:133], v[38:39] neg_lo:[1,0,0] neg_hi:[1,0,0]
	v_pk_fma_f32 v[42:43], v[230:231], v[132:133], v[42:43] neg_lo:[1,0,0] neg_hi:[1,0,0]
	v_pk_fma_f32 v[28:29], v[156:157], v[124:125], v[28:29] neg_lo:[1,0,0] neg_hi:[1,0,0]
	ds_read_b128 v[154:157], v109 offset:14336
	v_pk_fma_f32 v[34:35], v[160:161], v[124:125], v[34:35] neg_lo:[1,0,0] neg_hi:[1,0,0]
	ds_read_b128 v[158:161], v109 offset:14592
	v_pk_fma_f32 v[38:39], v[222:223], v[124:125], v[38:39] neg_lo:[1,0,0] neg_hi:[1,0,0]
	ds_read_b128 v[220:223], v109 offset:14848
	v_pk_fma_f32 v[42:43], v[232:233], v[124:125], v[42:43] neg_lo:[1,0,0] neg_hi:[1,0,0]
	ds_read_b128 v[230:233], v109 offset:15104
	s_waitcnt lgkmcnt(4)
	v_pk_fma_f32 v[28:29], v[234:235], v[118:119], v[28:29] neg_lo:[1,0,0] neg_hi:[1,0,0]
	v_pk_fma_f32 v[34:35], v[142:143], v[118:119], v[34:35] neg_lo:[1,0,0] neg_hi:[1,0,0]
	v_pk_fma_f32 v[38:39], v[146:147], v[118:119], v[38:39] neg_lo:[1,0,0] neg_hi:[1,0,0]
	v_pk_fma_f32 v[42:43], v[150:151], v[118:119], v[42:43] neg_lo:[1,0,0] neg_hi:[1,0,0]
	v_pk_fma_f32 v[28:29], v[236:237], v[74:75], v[28:29] neg_lo:[1,0,0] neg_hi:[1,0,0]
	ds_read_b128 v[234:237], v109 offset:14352
	v_pk_fma_f32 v[34:35], v[144:145], v[74:75], v[34:35] neg_lo:[1,0,0] neg_hi:[1,0,0]
	ds_read_b128 v[142:145], v109 offset:14608
	v_pk_fma_f32 v[38:39], v[148:149], v[74:75], v[38:39] neg_lo:[1,0,0] neg_hi:[1,0,0]
	ds_read_b128 v[146:149], v109 offset:14864
	v_pk_fma_f32 v[42:43], v[152:153], v[74:75], v[42:43] neg_lo:[1,0,0] neg_hi:[1,0,0]
	ds_read_b128 v[150:153], v109 offset:15120
	v_add_f32_e32 v28, v28, v29
	s_waitcnt lgkmcnt(5)
	v_pk_mul_f32 v[10:11], v[154:155], v[0:1] neg_lo:[1,0] neg_hi:[1,0]
	v_pk_mul_f32 v[16:17], v[158:159], v[0:1] neg_lo:[1,0] neg_hi:[1,0]
	v_add_f32_e32 v34, v34, v35
	v_pk_mul_f32 v[20:21], v[220:221], v[0:1] neg_lo:[1,0] neg_hi:[1,0]
	s_waitcnt lgkmcnt(4)
	v_pk_mul_f32 v[24:25], v[230:231], v[0:1] neg_lo:[1,0] neg_hi:[1,0]
	v_add_f32_e32 v38, v38, v39
	v_pk_fma_f32 v[10:11], v[156:157], v[8:9], v[10:11] neg_lo:[1,0,0] neg_hi:[1,0,0]
	ds_read_b128 v[154:157], v109 offset:13776
	v_pk_fma_f32 v[16:17], v[160:161], v[8:9], v[16:17] neg_lo:[1,0,0] neg_hi:[1,0,0]
	ds_read_b128 v[158:161], v109 offset:14368
	v_add_f32_e32 v42, v42, v43
	v_pk_fma_f32 v[20:21], v[222:223], v[8:9], v[20:21] neg_lo:[1,0,0] neg_hi:[1,0,0]
	ds_read_b128 v[220:223], v109 offset:14624
	v_pk_fma_f32 v[24:25], v[232:233], v[8:9], v[24:25] neg_lo:[1,0,0] neg_hi:[1,0,0]
	ds_read_b128 v[230:233], v109 offset:14032
	v_add_f32_e32 v66, v28, v66
	s_waitcnt lgkmcnt(5)
	v_pk_fma_f32 v[10:11], v[234:235], v[14:15], v[10:11] neg_lo:[1,0,0] neg_hi:[1,0,0]
	v_pk_fma_f32 v[16:17], v[142:143], v[14:15], v[16:17] neg_lo:[1,0,0] neg_hi:[1,0,0]
	v_add_f32_e32 v34, v34, v67
	v_pk_fma_f32 v[20:21], v[146:147], v[14:15], v[20:21] neg_lo:[1,0,0] neg_hi:[1,0,0]
	s_waitcnt lgkmcnt(4)
	v_pk_fma_f32 v[24:25], v[150:151], v[14:15], v[24:25] neg_lo:[1,0,0] neg_hi:[1,0,0]
	v_add_f32_e32 v38, v38, v56
	v_pk_fma_f32 v[10:11], v[236:237], v[18:19], v[10:11] neg_lo:[1,0,0] neg_hi:[1,0,0]
	ds_read_b128 v[234:237], v109 offset:14880
	v_pk_fma_f32 v[16:17], v[144:145], v[18:19], v[16:17] neg_lo:[1,0,0] neg_hi:[1,0,0]
	ds_read_b128 v[142:145], v109 offset:15136
	v_add_f32_e32 v42, v42, v57
	v_pk_fma_f32 v[20:21], v[148:149], v[18:19], v[20:21] neg_lo:[1,0,0] neg_hi:[1,0,0]
	ds_read_b128 v[146:149], v109 offset:14288
	v_pk_fma_f32 v[24:25], v[152:153], v[18:19], v[24:25] neg_lo:[1,0,0] neg_hi:[1,0,0]
	ds_read_b128 v[150:153], v109 offset:14384
	s_waitcnt lgkmcnt(4)
	v_fma_f32 v67, -v154, v66, v34
	ds_read_b128 v[154:157], v109 offset:14640
	v_pk_fma_f32 v[10:11], v[158:159], v[22:23], v[10:11] neg_lo:[1,0,0] neg_hi:[1,0,0]
	v_pk_fma_f32 v[16:17], v[220:221], v[22:23], v[16:17] neg_lo:[1,0,0] neg_hi:[1,0,0]
	v_fma_f32 v38, -v230, v66, v38
	s_waitcnt lgkmcnt(2)
	v_pk_fma_f32 v[20:21], v[234:235], v[22:23], v[20:21] neg_lo:[1,0,0] neg_hi:[1,0,0]
	v_pk_fma_f32 v[24:25], v[142:143], v[22:23], v[24:25] neg_lo:[1,0,0] neg_hi:[1,0,0]
	v_fma_f32 v42, -v146, v66, v42
	v_pk_fma_f32 v[10:11], v[160:161], v[26:27], v[10:11] neg_lo:[1,0,0] neg_hi:[1,0,0]
	ds_read_b128 v[158:161], v109 offset:14896
	v_pk_fma_f32 v[16:17], v[222:223], v[26:27], v[16:17] neg_lo:[1,0,0] neg_hi:[1,0,0]
	ds_read_b128 v[220:223], v109 offset:15152
	v_fma_f32 v56, -v231, v67, v38
	ds_read_b128 v[230:233], v109 offset:14400
	v_pk_fma_f32 v[20:21], v[236:237], v[26:27], v[20:21] neg_lo:[1,0,0] neg_hi:[1,0,0]
	ds_read_b128 v[234:237], v109 offset:14656
	v_pk_fma_f32 v[24:25], v[144:145], v[26:27], v[24:25] neg_lo:[1,0,0] neg_hi:[1,0,0]
	ds_read_b128 v[142:145], v109 offset:14912
	v_fma_f32 v42, -v147, v67, v42
	s_waitcnt lgkmcnt(4)
; #define LAS __attribute__((address_space(3)))
; __device__ __forceinline__ void gdn_local_unit(LAS unsigned char* lds, const GdnP& P, int unit, const int tid, const int pf) {
;     ...
;         for (int c = 1; c < 64; ++c) { f32x2 sp = (f32x2){sol2[c >> 1][c & 1], 0.f};
; #pragma unroll
;             for (int jb = 0; jb <= (c - 1) / 4; ++jb) { const f32x4 m4 = *(const LAS f32x4*)(Ms + c * 64 + 4 * jb);
;                 sp -= (f32x2){m4.x, m4.y} * sol2[2 * jb]; sp -= (f32x2){m4.z, m4.w} * sol2[2 * jb + 1]; }
;             sol2[c >> 1][c & 1] = sp.x + sp.y; }
	v_pk_fma_f32 v[10:11], v[150:151], v[30:31], v[10:11] neg_lo:[1,0,0] neg_hi:[1,0,0]
	v_pk_fma_f32 v[16:17], v[154:155], v[30:31], v[16:17] neg_lo:[1,0,0] neg_hi:[1,0,0]
	v_fma_f32 v57, -v148, v56, v42
	ds_read_b128 v[146:149], v109 offset:15168
	v_pk_fma_f32 v[20:21], v[158:159], v[30:31], v[20:21] neg_lo:[1,0,0] neg_hi:[1,0,0]
	s_waitcnt lgkmcnt(4)
	v_pk_fma_f32 v[24:25], v[220:221], v[30:31], v[24:25] neg_lo:[1,0,0] neg_hi:[1,0,0]
	v_pk_fma_f32 v[10:11], v[152:153], v[36:37], v[10:11] neg_lo:[1,0,0] neg_hi:[1,0,0]
	ds_read_b128 v[150:153], v109 offset:14416
	v_pk_fma_f32 v[16:17], v[156:157], v[36:37], v[16:17] neg_lo:[1,0,0] neg_hi:[1,0,0]
	ds_read_b128 v[154:157], v109 offset:14672
	v_pk_fma_f32 v[20:21], v[160:161], v[36:37], v[20:21] neg_lo:[1,0,0] neg_hi:[1,0,0]
	ds_read_b128 v[158:161], v109 offset:14928
	v_pk_fma_f32 v[24:25], v[222:223], v[36:37], v[24:25] neg_lo:[1,0,0] neg_hi:[1,0,0]
	ds_read_b128 v[220:223], v109 offset:15184
	s_waitcnt lgkmcnt(4)
	v_pk_fma_f32 v[10:11], v[230:231], v[40:41], v[10:11] neg_lo:[1,0,0] neg_hi:[1,0,0]
	v_pk_fma_f32 v[16:17], v[234:235], v[40:41], v[16:17] neg_lo:[1,0,0] neg_hi:[1,0,0]
	v_pk_fma_f32 v[20:21], v[142:143], v[40:41], v[20:21] neg_lo:[1,0,0] neg_hi:[1,0,0]
	v_pk_fma_f32 v[24:25], v[146:147], v[40:41], v[24:25] neg_lo:[1,0,0] neg_hi:[1,0,0]
	v_pk_fma_f32 v[10:11], v[232:233], v[44:45], v[10:11] neg_lo:[1,0,0] neg_hi:[1,0,0]
	ds_read_b128 v[230:233], v109 offset:14432
	v_pk_fma_f32 v[16:17], v[236:237], v[44:45], v[16:17] neg_lo:[1,0,0] neg_hi:[1,0,0]
	ds_read_b128 v[234:237], v109 offset:14688
	v_pk_fma_f32 v[20:21], v[144:145], v[44:45], v[20:21] neg_lo:[1,0,0] neg_hi:[1,0,0]
	ds_read_b128 v[142:145], v109 offset:14944
	v_pk_fma_f32 v[24:25], v[148:149], v[44:45], v[24:25] neg_lo:[1,0,0] neg_hi:[1,0,0]
	ds_read_b128 v[146:149], v109 offset:15200
	s_waitcnt lgkmcnt(4)
	v_pk_fma_f32 v[10:11], v[150:151], v[50:51], v[10:11] neg_lo:[1,0,0] neg_hi:[1,0,0]
	v_pk_fma_f32 v[16:17], v[154:155], v[50:51], v[16:17] neg_lo:[1,0,0] neg_hi:[1,0,0]
	v_pk_fma_f32 v[20:21], v[158:159], v[50:51], v[20:21] neg_lo:[1,0,0] neg_hi:[1,0,0]
	v_pk_fma_f32 v[24:25], v[220:221], v[50:51], v[24:25] neg_lo:[1,0,0] neg_hi:[1,0,0]
	v_pk_fma_f32 v[10:11], v[152:153], v[54:55], v[10:11] neg_lo:[1,0,0] neg_hi:[1,0,0]
	ds_read_b128 v[150:153], v109 offset:14448
	v_pk_fma_f32 v[16:17], v[156:157], v[54:55], v[16:17] neg_lo:[1,0,0] neg_hi:[1,0,0]
	ds_read_b128 v[154:157], v109 offset:14704
	v_pk_fma_f32 v[20:21], v[160:161], v[54:55], v[20:21] neg_lo:[1,0,0] neg_hi:[1,0,0]
	ds_read_b128 v[158:161], v109 offset:14960
	v_pk_fma_f32 v[24:25], v[222:223], v[54:55], v[24:25] neg_lo:[1,0,0] neg_hi:[1,0,0]
	ds_read_b128 v[220:223], v109 offset:15216
	s_waitcnt lgkmcnt(4)
	v_pk_fma_f32 v[10:11], v[230:231], v[60:61], v[10:11] neg_lo:[1,0,0] neg_hi:[1,0,0]
	v_pk_fma_f32 v[16:17], v[234:235], v[60:61], v[16:17] neg_lo:[1,0,0] neg_hi:[1,0,0]
	v_pk_fma_f32 v[20:21], v[142:143], v[60:61], v[20:21] neg_lo:[1,0,0] neg_hi:[1,0,0]
	v_pk_fma_f32 v[24:25], v[146:147], v[60:61], v[24:25] neg_lo:[1,0,0] neg_hi:[1,0,0]
	v_pk_fma_f32 v[10:11], v[232:233], v[64:65], v[10:11] neg_lo:[1,0,0] neg_hi:[1,0,0]
	ds_read_b128 v[230:233], v109 offset:14464
	v_pk_fma_f32 v[16:17], v[236:237], v[64:65], v[16:17] neg_lo:[1,0,0] neg_hi:[1,0,0]
	ds_read_b128 v[234:237], v109 offset:14720
	v_pk_fma_f32 v[20:21], v[144:145], v[64:65], v[20:21] neg_lo:[1,0,0] neg_hi:[1,0,0]
	ds_read_b128 v[142:145], v109 offset:14976
	v_pk_fma_f32 v[24:25], v[148:149], v[64:65], v[24:25] neg_lo:[1,0,0] neg_hi:[1,0,0]
	ds_read_b128 v[146:149], v109 offset:15232
	s_waitcnt lgkmcnt(4)
	v_pk_fma_f32 v[10:11], v[150:151], v[70:71], v[10:11] neg_lo:[1,0,0] neg_hi:[1,0,0]
	v_pk_fma_f32 v[16:17], v[154:155], v[70:71], v[16:17] neg_lo:[1,0,0] neg_hi:[1,0,0]
	v_pk_fma_f32 v[20:21], v[158:159], v[70:71], v[20:21] neg_lo:[1,0,0] neg_hi:[1,0,0]
	v_pk_fma_f32 v[24:25], v[220:221], v[70:71], v[24:25] neg_lo:[1,0,0] neg_hi:[1,0,0]
	v_pk_fma_f32 v[10:11], v[152:153], v[112:113], v[10:11] neg_lo:[1,0,0] neg_hi:[1,0,0]
	ds_read_b128 v[150:153], v109 offset:14480
	v_pk_fma_f32 v[16:17], v[156:157], v[112:113], v[16:17] neg_lo:[1,0,0] neg_hi:[1,0,0]
	ds_read_b128 v[154:157], v109 offset:14736
	v_pk_fma_f32 v[20:21], v[160:161], v[112:113], v[20:21] neg_lo:[1,0,0] neg_hi:[1,0,0]
	ds_read_b128 v[158:161], v109 offset:14992
	v_pk_fma_f32 v[24:25], v[222:223], v[112:113], v[24:25] neg_lo:[1,0,0] neg_hi:[1,0,0]
	ds_read_b128 v[220:223], v109 offset:15248
	s_waitcnt lgkmcnt(4)
	v_pk_fma_f32 v[10:11], v[230:231], v[116:117], v[10:11] neg_lo:[1,0,0] neg_hi:[1,0,0]
	v_pk_fma_f32 v[16:17], v[234:235], v[116:117], v[16:17] neg_lo:[1,0,0] neg_hi:[1,0,0]
	v_pk_fma_f32 v[20:21], v[142:143], v[116:117], v[20:21] neg_lo:[1,0,0] neg_hi:[1,0,0]
	v_pk_fma_f32 v[24:25], v[146:147], v[116:117], v[24:25] neg_lo:[1,0,0] neg_hi:[1,0,0]
	v_pk_fma_f32 v[10:11], v[232:233], v[122:123], v[10:11] neg_lo:[1,0,0] neg_hi:[1,0,0]
	ds_read_b128 v[230:233], v109 offset:14496
	v_pk_fma_f32 v[16:17], v[236:237], v[122:123], v[16:17] neg_lo:[1,0,0] neg_hi:[1,0,0]
	ds_read_b128 v[234:237], v109 offset:14752
	v_pk_fma_f32 v[20:21], v[144:145], v[122:123], v[20:21] neg_lo:[1,0,0] neg_hi:[1,0,0]
	ds_read_b128 v[142:145], v109 offset:15008
	v_pk_fma_f32 v[24:25], v[148:149], v[122:123], v[24:25] neg_lo:[1,0,0] neg_hi:[1,0,0]
	ds_read_b128 v[146:149], v109 offset:15264
	s_waitcnt lgkmcnt(4)
; #define LAS __attribute__((address_space(3)))
; __device__ __forceinline__ void gdn_local_unit(LAS unsigned char* lds, const GdnP& P, int unit, const int tid, const int pf) {
;     ...
;         for (int c = 1; c < 64; ++c) { f32x2 sp = (f32x2){sol2[c >> 1][c & 1], 0.f};
; #pragma unroll
;             for (int jb = 0; jb <= (c - 1) / 4; ++jb) { const f32x4 m4 = *(const LAS f32x4*)(Ms + c * 64 + 4 * jb);
;                 sp -= (f32x2){m4.x, m4.y} * sol2[2 * jb]; sp -= (f32x2){m4.z, m4.w} * sol2[2 * jb + 1]; }
;             sol2[c >> 1][c & 1] = sp.x + sp.y; }
	v_pk_fma_f32 v[10:11], v[150:151], v[128:129], v[10:11] neg_lo:[1,0,0] neg_hi:[1,0,0]
	v_pk_fma_f32 v[16:17], v[154:155], v[128:129], v[16:17] neg_lo:[1,0,0] neg_hi:[1,0,0]
	v_pk_fma_f32 v[20:21], v[158:159], v[128:129], v[20:21] neg_lo:[1,0,0] neg_hi:[1,0,0]
	v_pk_fma_f32 v[24:25], v[220:221], v[128:129], v[24:25] neg_lo:[1,0,0] neg_hi:[1,0,0]
	v_pk_fma_f32 v[10:11], v[152:153], v[134:135], v[10:11] neg_lo:[1,0,0] neg_hi:[1,0,0]
	ds_read_b128 v[150:153], v109 offset:14512
	v_pk_fma_f32 v[16:17], v[156:157], v[134:135], v[16:17] neg_lo:[1,0,0] neg_hi:[1,0,0]
	ds_read_b128 v[154:157], v109 offset:14768
	v_pk_fma_f32 v[20:21], v[160:161], v[134:135], v[20:21] neg_lo:[1,0,0] neg_hi:[1,0,0]
	ds_read_b128 v[158:161], v109 offset:15024
	v_pk_fma_f32 v[24:25], v[222:223], v[134:135], v[24:25] neg_lo:[1,0,0] neg_hi:[1,0,0]
	ds_read_b128 v[220:223], v109 offset:15280
	s_waitcnt lgkmcnt(4)
	v_pk_fma_f32 v[10:11], v[230:231], v[140:141], v[10:11] neg_lo:[1,0,0] neg_hi:[1,0,0]
	v_pk_fma_f32 v[16:17], v[234:235], v[140:141], v[16:17] neg_lo:[1,0,0] neg_hi:[1,0,0]
	v_pk_fma_f32 v[20:21], v[142:143], v[140:141], v[20:21] neg_lo:[1,0,0] neg_hi:[1,0,0]
	v_pk_fma_f32 v[24:25], v[146:147], v[140:141], v[24:25] neg_lo:[1,0,0] neg_hi:[1,0,0]
	v_pk_fma_f32 v[10:11], v[232:233], v[138:139], v[10:11] neg_lo:[1,0,0] neg_hi:[1,0,0]
	ds_read_b128 v[230:233], v109 offset:14528
	v_pk_fma_f32 v[16:17], v[236:237], v[138:139], v[16:17] neg_lo:[1,0,0] neg_hi:[1,0,0]
	ds_read_b128 v[234:237], v109 offset:14784
	v_pk_fma_f32 v[20:21], v[144:145], v[138:139], v[20:21] neg_lo:[1,0,0] neg_hi:[1,0,0]
	ds_read_b128 v[142:145], v109 offset:15040
	v_pk_fma_f32 v[24:25], v[148:149], v[138:139], v[24:25] neg_lo:[1,0,0] neg_hi:[1,0,0]
	ds_read_b128 v[146:149], v109 offset:15296
	s_waitcnt lgkmcnt(4)
	v_pk_fma_f32 v[10:11], v[150:151], v[132:133], v[10:11] neg_lo:[1,0,0] neg_hi:[1,0,0]
	v_pk_fma_f32 v[16:17], v[154:155], v[132:133], v[16:17] neg_lo:[1,0,0] neg_hi:[1,0,0]
	v_pk_fma_f32 v[20:21], v[158:159], v[132:133], v[20:21] neg_lo:[1,0,0] neg_hi:[1,0,0]
	v_pk_fma_f32 v[24:25], v[220:221], v[132:133], v[24:25] neg_lo:[1,0,0] neg_hi:[1,0,0]
	v_pk_fma_f32 v[10:11], v[152:153], v[124:125], v[10:11] neg_lo:[1,0,0] neg_hi:[1,0,0]
	ds_read_b128 v[150:153], v109 offset:14544
	v_pk_fma_f32 v[16:17], v[156:157], v[124:125], v[16:17] neg_lo:[1,0,0] neg_hi:[1,0,0]
	ds_read_b128 v[154:157], v109 offset:14800
	v_pk_fma_f32 v[20:21], v[160:161], v[124:125], v[20:21] neg_lo:[1,0,0] neg_hi:[1,0,0]
	ds_read_b128 v[158:161], v109 offset:15056
	v_pk_fma_f32 v[24:25], v[222:223], v[124:125], v[24:25] neg_lo:[1,0,0] neg_hi:[1,0,0]
	ds_read_b128 v[220:223], v109 offset:15312
	s_waitcnt lgkmcnt(4)
	v_pk_fma_f32 v[10:11], v[230:231], v[118:119], v[10:11] neg_lo:[1,0,0] neg_hi:[1,0,0]
	v_pk_fma_f32 v[16:17], v[234:235], v[118:119], v[16:17] neg_lo:[1,0,0] neg_hi:[1,0,0]
	v_pk_fma_f32 v[20:21], v[142:143], v[118:119], v[20:21] neg_lo:[1,0,0] neg_hi:[1,0,0]
	v_pk_fma_f32 v[24:25], v[146:147], v[118:119], v[24:25] neg_lo:[1,0,0] neg_hi:[1,0,0]
	v_pk_fma_f32 v[10:11], v[232:233], v[74:75], v[10:11] neg_lo:[1,0,0] neg_hi:[1,0,0]
	ds_read_b128 v[230:233], v109 offset:15360
	v_pk_fma_f32 v[16:17], v[236:237], v[74:75], v[16:17] neg_lo:[1,0,0] neg_hi:[1,0,0]
	ds_read_b128 v[234:237], v109 offset:15616
	v_pk_fma_f32 v[20:21], v[144:145], v[74:75], v[20:21] neg_lo:[1,0,0] neg_hi:[1,0,0]
	ds_read_b128 v[142:145], v109 offset:15872
	v_pk_fma_f32 v[24:25], v[148:149], v[74:75], v[24:25] neg_lo:[1,0,0] neg_hi:[1,0,0]
	ds_read_b128 v[146:149], v109 offset:16128
	s_waitcnt lgkmcnt(4)
	v_pk_fma_f32 v[10:11], v[150:151], v[66:67], v[10:11] neg_lo:[1,0,0] neg_hi:[1,0,0]
	v_pk_fma_f32 v[16:17], v[154:155], v[66:67], v[16:17] neg_lo:[1,0,0] neg_hi:[1,0,0]
	v_pk_fma_f32 v[20:21], v[158:159], v[66:67], v[20:21] neg_lo:[1,0,0] neg_hi:[1,0,0]
	v_pk_fma_f32 v[24:25], v[220:221], v[66:67], v[24:25] neg_lo:[1,0,0] neg_hi:[1,0,0]
	v_pk_fma_f32 v[10:11], v[152:153], v[56:57], v[10:11] neg_lo:[1,0,0] neg_hi:[1,0,0]
	ds_read_b128 v[150:153], v109 offset:15376
	v_pk_fma_f32 v[16:17], v[156:157], v[56:57], v[16:17] neg_lo:[1,0,0] neg_hi:[1,0,0]
	ds_read_b128 v[154:157], v109 offset:15632
	v_pk_fma_f32 v[20:21], v[160:161], v[56:57], v[20:21] neg_lo:[1,0,0] neg_hi:[1,0,0]
	ds_read_b128 v[158:161], v109 offset:15888
	v_pk_fma_f32 v[24:25], v[222:223], v[56:57], v[24:25] neg_lo:[1,0,0] neg_hi:[1,0,0]
	ds_read_b128 v[220:223], v109 offset:16144
	v_add_f32_e32 v10, v10, v11
	s_waitcnt lgkmcnt(5)
	v_pk_mul_f32 v[28:29], v[230:231], v[0:1] neg_lo:[1,0] neg_hi:[1,0]
	v_pk_mul_f32 v[34:35], v[234:235], v[0:1] neg_lo:[1,0] neg_hi:[1,0]
	v_add_f32_e32 v16, v16, v17
	v_pk_mul_f32 v[38:39], v[142:143], v[0:1] neg_lo:[1,0] neg_hi:[1,0]
	s_waitcnt lgkmcnt(4)
	v_pk_mul_f32 v[42:43], v[146:147], v[0:1] neg_lo:[1,0] neg_hi:[1,0]
	v_add_f32_e32 v20, v20, v21
	v_pk_fma_f32 v[28:29], v[232:233], v[8:9], v[28:29] neg_lo:[1,0,0] neg_hi:[1,0,0]
	ds_read_b128 v[230:233], v109 offset:14816
	v_pk_fma_f32 v[34:35], v[236:237], v[8:9], v[34:35] neg_lo:[1,0,0] neg_hi:[1,0,0]
	ds_read_b128 v[234:237], v109 offset:15392
	v_add_f32_e32 v24, v24, v25
	v_pk_fma_f32 v[38:39], v[144:145], v[8:9], v[38:39] neg_lo:[1,0,0] neg_hi:[1,0,0]
	ds_read_b128 v[142:145], v109 offset:15648
	v_pk_fma_f32 v[42:43], v[148:149], v[8:9], v[42:43] neg_lo:[1,0,0] neg_hi:[1,0,0]
	ds_read_b128 v[146:149], v109 offset:15072
	v_add_f32_e32 v46, v10, v46
	s_waitcnt lgkmcnt(5)
	v_pk_fma_f32 v[28:29], v[150:151], v[14:15], v[28:29] neg_lo:[1,0,0] neg_hi:[1,0,0]
	v_pk_fma_f32 v[34:35], v[154:155], v[14:15], v[34:35] neg_lo:[1,0,0] neg_hi:[1,0,0]
	v_add_f32_e32 v16, v16, v47
	v_pk_fma_f32 v[38:39], v[158:159], v[14:15], v[38:39] neg_lo:[1,0,0] neg_hi:[1,0,0]
	s_waitcnt lgkmcnt(4)
; #define LAS __attribute__((address_space(3)))
; __device__ __forceinline__ void gdn_local_unit(LAS unsigned char* lds, const GdnP& P, int unit, const int tid, const int pf) {
;     ...
;         for (int c = 1; c < 64; ++c) { f32x2 sp = (f32x2){sol2[c >> 1][c & 1], 0.f};
; #pragma unroll
;             for (int jb = 0; jb <= (c - 1) / 4; ++jb) { const f32x4 m4 = *(const LAS f32x4*)(Ms + c * 64 + 4 * jb);
;                 sp -= (f32x2){m4.x, m4.y} * sol2[2 * jb]; sp -= (f32x2){m4.z, m4.w} * sol2[2 * jb + 1]; }
;             sol2[c >> 1][c & 1] = sp.x + sp.y; }
	v_pk_fma_f32 v[42:43], v[220:221], v[14:15], v[42:43] neg_lo:[1,0,0] neg_hi:[1,0,0]
	v_add_f32_e32 v20, v20, v32
	v_pk_fma_f32 v[28:29], v[152:153], v[18:19], v[28:29] neg_lo:[1,0,0] neg_hi:[1,0,0]
	ds_read_b128 v[150:153], v109 offset:15904
	v_pk_fma_f32 v[34:35], v[156:157], v[18:19], v[34:35] neg_lo:[1,0,0] neg_hi:[1,0,0]
	ds_read_b128 v[154:157], v109 offset:16160
	v_add_f32_e32 v24, v24, v33
	v_pk_fma_f32 v[38:39], v[160:161], v[18:19], v[38:39] neg_lo:[1,0,0] neg_hi:[1,0,0]
	ds_read_b128 v[158:161], v109 offset:15328
	v_pk_fma_f32 v[42:43], v[222:223], v[18:19], v[42:43] neg_lo:[1,0,0] neg_hi:[1,0,0]
	ds_read_b128 v[220:223], v109 offset:15408
	s_waitcnt lgkmcnt(4)
	v_fma_f32 v47, -v230, v46, v16
	ds_read_b128 v[230:233], v109 offset:15664
	v_pk_fma_f32 v[28:29], v[234:235], v[22:23], v[28:29] neg_lo:[1,0,0] neg_hi:[1,0,0]
	v_pk_fma_f32 v[34:35], v[142:143], v[22:23], v[34:35] neg_lo:[1,0,0] neg_hi:[1,0,0]
	v_fma_f32 v20, -v146, v46, v20
	s_waitcnt lgkmcnt(2)
	v_pk_fma_f32 v[38:39], v[150:151], v[22:23], v[38:39] neg_lo:[1,0,0] neg_hi:[1,0,0]
	v_pk_fma_f32 v[42:43], v[154:155], v[22:23], v[42:43] neg_lo:[1,0,0] neg_hi:[1,0,0]
	v_fma_f32 v24, -v158, v46, v24
	v_pk_fma_f32 v[28:29], v[236:237], v[26:27], v[28:29] neg_lo:[1,0,0] neg_hi:[1,0,0]
	ds_read_b128 v[234:237], v109 offset:15920
	v_pk_fma_f32 v[34:35], v[144:145], v[26:27], v[34:35] neg_lo:[1,0,0] neg_hi:[1,0,0]
	ds_read_b128 v[142:145], v109 offset:16176
	v_fma_f32 v32, -v147, v47, v20
	ds_read_b128 v[146:149], v109 offset:15424
	v_pk_fma_f32 v[38:39], v[152:153], v[26:27], v[38:39] neg_lo:[1,0,0] neg_hi:[1,0,0]
	ds_read_b128 v[150:153], v109 offset:15680
	v_pk_fma_f32 v[42:43], v[156:157], v[26:27], v[42:43] neg_lo:[1,0,0] neg_hi:[1,0,0]
	ds_read_b128 v[154:157], v109 offset:15936
	v_fma_f32 v24, -v159, v47, v24
	s_waitcnt lgkmcnt(4)
	v_pk_fma_f32 v[28:29], v[220:221], v[30:31], v[28:29] neg_lo:[1,0,0] neg_hi:[1,0,0]
	v_pk_fma_f32 v[34:35], v[230:231], v[30:31], v[34:35] neg_lo:[1,0,0] neg_hi:[1,0,0]
	v_fma_f32 v33, -v160, v32, v24
	ds_read_b128 v[158:161], v109 offset:16192
	v_pk_fma_f32 v[38:39], v[234:235], v[30:31], v[38:39] neg_lo:[1,0,0] neg_hi:[1,0,0]
	s_waitcnt lgkmcnt(4)
	v_pk_fma_f32 v[42:43], v[142:143], v[30:31], v[42:43] neg_lo:[1,0,0] neg_hi:[1,0,0]
	v_pk_fma_f32 v[28:29], v[222:223], v[36:37], v[28:29] neg_lo:[1,0,0] neg_hi:[1,0,0]
	ds_read_b128 v[220:223], v109 offset:15440
	v_pk_fma_f32 v[34:35], v[232:233], v[36:37], v[34:35] neg_lo:[1,0,0] neg_hi:[1,0,0]
	ds_read_b128 v[230:233], v109 offset:15696
	v_pk_fma_f32 v[38:39], v[236:237], v[36:37], v[38:39] neg_lo:[1,0,0] neg_hi:[1,0,0]
	ds_read_b128 v[234:237], v109 offset:15952
	v_pk_fma_f32 v[42:43], v[144:145], v[36:37], v[42:43] neg_lo:[1,0,0] neg_hi:[1,0,0]
	ds_read_b128 v[142:145], v109 offset:16208
	s_waitcnt lgkmcnt(4)
	v_pk_fma_f32 v[28:29], v[146:147], v[40:41], v[28:29] neg_lo:[1,0,0] neg_hi:[1,0,0]
	v_pk_fma_f32 v[34:35], v[150:151], v[40:41], v[34:35] neg_lo:[1,0,0] neg_hi:[1,0,0]
	v_pk_fma_f32 v[38:39], v[154:155], v[40:41], v[38:39] neg_lo:[1,0,0] neg_hi:[1,0,0]
	v_pk_fma_f32 v[42:43], v[158:159], v[40:41], v[42:43] neg_lo:[1,0,0] neg_hi:[1,0,0]
	v_pk_fma_f32 v[28:29], v[148:149], v[44:45], v[28:29] neg_lo:[1,0,0] neg_hi:[1,0,0]
	ds_read_b128 v[146:149], v109 offset:15456
	v_pk_fma_f32 v[34:35], v[152:153], v[44:45], v[34:35] neg_lo:[1,0,0] neg_hi:[1,0,0]
	ds_read_b128 v[150:153], v109 offset:15712
	v_pk_fma_f32 v[38:39], v[156:157], v[44:45], v[38:39] neg_lo:[1,0,0] neg_hi:[1,0,0]
	ds_read_b128 v[154:157], v109 offset:15968
	v_pk_fma_f32 v[42:43], v[160:161], v[44:45], v[42:43] neg_lo:[1,0,0] neg_hi:[1,0,0]
	ds_read_b128 v[158:161], v109 offset:16224
	s_waitcnt lgkmcnt(4)
	v_pk_fma_f32 v[28:29], v[220:221], v[50:51], v[28:29] neg_lo:[1,0,0] neg_hi:[1,0,0]
	v_pk_fma_f32 v[34:35], v[230:231], v[50:51], v[34:35] neg_lo:[1,0,0] neg_hi:[1,0,0]
	v_pk_fma_f32 v[38:39], v[234:235], v[50:51], v[38:39] neg_lo:[1,0,0] neg_hi:[1,0,0]
	v_pk_fma_f32 v[42:43], v[142:143], v[50:51], v[42:43] neg_lo:[1,0,0] neg_hi:[1,0,0]
	v_pk_fma_f32 v[28:29], v[222:223], v[54:55], v[28:29] neg_lo:[1,0,0] neg_hi:[1,0,0]
	ds_read_b128 v[220:223], v109 offset:15472
	v_pk_fma_f32 v[34:35], v[232:233], v[54:55], v[34:35] neg_lo:[1,0,0] neg_hi:[1,0,0]
	ds_read_b128 v[230:233], v109 offset:15728
	v_pk_fma_f32 v[38:39], v[236:237], v[54:55], v[38:39] neg_lo:[1,0,0] neg_hi:[1,0,0]
	ds_read_b128 v[234:237], v109 offset:15984
	v_pk_fma_f32 v[42:43], v[144:145], v[54:55], v[42:43] neg_lo:[1,0,0] neg_hi:[1,0,0]
	ds_read_b128 v[142:145], v109 offset:16240
	s_waitcnt lgkmcnt(4)
	v_pk_fma_f32 v[28:29], v[146:147], v[60:61], v[28:29] neg_lo:[1,0,0] neg_hi:[1,0,0]
	v_pk_fma_f32 v[34:35], v[150:151], v[60:61], v[34:35] neg_lo:[1,0,0] neg_hi:[1,0,0]
	v_pk_fma_f32 v[38:39], v[154:155], v[60:61], v[38:39] neg_lo:[1,0,0] neg_hi:[1,0,0]
	v_pk_fma_f32 v[42:43], v[158:159], v[60:61], v[42:43] neg_lo:[1,0,0] neg_hi:[1,0,0]
	v_pk_fma_f32 v[28:29], v[148:149], v[64:65], v[28:29] neg_lo:[1,0,0] neg_hi:[1,0,0]
	ds_read_b128 v[146:149], v109 offset:15488
	v_pk_fma_f32 v[34:35], v[152:153], v[64:65], v[34:35] neg_lo:[1,0,0] neg_hi:[1,0,0]
	ds_read_b128 v[150:153], v109 offset:15744
	v_pk_fma_f32 v[38:39], v[156:157], v[64:65], v[38:39] neg_lo:[1,0,0] neg_hi:[1,0,0]
	ds_read_b128 v[154:157], v109 offset:16000
	v_pk_fma_f32 v[42:43], v[160:161], v[64:65], v[42:43] neg_lo:[1,0,0] neg_hi:[1,0,0]
	ds_read_b128 v[158:161], v109 offset:16256
	s_waitcnt lgkmcnt(4)
; #define LAS __attribute__((address_space(3)))
; __device__ __forceinline__ void gdn_local_unit(LAS unsigned char* lds, const GdnP& P, int unit, const int tid, const int pf) {
;     ...
;         for (int c = 1; c < 64; ++c) { f32x2 sp = (f32x2){sol2[c >> 1][c & 1], 0.f};
; #pragma unroll
;             for (int jb = 0; jb <= (c - 1) / 4; ++jb) { const f32x4 m4 = *(const LAS f32x4*)(Ms + c * 64 + 4 * jb);
;                 sp -= (f32x2){m4.x, m4.y} * sol2[2 * jb]; sp -= (f32x2){m4.z, m4.w} * sol2[2 * jb + 1]; }
;             sol2[c >> 1][c & 1] = sp.x + sp.y; }
	v_pk_fma_f32 v[28:29], v[220:221], v[70:71], v[28:29] neg_lo:[1,0,0] neg_hi:[1,0,0]
	v_pk_fma_f32 v[34:35], v[230:231], v[70:71], v[34:35] neg_lo:[1,0,0] neg_hi:[1,0,0]
	v_pk_fma_f32 v[38:39], v[234:235], v[70:71], v[38:39] neg_lo:[1,0,0] neg_hi:[1,0,0]
	v_pk_fma_f32 v[42:43], v[142:143], v[70:71], v[42:43] neg_lo:[1,0,0] neg_hi:[1,0,0]
	v_pk_fma_f32 v[28:29], v[222:223], v[112:113], v[28:29] neg_lo:[1,0,0] neg_hi:[1,0,0]
	ds_read_b128 v[220:223], v109 offset:15504
	v_pk_fma_f32 v[34:35], v[232:233], v[112:113], v[34:35] neg_lo:[1,0,0] neg_hi:[1,0,0]
	ds_read_b128 v[230:233], v109 offset:15760
	v_pk_fma_f32 v[38:39], v[236:237], v[112:113], v[38:39] neg_lo:[1,0,0] neg_hi:[1,0,0]
	ds_read_b128 v[234:237], v109 offset:16016
	v_pk_fma_f32 v[42:43], v[144:145], v[112:113], v[42:43] neg_lo:[1,0,0] neg_hi:[1,0,0]
	ds_read_b128 v[142:145], v109 offset:16272
	s_waitcnt lgkmcnt(4)
	v_pk_fma_f32 v[28:29], v[146:147], v[116:117], v[28:29] neg_lo:[1,0,0] neg_hi:[1,0,0]
	v_pk_fma_f32 v[34:35], v[150:151], v[116:117], v[34:35] neg_lo:[1,0,0] neg_hi:[1,0,0]
	v_pk_fma_f32 v[38:39], v[154:155], v[116:117], v[38:39] neg_lo:[1,0,0] neg_hi:[1,0,0]
	v_pk_fma_f32 v[42:43], v[158:159], v[116:117], v[42:43] neg_lo:[1,0,0] neg_hi:[1,0,0]
	v_pk_fma_f32 v[28:29], v[148:149], v[122:123], v[28:29] neg_lo:[1,0,0] neg_hi:[1,0,0]
	ds_read_b128 v[146:149], v109 offset:15520
	v_pk_fma_f32 v[34:35], v[152:153], v[122:123], v[34:35] neg_lo:[1,0,0] neg_hi:[1,0,0]
	ds_read_b128 v[150:153], v109 offset:15776
	v_pk_fma_f32 v[38:39], v[156:157], v[122:123], v[38:39] neg_lo:[1,0,0] neg_hi:[1,0,0]
	ds_read_b128 v[154:157], v109 offset:16032
	v_pk_fma_f32 v[42:43], v[160:161], v[122:123], v[42:43] neg_lo:[1,0,0] neg_hi:[1,0,0]
	ds_read_b128 v[158:161], v109 offset:16288
	s_waitcnt lgkmcnt(4)
	v_pk_fma_f32 v[28:29], v[220:221], v[128:129], v[28:29] neg_lo:[1,0,0] neg_hi:[1,0,0]
	v_pk_fma_f32 v[34:35], v[230:231], v[128:129], v[34:35] neg_lo:[1,0,0] neg_hi:[1,0,0]
	v_pk_fma_f32 v[38:39], v[234:235], v[128:129], v[38:39] neg_lo:[1,0,0] neg_hi:[1,0,0]
	v_pk_fma_f32 v[42:43], v[142:143], v[128:129], v[42:43] neg_lo:[1,0,0] neg_hi:[1,0,0]
	v_pk_fma_f32 v[28:29], v[222:223], v[134:135], v[28:29] neg_lo:[1,0,0] neg_hi:[1,0,0]
	ds_read_b128 v[220:223], v109 offset:15536
	v_pk_fma_f32 v[34:35], v[232:233], v[134:135], v[34:35] neg_lo:[1,0,0] neg_hi:[1,0,0]
	ds_read_b128 v[230:233], v109 offset:15792
	v_pk_fma_f32 v[38:39], v[236:237], v[134:135], v[38:39] neg_lo:[1,0,0] neg_hi:[1,0,0]
	ds_read_b128 v[234:237], v109 offset:16048
	v_pk_fma_f32 v[42:43], v[144:145], v[134:135], v[42:43] neg_lo:[1,0,0] neg_hi:[1,0,0]
	ds_read_b128 v[142:145], v109 offset:16304
	s_waitcnt lgkmcnt(4)
	v_pk_fma_f32 v[28:29], v[146:147], v[140:141], v[28:29] neg_lo:[1,0,0] neg_hi:[1,0,0]
	v_pk_fma_f32 v[34:35], v[150:151], v[140:141], v[34:35] neg_lo:[1,0,0] neg_hi:[1,0,0]
	v_pk_fma_f32 v[38:39], v[154:155], v[140:141], v[38:39] neg_lo:[1,0,0] neg_hi:[1,0,0]
	v_pk_fma_f32 v[42:43], v[158:159], v[140:141], v[42:43] neg_lo:[1,0,0] neg_hi:[1,0,0]
	v_pk_fma_f32 v[28:29], v[148:149], v[138:139], v[28:29] neg_lo:[1,0,0] neg_hi:[1,0,0]
	ds_read_b128 v[146:149], v109 offset:15552
	v_pk_fma_f32 v[34:35], v[152:153], v[138:139], v[34:35] neg_lo:[1,0,0] neg_hi:[1,0,0]
	ds_read_b128 v[150:153], v109 offset:15808
	v_pk_fma_f32 v[38:39], v[156:157], v[138:139], v[38:39] neg_lo:[1,0,0] neg_hi:[1,0,0]
	ds_read_b128 v[154:157], v109 offset:16064
	v_pk_fma_f32 v[42:43], v[160:161], v[138:139], v[42:43] neg_lo:[1,0,0] neg_hi:[1,0,0]
	ds_read_b128 v[158:161], v109 offset:16320
	s_waitcnt lgkmcnt(4)
	v_pk_fma_f32 v[28:29], v[220:221], v[132:133], v[28:29] neg_lo:[1,0,0] neg_hi:[1,0,0]
	v_pk_fma_f32 v[34:35], v[230:231], v[132:133], v[34:35] neg_lo:[1,0,0] neg_hi:[1,0,0]
	v_pk_fma_f32 v[38:39], v[234:235], v[132:133], v[38:39] neg_lo:[1,0,0] neg_hi:[1,0,0]
	v_pk_fma_f32 v[42:43], v[142:143], v[132:133], v[42:43] neg_lo:[1,0,0] neg_hi:[1,0,0]
	v_pk_fma_f32 v[28:29], v[222:223], v[124:125], v[28:29] neg_lo:[1,0,0] neg_hi:[1,0,0]
	ds_read_b128 v[220:223], v109 offset:15568
	v_pk_fma_f32 v[34:35], v[232:233], v[124:125], v[34:35] neg_lo:[1,0,0] neg_hi:[1,0,0]
	ds_read_b128 v[230:233], v109 offset:15824
	v_pk_fma_f32 v[38:39], v[236:237], v[124:125], v[38:39] neg_lo:[1,0,0] neg_hi:[1,0,0]
	ds_read_b128 v[234:237], v109 offset:16080
	v_pk_fma_f32 v[42:43], v[144:145], v[124:125], v[42:43] neg_lo:[1,0,0] neg_hi:[1,0,0]
	ds_read_b128 v[142:145], v109 offset:16336
	s_waitcnt lgkmcnt(4)
	v_pk_fma_f32 v[28:29], v[146:147], v[118:119], v[28:29] neg_lo:[1,0,0] neg_hi:[1,0,0]
	v_pk_fma_f32 v[34:35], v[150:151], v[118:119], v[34:35] neg_lo:[1,0,0] neg_hi:[1,0,0]
	v_pk_fma_f32 v[38:39], v[154:155], v[118:119], v[38:39] neg_lo:[1,0,0] neg_hi:[1,0,0]
	v_pk_fma_f32 v[42:43], v[158:159], v[118:119], v[42:43] neg_lo:[1,0,0] neg_hi:[1,0,0]
	v_pk_fma_f32 v[28:29], v[148:149], v[74:75], v[28:29] neg_lo:[1,0,0] neg_hi:[1,0,0]
	ds_read_b128 v[146:149], v109 offset:15584
	v_pk_fma_f32 v[34:35], v[152:153], v[74:75], v[34:35] neg_lo:[1,0,0] neg_hi:[1,0,0]
	ds_read_b128 v[150:153], v109 offset:15840
	v_pk_fma_f32 v[38:39], v[156:157], v[74:75], v[38:39] neg_lo:[1,0,0] neg_hi:[1,0,0]
	ds_read_b128 v[154:157], v109 offset:16096
	v_pk_fma_f32 v[42:43], v[160:161], v[74:75], v[42:43] neg_lo:[1,0,0] neg_hi:[1,0,0]
	ds_read_b128 v[158:161], v109 offset:16352
	s_waitcnt lgkmcnt(4)
; #define LAS __attribute__((address_space(3)))
; __device__ __forceinline__ unsigned f2bf(float f) { return pk2(f, 0.f) & 0xffffu; }
; __device__ __forceinline__ void gdn_local_unit(LAS unsigned char* lds, const GdnP& P, int unit, const int tid, const int pf) {
;     ...
;         for (int c = 1; c < 64; ++c) { f32x2 sp = (f32x2){sol2[c >> 1][c & 1], 0.f};
; #pragma unroll
;             for (int jb = 0; jb <= (c - 1) / 4; ++jb) { const f32x4 m4 = *(const LAS f32x4*)(Ms + c * 64 + 4 * jb);
;                 sp -= (f32x2){m4.x, m4.y} * sol2[2 * jb]; sp -= (f32x2){m4.z, m4.w} * sol2[2 * jb + 1]; }
;             sol2[c >> 1][c & 1] = sp.x + sp.y; }
;         if (col < 128) {
; #pragma unroll
;             for (int t = 0; t < 64; ++t) Vs[t * 128 + col] = sol2[t >> 1][t & 1];
;         } else {
; #pragma unroll
;             for (int t = 0; t < 64; ++t) *(LAS bf16_t*)(lds + GL_QB + t * 272 + (col - 128) * 2) = (bf16_t)f2bf(sol2[t >> 1][t & 1]);
	v_pk_fma_f32 v[28:29], v[220:221], v[66:67], v[28:29] neg_lo:[1,0,0] neg_hi:[1,0,0]
	v_pk_fma_f32 v[34:35], v[230:231], v[66:67], v[34:35] neg_lo:[1,0,0] neg_hi:[1,0,0]
	v_pk_fma_f32 v[38:39], v[234:235], v[66:67], v[38:39] neg_lo:[1,0,0] neg_hi:[1,0,0]
	v_pk_fma_f32 v[42:43], v[142:143], v[66:67], v[42:43] neg_lo:[1,0,0] neg_hi:[1,0,0]
	v_pk_fma_f32 v[28:29], v[222:223], v[56:57], v[28:29] neg_lo:[1,0,0] neg_hi:[1,0,0]
	ds_read_b128 v[220:223], v109 offset:15856
	v_pk_fma_f32 v[34:35], v[232:233], v[56:57], v[34:35] neg_lo:[1,0,0] neg_hi:[1,0,0]
	ds_read_b128 v[230:233], v109 offset:16112
	v_pk_fma_f32 v[38:39], v[236:237], v[56:57], v[38:39] neg_lo:[1,0,0] neg_hi:[1,0,0]
	ds_read_b128 v[234:237], v109 offset:16368
	v_pk_fma_f32 v[42:43], v[144:145], v[56:57], v[42:43] neg_lo:[1,0,0] neg_hi:[1,0,0]
	s_waitcnt lgkmcnt(3)
	v_pk_fma_f32 v[28:29], v[146:147], v[46:47], v[28:29] neg_lo:[1,0,0] neg_hi:[1,0,0]
	v_pk_fma_f32 v[34:35], v[150:151], v[46:47], v[34:35] neg_lo:[1,0,0] neg_hi:[1,0,0]
	v_pk_fma_f32 v[38:39], v[154:155], v[46:47], v[38:39] neg_lo:[1,0,0] neg_hi:[1,0,0]
	v_pk_fma_f32 v[42:43], v[158:159], v[46:47], v[42:43] neg_lo:[1,0,0] neg_hi:[1,0,0]
	v_pk_fma_f32 v[28:29], v[148:149], v[32:33], v[28:29] neg_lo:[1,0,0] neg_hi:[1,0,0]
	v_pk_fma_f32 v[34:35], v[152:153], v[32:33], v[34:35] neg_lo:[1,0,0] neg_hi:[1,0,0]
	v_pk_fma_f32 v[38:39], v[156:157], v[32:33], v[38:39] neg_lo:[1,0,0] neg_hi:[1,0,0]
	v_pk_fma_f32 v[42:43], v[160:161], v[32:33], v[42:43] neg_lo:[1,0,0] neg_hi:[1,0,0]
	v_add_f32_e32 v28, v28, v29
	v_add_f32_e32 v34, v34, v35
	v_add_f32_e32 v38, v38, v39
	v_add_f32_e32 v42, v42, v43
	v_add_f32_e32 v12, v28, v12
	v_add_f32_e32 v34, v34, v13
	v_add_f32_e32 v38, v38, v2
	v_add_f32_e32 v42, v42, v3
	s_waitcnt lgkmcnt(0)
	v_fma_f32 v13, -v220, v12, v34
	v_fma_f32 v38, -v230, v12, v38
	v_fma_f32 v42, -v234, v12, v42
	v_fma_f32 v2, -v231, v13, v38
	v_fma_f32 v42, -v235, v13, v42
	v_fma_f32 v3, -v236, v2, v42
	s_and_saveexec_b64 s[0:1], s[8:9]
	s_xor_b64 s[0:1], exec, s[0:1]
	s_cbranch_execz .LBB0_1027
	v_cvt_pk_bf16_f32 v100, v0, v0
	ds_write_b16 v200, v100
	v_cvt_pk_bf16_f32 v100, v1, v1
	ds_write_b16 v199, v100 offset:16
	v_cvt_pk_bf16_f32 v100, v8, v8
	ds_write_b16 v199, v100 offset:288
	v_cvt_pk_bf16_f32 v100, v9, v9
	ds_write_b16 v199, v100 offset:560
	v_cvt_pk_bf16_f32 v100, v14, v14
	ds_write_b16 v199, v100 offset:832
	v_cvt_pk_bf16_f32 v100, v15, v15
	ds_write_b16 v199, v100 offset:1104
	v_cvt_pk_bf16_f32 v100, v18, v18
	ds_write_b16 v199, v100 offset:1376
	v_cvt_pk_bf16_f32 v100, v19, v19
	ds_write_b16 v199, v100 offset:1648
	v_cvt_pk_bf16_f32 v100, v22, v22
	ds_write_b16 v199, v100 offset:1920
	v_cvt_pk_bf16_f32 v100, v23, v23
	ds_write_b16 v199, v100 offset:2192
	v_cvt_pk_bf16_f32 v100, v26, v26
	ds_write_b16 v199, v100 offset:2464
	v_cvt_pk_bf16_f32 v100, v27, v27
	ds_write_b16 v199, v100 offset:2736
	v_cvt_pk_bf16_f32 v100, v30, v30
	ds_write_b16 v199, v100 offset:3008
	v_cvt_pk_bf16_f32 v100, v31, v31
	ds_write_b16 v199, v100 offset:3280
	v_cvt_pk_bf16_f32 v100, v36, v36
	ds_write_b16 v199, v100 offset:3552
	v_cvt_pk_bf16_f32 v100, v37, v37
	ds_write_b16 v199, v100 offset:3824
	v_cvt_pk_bf16_f32 v100, v40, v40
	ds_write_b16 v199, v100 offset:4096
	v_cvt_pk_bf16_f32 v100, v41, v41
	ds_write_b16 v199, v100 offset:4368
	v_cvt_pk_bf16_f32 v100, v44, v44
	ds_write_b16 v199, v100 offset:4640
	v_cvt_pk_bf16_f32 v100, v45, v45
	ds_write_b16 v199, v100 offset:4912
	v_cvt_pk_bf16_f32 v100, v50, v50
	ds_write_b16 v199, v100 offset:5184
	v_cvt_pk_bf16_f32 v100, v51, v51
	ds_write_b16 v199, v100 offset:5456
	v_cvt_pk_bf16_f32 v100, v54, v54
	ds_write_b16 v199, v100 offset:5728
	v_cvt_pk_bf16_f32 v100, v55, v55
	ds_write_b16 v199, v100 offset:6000
	v_cvt_pk_bf16_f32 v100, v60, v60
	ds_write_b16 v199, v100 offset:6272
	v_cvt_pk_bf16_f32 v100, v61, v61
	ds_write_b16 v199, v100 offset:6544
	v_cvt_pk_bf16_f32 v100, v64, v64
	ds_write_b16 v199, v100 offset:6816
	v_cvt_pk_bf16_f32 v100, v65, v65
	ds_write_b16 v199, v100 offset:7088
	v_cvt_pk_bf16_f32 v100, v70, v70
	ds_write_b16 v199, v100 offset:7360
	v_cvt_pk_bf16_f32 v100, v71, v71
	ds_write_b16 v199, v100 offset:7632
	v_cvt_pk_bf16_f32 v100, v112, v112
	ds_write_b16 v199, v100 offset:7904
	v_cvt_pk_bf16_f32 v100, v113, v113
	ds_write_b16 v199, v100 offset:8176
	v_cvt_pk_bf16_f32 v100, v116, v116
	ds_write_b16 v199, v100 offset:8448
	v_cvt_pk_bf16_f32 v100, v117, v117
	ds_write_b16 v199, v100 offset:8720
	v_cvt_pk_bf16_f32 v100, v122, v122
	ds_write_b16 v199, v100 offset:8992
	v_cvt_pk_bf16_f32 v100, v123, v123
	ds_write_b16 v199, v100 offset:9264
	v_cvt_pk_bf16_f32 v100, v128, v128
	ds_write_b16 v199, v100 offset:9536
	v_cvt_pk_bf16_f32 v100, v129, v129
	ds_write_b16 v199, v100 offset:9808
	v_cvt_pk_bf16_f32 v100, v134, v134
	ds_write_b16 v199, v100 offset:10080
	v_cvt_pk_bf16_f32 v100, v135, v135
	ds_write_b16 v199, v100 offset:10352
	v_cvt_pk_bf16_f32 v100, v140, v140
	ds_write_b16 v199, v100 offset:10624
	v_cvt_pk_bf16_f32 v100, v141, v141
	ds_write_b16 v199, v100 offset:10896
	v_cvt_pk_bf16_f32 v100, v138, v138
	ds_write_b16 v199, v100 offset:11168
	v_cvt_pk_bf16_f32 v100, v139, v139
	ds_write_b16 v199, v100 offset:11440
	v_cvt_pk_bf16_f32 v100, v132, v132
	ds_write_b16 v199, v100 offset:11712
	v_cvt_pk_bf16_f32 v100, v133, v133
	ds_write_b16 v199, v100 offset:11984
	v_cvt_pk_bf16_f32 v100, v124, v124
	ds_write_b16 v199, v100 offset:12256
	v_cvt_pk_bf16_f32 v100, v125, v125
	ds_write_b16 v199, v100 offset:12528
	v_cvt_pk_bf16_f32 v100, v118, v118
	ds_write_b16 v199, v100 offset:12800
	v_cvt_pk_bf16_f32 v100, v119, v119
	ds_write_b16 v199, v100 offset:13072
	v_cvt_pk_bf16_f32 v100, v74, v74
	ds_write_b16 v199, v100 offset:13344
	v_cvt_pk_bf16_f32 v100, v75, v75
	ds_write_b16 v199, v100 offset:13616
	v_cvt_pk_bf16_f32 v100, v66, v66
	ds_write_b16 v199, v100 offset:13888
	v_cvt_pk_bf16_f32 v100, v67, v67
	ds_write_b16 v199, v100 offset:14160
	v_cvt_pk_bf16_f32 v100, v56, v56
	ds_write_b16 v199, v100 offset:14432
	v_cvt_pk_bf16_f32 v100, v57, v57
	ds_write_b16 v199, v100 offset:14704
	v_cvt_pk_bf16_f32 v100, v46, v46
	ds_write_b16 v199, v100 offset:14976
	v_cvt_pk_bf16_f32 v100, v47, v47
	ds_write_b16 v199, v100 offset:15248
	v_cvt_pk_bf16_f32 v100, v32, v32
	ds_write_b16 v199, v100 offset:15520
	v_cvt_pk_bf16_f32 v100, v33, v33
	ds_write_b16 v199, v100 offset:15792
	v_cvt_pk_bf16_f32 v100, v12, v12
	ds_write_b16 v199, v100 offset:16064
	v_cvt_pk_bf16_f32 v100, v13, v13
	ds_write_b16 v199, v100 offset:16336
	v_cvt_pk_bf16_f32 v100, v2, v2
	ds_write_b16 v199, v100 offset:16608
	v_cvt_pk_bf16_f32 v100, v3, v3
	ds_write_b16 v199, v100 offset:16880
